# low-rank tile epilogues: KIND 2/3 hand-written with batched row loads (one wait per 32x32 tile instead of 16 dependent round trips), KIND 0/1 w0 vector loaded once per feature half
# speedup vs baseline: 1.0848x; 1.0023x over previous
.LBB0_294:
	s_and_b32 s15, s14, 1
	s_ashr_i32 s2, s14, 1
	s_lshl_b32 s3, s15, 14
	s_add_u32 s20, s12, s3
	v_mov_b32_e32 v66, v131
	v_mov_b32_e32 v67, v131
	s_addc_u32 s21, s13, 0
	s_ashr_i32 s3, s2, 31
	s_waitcnt vmcnt(10)
	v_mov_b32_e32 v6, v131
	s_lshl_b64 s[40:41], s[2:3], 15
	s_add_u32 s40, s6, s40
	v_ashrrev_i32_e32 v2, 3, v6
	v_lshrrev_b32_e32 v0, 4, v6
	v_xor_b32_e32 v0, v0, v6
	v_ashrrev_i32_e32 v3, 31, v2
	s_addc_u32 s41, s7, s41
	v_lshlrev_b64 v[4:5], 7, v[2:3]
	v_lshlrev_b32_e32 v0, 4, v0
	v_lshlrev_b64 v[2:3], 8, v[2:3]
	v_lshl_add_u64 v[4:5], s[20:21], 0, v[4:5]
	v_and_b32_e32 v0, 0x70, v0
	v_lshl_add_u64 v[2:3], s[40:41], 0, v[2:3]
	s_waitcnt vmcnt(9)
	v_lshlrev_b32_e32 v12, 4, v6
	v_and_b32_e32 v7, 31, v6
	v_lshl_add_u64 v[4:5], v[4:5], 0, v[0:1]
	v_lshl_add_u64 v[2:3], v[2:3], 0, v[0:1]
	v_lshrrev_b32_e32 v0, 1, v6
	v_readfirstlane_b32 s3, v12
	v_add_u32_e32 v13, 0x1000, v12
	v_and_or_b32 v0, v0, s16, v7
	v_lshlrev_b32_e32 v7, 7, v6
	s_mov_b32 m0, s3
	v_readfirstlane_b32 s3, v13
	v_add_u32_e32 v13, 0x2000, v12
	v_lshrrev_b32_e32 v8, 5, v6
	v_bfe_u32 v9, v6, 5, 1
	v_bfe_u32 v10, v6, 1, 3
	v_and_b32_e32 v11, 0x2f80, v7
	global_load_lds_dwordx4 v[4:5], off
	v_lshl_add_u64 v[6:7], v[4:5], 0, s[70:71]
	s_mov_b32 m0, s3
	v_readfirstlane_b32 s3, v13
	global_load_lds_dwordx4 v[6:7], off
	v_lshl_add_u64 v[6:7], v[4:5], 0, s[52:53]
	s_mov_b32 m0, s3
	v_lshl_add_u64 v[4:5], v[4:5], 0, s[60:61]
	global_load_lds_dwordx4 v[6:7], off
	v_add_u32_e32 v6, 0x3000, v12
	v_lshlrev_b32_e32 v0, 7, v0
	v_readfirstlane_b32 s3, v6
	s_mov_b32 m0, s3
	v_add_u32_e32 v6, 0x5000, v12
	global_load_lds_dwordx4 v[4:5], off
	v_add_u32_e32 v4, 0x4000, v12
	v_lshrrev_b32_e32 v69, 6, v67
	v_readfirstlane_b32 s3, v4
	s_mov_b32 m0, s3
	v_readfirstlane_b32 s3, v6
	v_add_u32_e32 v6, 0x6000, v12
	global_load_lds_dwordx4 v[2:3], off
	v_lshl_add_u64 v[4:5], v[2:3], 0, s[52:53]
	s_mov_b32 m0, s3
	v_readfirstlane_b32 s3, v6
	global_load_lds_dwordx4 v[4:5], off
	v_lshl_add_u64 v[4:5], v[2:3], 0, s[42:43]
	s_mov_b32 m0, s3
	v_lshl_add_u64 v[2:3], v[2:3], 0, s[44:45]
	global_load_lds_dwordx4 v[4:5], off
	v_add_u32_e32 v4, 0x7000, v12
	s_lshl_b32 s2, s2, 7
	v_readfirstlane_b32 s3, v4
	s_mov_b32 m0, s3
	v_and_b32_e32 v68, 31, v66
	global_load_lds_dwordx4 v[2:3], off
	v_bitop3_b32 v2, v8, v10, 1 bitop3:0x6c
	v_lshlrev_b32_e32 v2, 4, v2
	v_or_b32_e32 v6, v2, v0
	s_waitcnt vmcnt(0)
	v_or_b32_e32 v14, v2, v11
	v_bitop3_b32 v2, v9, v10, 2 bitop3:0x36
	v_lshlrev_b32_e32 v2, 4, v2
	v_or_b32_e32 v18, v2, v0
	v_or_b32_e32 v19, v2, v11
	v_bitop3_b32 v2, v9, v10, 4 bitop3:0x36
	v_lshlrev_b32_e32 v2, 4, v2
	v_or_b32_e32 v90, v2, v0
	v_or_b32_e32 v98, v2, v11
	v_bitop3_b32 v2, v9, v10, 6 bitop3:0x36
	v_lshlrev_b32_e32 v2, 4, v2
	s_waitcnt vmcnt(0)
	s_waitcnt lgkmcnt(0)
	s_barrier
	v_or_b32_e32 v0, v2, v0
	v_or_b32_e32 v102, v2, v11
	ds_read_b128 v[2:5], v6 offset:0
	ds_read_b128 v[6:9], v6 offset:0x1000
	ds_read_b128 v[10:13], v14 offset:0x4000
	ds_read_b128 v[14:17], v14 offset:0x5000
	ds_read_b128 v[70:73], v18 offset:0
	ds_read_b128 v[74:77], v18 offset:0x1000
	ds_read_b128 v[78:81], v19 offset:0x4000
	ds_read_b128 v[82:85], v19 offset:0x5000
	s_add_i32 s14, s14, s76
	s_waitcnt lgkmcnt(4)
	ds_read_b128 v[86:89], v90 offset:0
	ds_read_b128 v[90:93], v90 offset:0x1000
	ds_read_b128 v[94:97], v98 offset:0x4000
	ds_read_b128 v[98:101], v98 offset:0x5000
	s_waitcnt lgkmcnt(4)
	s_nop 0
	v_mfma_f32_32x32x16_f16 v[50:65], v[2:5], v[10:13], 0
	s_cmpk_gt_i32 s14, 0xbf
	v_mfma_f32_32x32x16_f16 v[34:49], v[2:5], v[14:17], 0
	v_mfma_f32_32x32x16_f16 v[18:33], v[6:9], v[10:13], 0
	v_mfma_f32_32x32x16_f16 v[2:17], v[6:9], v[14:17], 0
	v_mfma_f32_32x32x16_f16 v[18:33], v[74:77], v[78:81], v[18:33]
	v_mfma_f32_32x32x16_f16 v[2:17], v[74:77], v[82:85], v[2:17]
	v_mfma_f32_32x32x16_f16 v[50:65], v[70:73], v[78:81], v[50:65]
	v_mfma_f32_32x32x16_f16 v[34:49], v[70:73], v[82:85], v[34:49]
	ds_read_b128 v[70:73], v0 offset:0
	ds_read_b128 v[74:77], v0 offset:0x1000
	ds_read_b128 v[78:81], v102 offset:0x4000
	ds_read_b128 v[82:85], v102 offset:0x5000
	s_waitcnt lgkmcnt(4)
	v_mul_lo_u32 v0, v69, s66
	s_waitcnt lgkmcnt(0)
	v_mfma_f32_32x32x16_f16 v[18:33], v[90:93], v[94:97], v[18:33]
	s_waitcnt vmcnt(0)
	s_barrier
	v_mfma_f32_32x32x16_f16 v[2:17], v[90:93], v[98:101], v[2:17]
	v_mfma_f32_32x32x16_f16 v[50:65], v[86:89], v[94:97], v[50:65]
	v_mfma_f32_32x32x16_f16 v[34:49], v[86:89], v[98:101], v[34:49]
	v_mfma_f32_32x32x16_f16 v[18:33], v[74:77], v[78:81], v[18:33]
	v_mfma_f32_32x32x16_f16 v[2:17], v[74:77], v[82:85], v[2:17]
	v_add_u32_e32 v76, 0xa000, v0
	v_lshrrev_b32_e32 v0, 1, v66
	v_and_b32_e32 v77, 16, v0
	v_ashrrev_i32_e32 v0, 1, v67
	v_and_b32_e32 v0, 0xffffffc0, v0
	v_and_or_b32 v75, v67, 64, s2
	s_load_dwordx2 s[2:3], s[28:29], 0x1c8
	v_mfma_f32_32x32x16_f16 v[50:65], v[70:73], v[78:81], v[50:65]
	v_bfe_u32 v74, v66, 3, 3
	v_mfma_f32_32x32x16_f16 v[34:49], v[70:73], v[82:85], v[34:49]
	v_lshl_add_u32 v73, s15, 7, v0
	v_and_b32_e32 v0, 7, v66
	v_lshrrev_b32_e32 v66, 6, v73
	v_mul_lo_u32 v66, v66, s4
	v_lshlrev_b32_e32 v70, 2, v0
	v_ashrrev_i32_e32 v67, 31, v66
	v_mul_u32_u24_e32 v72, 0x90, v68
	s_waitcnt lgkmcnt(0)
	v_lshl_add_u64 v[68:69], v[66:67], 2, s[2:3]
	v_or_b32_e32 v66, v73, v70
	v_ashrrev_i32_e32 v67, 31, v66
	v_add3_u32 v72, v76, v72, v77
	v_lshl_add_u64 v[70:71], v[66:67], 2, s[8:9]
	ds_write_b128 v72, v[50:53]
	ds_write_b128 v72, v[54:57] offset:32
	ds_write_b128 v72, v[58:61] offset:64
	ds_write_b128 v72, v[62:65] offset:96
	global_load_dwordx4 v[54:57], v[70:71], off
	v_lshlrev_b32_e32 v0, 4, v0
	v_lshl_add_u64 v[68:69], v[68:69], 0, v[0:1]
	v_or_b32_e32 v0, v76, v0
	v_mad_u32_u24 v0, v74, s67, v0
	ds_read_b128 v[50:53], v0
	v_or_b32_e32 v67, 8, v74
	v_or_b32_e32 v76, 16, v74
	v_or_b32_e32 v77, 24, v74
	s_waitcnt vmcnt(0) lgkmcnt(0)
	v_mov_b32_e32 v104, v54
	v_mov_b32_e32 v105, v55
	v_mov_b32_e32 v106, v56
	v_mov_b32_e32 v107, v57
	v_add_f32_e32 v50, v50, v54
	v_mul_f32_e32 v50, 0xbfb8aa3b, v50
	v_exp_f32_e32 v50, v50
	s_nop 0
	v_add_f32_e32 v50, 1.0, v50
	v_rcp_f32_e32 v50, v50
	s_nop 0
	v_mul_f32_e32 v50, 0xbf1b4598, v50
	v_mul_f32_e32 v50, 0x3fb8aa3b, v50
	v_exp_f32_e32 v54, v50
	v_add_f32_e32 v50, v51, v55
	v_mul_f32_e32 v50, 0xbfb8aa3b, v50
	v_exp_f32_e32 v50, v50
	s_nop 0
	v_add_f32_e32 v50, 1.0, v50
	v_rcp_f32_e32 v50, v50
	s_nop 0
	v_mul_f32_e32 v50, 0xbf1b4598, v50
	v_mul_f32_e32 v50, 0x3fb8aa3b, v50
	v_exp_f32_e32 v55, v50
	v_add_f32_e32 v50, v52, v56
	v_mul_f32_e32 v50, 0xbfb8aa3b, v50
	v_exp_f32_e32 v50, v50
	s_nop 0
	v_add_f32_e32 v50, 1.0, v50
	v_rcp_f32_e32 v50, v50
	s_nop 0
	v_mul_f32_e32 v50, 0xbf1b4598, v50
	v_mul_f32_e32 v50, 0x3fb8aa3b, v50
	v_exp_f32_e32 v56, v50
	v_add_f32_e32 v50, v53, v57
	v_mul_f32_e32 v50, 0xbfb8aa3b, v50
	v_exp_f32_e32 v50, v50
	s_nop 0
	v_add_f32_e32 v50, 1.0, v50
	v_rcp_f32_e32 v50, v50
	s_nop 0
	v_mul_f32_e32 v50, 0xbf1b4598, v50
	v_mul_f32_e32 v50, 0x3fb8aa3b, v50
	v_exp_f32_e32 v57, v50
	v_or_b32_e32 v50, v75, v74
	v_mad_i64_i32 v[52:53], s[2:3], v50, s17, v[68:69]
	global_store_dwordx4 v[52:53], v[54:57], off
	s_nop 2
	v_mov_b32_e32 v58, v104
	v_mov_b32_e32 v59, v105
	v_mov_b32_e32 v60, v106
	v_mov_b32_e32 v61, v107
	ds_read_b128 v[54:57], v0 offset:1152
	s_waitcnt lgkmcnt(0)
	v_add_f32_e32 v50, v54, v58
	v_mul_f32_e32 v50, 0xbfb8aa3b, v50
	v_exp_f32_e32 v50, v50
	s_nop 0
	v_add_f32_e32 v50, 1.0, v50
	v_rcp_f32_e32 v50, v50
	s_nop 0
	v_mul_f32_e32 v50, 0xbf1b4598, v50
	v_mul_f32_e32 v50, 0x3fb8aa3b, v50
	v_exp_f32_e32 v58, v50
	v_add_f32_e32 v50, v55, v59
	v_mul_f32_e32 v50, 0xbfb8aa3b, v50
	v_exp_f32_e32 v50, v50
	s_nop 0
	v_add_f32_e32 v50, 1.0, v50
	v_rcp_f32_e32 v50, v50
	s_nop 0
	v_mul_f32_e32 v50, 0xbf1b4598, v50
	v_mul_f32_e32 v50, 0x3fb8aa3b, v50
	v_exp_f32_e32 v59, v50
	v_add_f32_e32 v50, v56, v60
	v_mul_f32_e32 v50, 0xbfb8aa3b, v50
	v_exp_f32_e32 v50, v50
	s_nop 0
	v_add_f32_e32 v50, 1.0, v50
	v_rcp_f32_e32 v50, v50
	s_nop 0
	v_mul_f32_e32 v50, 0xbf1b4598, v50
	v_mul_f32_e32 v50, 0x3fb8aa3b, v50
	v_exp_f32_e32 v60, v50
	v_add_f32_e32 v50, v57, v61
	v_mul_f32_e32 v50, 0xbfb8aa3b, v50
	v_exp_f32_e32 v50, v50
	s_nop 0
	v_add_f32_e32 v50, 1.0, v50
	v_rcp_f32_e32 v50, v50
	s_nop 0
	v_mul_f32_e32 v50, 0xbf1b4598, v50
	v_mul_f32_e32 v50, 0x3fb8aa3b, v50
	v_exp_f32_e32 v61, v50
	v_or_b32_e32 v50, v67, v75
	v_mad_i64_i32 v[54:55], s[2:3], v50, s17, v[68:69]
	global_store_dwordx4 v[54:55], v[58:61], off
	s_nop 2
	v_mov_b32_e32 v60, v104
	v_mov_b32_e32 v61, v105
	v_mov_b32_e32 v62, v106
	v_mov_b32_e32 v63, v107
	ds_read_b128 v[56:59], v0 offset:2304
	s_waitcnt lgkmcnt(0)
	v_add_f32_e32 v50, v56, v60
	v_mul_f32_e32 v50, 0xbfb8aa3b, v50
	v_exp_f32_e32 v50, v50
	s_nop 0
	v_add_f32_e32 v50, 1.0, v50
	v_rcp_f32_e32 v50, v50
	s_nop 0
	v_mul_f32_e32 v50, 0xbf1b4598, v50
	v_mul_f32_e32 v50, 0x3fb8aa3b, v50
	v_exp_f32_e32 v60, v50
	v_add_f32_e32 v50, v57, v61
	v_mul_f32_e32 v50, 0xbfb8aa3b, v50
	v_exp_f32_e32 v50, v50
	s_nop 0
	v_add_f32_e32 v50, 1.0, v50
	v_rcp_f32_e32 v50, v50
	s_nop 0
	v_mul_f32_e32 v50, 0xbf1b4598, v50
	v_mul_f32_e32 v50, 0x3fb8aa3b, v50
	v_exp_f32_e32 v61, v50
	v_add_f32_e32 v50, v58, v62
	v_mul_f32_e32 v50, 0xbfb8aa3b, v50
	v_exp_f32_e32 v50, v50
	s_nop 0
	v_add_f32_e32 v50, 1.0, v50
	v_rcp_f32_e32 v50, v50
	s_nop 0
	v_mul_f32_e32 v50, 0xbf1b4598, v50
	v_mul_f32_e32 v50, 0x3fb8aa3b, v50
	v_exp_f32_e32 v62, v50
	v_add_f32_e32 v50, v59, v63
	v_mul_f32_e32 v50, 0xbfb8aa3b, v50
	v_exp_f32_e32 v50, v50
	s_nop 0
	v_add_f32_e32 v50, 1.0, v50
	v_rcp_f32_e32 v50, v50
	s_nop 0
	v_mul_f32_e32 v50, 0xbf1b4598, v50
	v_mul_f32_e32 v50, 0x3fb8aa3b, v50
	v_exp_f32_e32 v63, v50
	v_or_b32_e32 v50, v76, v75
	v_mad_i64_i32 v[56:57], s[2:3], v50, s17, v[68:69]
	global_store_dwordx4 v[56:57], v[60:63], off
	s_nop 2
	v_mov_b32_e32 v62, v104
	v_mov_b32_e32 v63, v105
	v_mov_b32_e32 v64, v106
	v_mov_b32_e32 v65, v107
	ds_read_b128 v[58:61], v0 offset:3456
	s_waitcnt lgkmcnt(0)
	v_add_f32_e32 v50, v58, v62
	v_mul_f32_e32 v50, 0xbfb8aa3b, v50
	v_exp_f32_e32 v50, v50
	s_nop 0
	v_add_f32_e32 v50, 1.0, v50
	v_rcp_f32_e32 v50, v50
	s_nop 0
	v_mul_f32_e32 v50, 0xbf1b4598, v50
	v_mul_f32_e32 v50, 0x3fb8aa3b, v50
	v_exp_f32_e32 v58, v50
	v_add_f32_e32 v50, v59, v63
	v_mul_f32_e32 v50, 0xbfb8aa3b, v50
	v_exp_f32_e32 v50, v50
	s_nop 0
	v_add_f32_e32 v50, 1.0, v50
	v_rcp_f32_e32 v50, v50
	s_nop 0
	v_mul_f32_e32 v50, 0xbf1b4598, v50
	v_mul_f32_e32 v50, 0x3fb8aa3b, v50
	v_exp_f32_e32 v59, v50
	v_add_f32_e32 v50, v60, v64
	v_mul_f32_e32 v50, 0xbfb8aa3b, v50
	v_exp_f32_e32 v50, v50
	s_nop 0
	v_add_f32_e32 v50, 1.0, v50
	v_rcp_f32_e32 v50, v50
	s_nop 0
	v_mul_f32_e32 v50, 0xbf1b4598, v50
	v_mul_f32_e32 v50, 0x3fb8aa3b, v50
	v_exp_f32_e32 v60, v50
	v_add_f32_e32 v50, v61, v65
	v_mul_f32_e32 v50, 0xbfb8aa3b, v50
	v_exp_f32_e32 v50, v50
	s_nop 0
	v_add_f32_e32 v50, 1.0, v50
	v_rcp_f32_e32 v50, v50
	s_nop 0
	v_mul_f32_e32 v50, 0xbf1b4598, v50
	v_mul_f32_e32 v50, 0x3fb8aa3b, v50
	v_exp_f32_e32 v61, v50
	v_or_b32_e32 v50, v77, v75
	v_mad_i64_i32 v[50:51], s[2:3], v50, s17, v[68:69]
	global_store_dwordx4 v[50:51], v[58:61], off
	ds_write_b128 v72, v[34:37] offset:4608
	ds_write_b128 v72, v[38:41] offset:4640
	ds_write_b128 v72, v[42:45] offset:4672
	ds_write_b128 v72, v[46:49] offset:4704
	s_nop 2
	v_mov_b32_e32 v38, v104
	v_mov_b32_e32 v39, v105
	v_mov_b32_e32 v40, v106
	v_mov_b32_e32 v41, v107
	ds_read_b128 v[34:37], v0 offset:4608
	v_or_b32_e32 v58, 32, v75
	s_waitcnt lgkmcnt(0)
	v_add_f32_e32 v34, v34, v38
	v_add_f32_e32 v35, v35, v39
	v_add_f32_e32 v36, v36, v40
	v_add_f32_e32 v37, v37, v41
	v_mul_f32_e32 v34, 0xbfb8aa3b, v34
	v_mul_f32_e32 v35, 0xbfb8aa3b, v35
	v_mul_f32_e32 v36, 0xbfb8aa3b, v36
	v_mul_f32_e32 v37, 0xbfb8aa3b, v37
	v_exp_f32_e32 v34, v34
	v_exp_f32_e32 v35, v35
	v_exp_f32_e32 v36, v36
	v_exp_f32_e32 v37, v37
	v_add_f32_e32 v34, 1.0, v34
	v_add_f32_e32 v35, 1.0, v35
	v_add_f32_e32 v36, 1.0, v36
	v_add_f32_e32 v37, 1.0, v37
	v_rcp_f32_e32 v34, v34
	v_rcp_f32_e32 v35, v35
	v_rcp_f32_e32 v36, v36
	v_rcp_f32_e32 v37, v37
	v_mul_f32_e32 v34, 0xbf1b4598, v34
	v_mul_f32_e32 v35, 0xbf1b4598, v35
	v_mul_f32_e32 v36, 0xbf1b4598, v36
	v_mul_f32_e32 v37, 0xbf1b4598, v37
	v_mul_f32_e32 v34, 0x3fb8aa3b, v34
	v_mul_f32_e32 v35, 0x3fb8aa3b, v35
	v_mul_f32_e32 v36, 0x3fb8aa3b, v36
	v_mul_f32_e32 v37, 0x3fb8aa3b, v37
	v_exp_f32_e32 v34, v34
	v_exp_f32_e32 v35, v35
	v_exp_f32_e32 v36, v36
	v_exp_f32_e32 v37, v37
	v_or_b32_e32 v38, v58, v74
	v_mad_i64_i32 v[40:41], s[2:3], v38, s17, v[68:69]
	global_store_dwordx4 v[40:41], v[34:37], off
	s_nop 2
	v_mov_b32_e32 v42, v104
	v_mov_b32_e32 v43, v105
	v_mov_b32_e32 v44, v106
	v_mov_b32_e32 v45, v107
	ds_read_b128 v[34:37], v0 offset:5760
	v_or_b32_e32 v38, v58, v67
	v_mad_i64_i32 v[38:39], s[2:3], v38, s17, v[68:69]
	v_ashrrev_i32_e32 v67, 31, v73
	s_waitcnt lgkmcnt(0)
	v_add_f32_e32 v34, v34, v42
	v_add_f32_e32 v35, v35, v43
	v_add_f32_e32 v36, v36, v44
	v_add_f32_e32 v37, v37, v45
	v_mul_f32_e32 v34, 0xbfb8aa3b, v34
	v_mul_f32_e32 v35, 0xbfb8aa3b, v35
	v_mul_f32_e32 v36, 0xbfb8aa3b, v36
	v_mul_f32_e32 v37, 0xbfb8aa3b, v37
	v_exp_f32_e32 v34, v34
	v_exp_f32_e32 v35, v35
	v_exp_f32_e32 v36, v36
	v_exp_f32_e32 v37, v37
	v_add_f32_e32 v34, 1.0, v34
	v_add_f32_e32 v35, 1.0, v35
	v_add_f32_e32 v36, 1.0, v36
	v_add_f32_e32 v37, 1.0, v37
	v_rcp_f32_e32 v34, v34
	v_rcp_f32_e32 v35, v35
	v_rcp_f32_e32 v36, v36
	v_rcp_f32_e32 v37, v37
	v_mul_f32_e32 v34, 0xbf1b4598, v34
	v_mul_f32_e32 v35, 0xbf1b4598, v35
	v_mul_f32_e32 v36, 0xbf1b4598, v36
	v_mul_f32_e32 v37, 0xbf1b4598, v37
	v_mul_f32_e32 v34, 0x3fb8aa3b, v34
	v_mul_f32_e32 v35, 0x3fb8aa3b, v35
	v_mul_f32_e32 v36, 0x3fb8aa3b, v36
	v_mul_f32_e32 v37, 0x3fb8aa3b, v37
	v_exp_f32_e32 v34, v34
	v_exp_f32_e32 v35, v35
	v_exp_f32_e32 v36, v36
	v_exp_f32_e32 v37, v37
	global_store_dwordx4 v[38:39], v[34:37], off
	s_nop 2
	v_mov_b32_e32 v42, v104
	v_mov_b32_e32 v43, v105
	v_mov_b32_e32 v44, v106
	v_mov_b32_e32 v45, v107
	ds_read_b128 v[34:37], v0 offset:6912
	s_waitcnt lgkmcnt(0)
	v_add_f32_e32 v34, v34, v42
	v_mul_f32_e32 v34, 0xbfb8aa3b, v34
	v_exp_f32_e32 v34, v34
	s_nop 0
	v_add_f32_e32 v34, 1.0, v34
	v_rcp_f32_e32 v34, v34
	s_nop 0
	v_mul_f32_e32 v34, 0xbf1b4598, v34
	v_mul_f32_e32 v34, 0x3fb8aa3b, v34
	v_exp_f32_e32 v42, v34
	v_add_f32_e32 v34, v35, v43
	v_mul_f32_e32 v34, 0xbfb8aa3b, v34
	v_exp_f32_e32 v34, v34
	s_nop 0
	v_add_f32_e32 v34, 1.0, v34
	v_rcp_f32_e32 v34, v34
	s_nop 0
	v_mul_f32_e32 v34, 0xbf1b4598, v34
	v_mul_f32_e32 v34, 0x3fb8aa3b, v34
	v_exp_f32_e32 v43, v34
	v_add_f32_e32 v34, v36, v44
	v_mul_f32_e32 v34, 0xbfb8aa3b, v34
	v_exp_f32_e32 v34, v34
	s_nop 0
	v_add_f32_e32 v34, 1.0, v34
	v_rcp_f32_e32 v34, v34
	s_nop 0
	v_mul_f32_e32 v34, 0xbf1b4598, v34
	v_mul_f32_e32 v34, 0x3fb8aa3b, v34
	v_exp_f32_e32 v44, v34
	v_add_f32_e32 v34, v37, v45
	v_mul_f32_e32 v34, 0xbfb8aa3b, v34
	v_exp_f32_e32 v34, v34
	s_nop 0
	v_add_f32_e32 v34, 1.0, v34
	v_rcp_f32_e32 v34, v34
	s_nop 0
	v_mul_f32_e32 v34, 0xbf1b4598, v34
	v_mul_f32_e32 v34, 0x3fb8aa3b, v34
	v_exp_f32_e32 v45, v34
	v_or_b32_e32 v34, v58, v76
	v_mad_i64_i32 v[36:37], s[2:3], v34, s17, v[68:69]
	global_store_dwordx4 v[36:37], v[42:45], off
	s_nop 2
	v_mov_b32_e32 v46, v104
	v_mov_b32_e32 v47, v105
	v_mov_b32_e32 v48, v106
	v_mov_b32_e32 v49, v107
	ds_read_b128 v[42:45], v0 offset:8064
	s_waitcnt lgkmcnt(0)
	v_add_f32_e32 v34, v42, v46
	v_mul_f32_e32 v34, 0xbfb8aa3b, v34
	v_exp_f32_e32 v34, v34
	s_nop 0
	v_add_f32_e32 v34, 1.0, v34
	v_rcp_f32_e32 v34, v34
	s_nop 0
	v_mul_f32_e32 v34, 0xbf1b4598, v34
	v_mul_f32_e32 v34, 0x3fb8aa3b, v34
	v_exp_f32_e32 v42, v34
	v_add_f32_e32 v34, v43, v47
	v_mul_f32_e32 v34, 0xbfb8aa3b, v34
	v_exp_f32_e32 v34, v34
	s_nop 0
	v_add_f32_e32 v34, 1.0, v34
	v_rcp_f32_e32 v34, v34
	s_nop 0
	v_mul_f32_e32 v34, 0xbf1b4598, v34
	v_mul_f32_e32 v34, 0x3fb8aa3b, v34
	v_exp_f32_e32 v43, v34
	v_add_f32_e32 v34, v44, v48
	v_mul_f32_e32 v34, 0xbfb8aa3b, v34
	v_exp_f32_e32 v34, v34
	s_nop 0
	v_add_f32_e32 v34, 1.0, v34
	v_rcp_f32_e32 v34, v34
	s_nop 0
	v_mul_f32_e32 v34, 0xbf1b4598, v34
	v_mul_f32_e32 v34, 0x3fb8aa3b, v34
	v_exp_f32_e32 v44, v34
	v_add_f32_e32 v34, v45, v49
	v_mul_f32_e32 v34, 0xbfb8aa3b, v34
	v_exp_f32_e32 v34, v34
	s_nop 0
	v_add_f32_e32 v34, 1.0, v34
	v_rcp_f32_e32 v34, v34
	s_nop 0
	v_mul_f32_e32 v34, 0xbf1b4598, v34
	v_mul_f32_e32 v34, 0x3fb8aa3b, v34
	v_exp_f32_e32 v45, v34
	v_or_b32_e32 v34, v58, v77
	v_mad_i64_i32 v[34:35], s[2:3], v34, s17, v[68:69]
	global_store_dwordx4 v[34:35], v[42:45], off
	ds_write_b128 v72, v[18:21]
	ds_write_b128 v72, v[22:25] offset:32
	ds_write_b128 v72, v[26:29] offset:64
	ds_write_b128 v72, v[30:33] offset:96
	v_lshl_add_u64 v[42:43], v[66:67], 2, s[8:9]
	global_load_dwordx4 v[22:25], v[42:43], off offset:128
	ds_read_b128 v[18:21], v0
	s_waitcnt vmcnt(0) lgkmcnt(0)
	v_mov_b32_e32 v108, v22
	v_mov_b32_e32 v109, v23
	v_mov_b32_e32 v110, v24
	v_mov_b32_e32 v111, v25
	v_add_f32_e32 v18, v18, v22
	v_add_f32_e32 v19, v19, v23
	v_add_f32_e32 v20, v20, v24
	v_add_f32_e32 v21, v21, v25
	v_mul_f32_e32 v18, 0xbfb8aa3b, v18
	v_mul_f32_e32 v19, 0xbfb8aa3b, v19
	v_mul_f32_e32 v20, 0xbfb8aa3b, v20
	v_mul_f32_e32 v21, 0xbfb8aa3b, v21
	v_exp_f32_e32 v18, v18
	v_exp_f32_e32 v19, v19
	v_exp_f32_e32 v20, v20
	v_exp_f32_e32 v21, v21
	v_add_f32_e32 v18, 1.0, v18
	v_add_f32_e32 v19, 1.0, v19
	v_add_f32_e32 v20, 1.0, v20
	v_add_f32_e32 v21, 1.0, v21
	v_rcp_f32_e32 v18, v18
	v_rcp_f32_e32 v19, v19
	v_rcp_f32_e32 v20, v20
	v_rcp_f32_e32 v21, v21
	v_mul_f32_e32 v18, 0xbf1b4598, v18
	v_mul_f32_e32 v19, 0xbf1b4598, v19
	v_mul_f32_e32 v20, 0xbf1b4598, v20
	v_mul_f32_e32 v21, 0xbf1b4598, v21
	v_mul_f32_e32 v18, 0x3fb8aa3b, v18
	v_mul_f32_e32 v19, 0x3fb8aa3b, v19
	v_mul_f32_e32 v20, 0x3fb8aa3b, v20
	v_mul_f32_e32 v21, 0x3fb8aa3b, v21
	v_exp_f32_e32 v18, v18
	v_exp_f32_e32 v19, v19
	v_exp_f32_e32 v20, v20
	v_exp_f32_e32 v21, v21
	global_store_dwordx4 v[52:53], v[18:21], off offset:128
	s_nop 2
	v_mov_b32_e32 v22, v108
	v_mov_b32_e32 v23, v109
	v_mov_b32_e32 v24, v110
	v_mov_b32_e32 v25, v111
	ds_read_b128 v[18:21], v0 offset:1152
	s_waitcnt lgkmcnt(0)
	v_add_f32_e32 v18, v18, v22
	v_add_f32_e32 v19, v19, v23
	v_add_f32_e32 v20, v20, v24
	v_add_f32_e32 v21, v21, v25
	v_mul_f32_e32 v18, 0xbfb8aa3b, v18
	v_mul_f32_e32 v19, 0xbfb8aa3b, v19
	v_mul_f32_e32 v20, 0xbfb8aa3b, v20
	v_mul_f32_e32 v21, 0xbfb8aa3b, v21
	v_exp_f32_e32 v18, v18
	v_exp_f32_e32 v19, v19
	v_exp_f32_e32 v20, v20
	v_exp_f32_e32 v21, v21
	v_add_f32_e32 v18, 1.0, v18
	v_add_f32_e32 v19, 1.0, v19
	v_add_f32_e32 v20, 1.0, v20
	v_add_f32_e32 v21, 1.0, v21
	v_rcp_f32_e32 v18, v18
	v_rcp_f32_e32 v19, v19
	v_rcp_f32_e32 v20, v20
	v_rcp_f32_e32 v21, v21
	v_mul_f32_e32 v18, 0xbf1b4598, v18
	v_mul_f32_e32 v19, 0xbf1b4598, v19
	v_mul_f32_e32 v20, 0xbf1b4598, v20
	v_mul_f32_e32 v21, 0xbf1b4598, v21
	v_mul_f32_e32 v18, 0x3fb8aa3b, v18
	v_mul_f32_e32 v19, 0x3fb8aa3b, v19
	v_mul_f32_e32 v20, 0x3fb8aa3b, v20
	v_mul_f32_e32 v21, 0x3fb8aa3b, v21
	v_exp_f32_e32 v18, v18
	v_exp_f32_e32 v19, v19
	v_exp_f32_e32 v20, v20
	v_exp_f32_e32 v21, v21
	global_store_dwordx4 v[54:55], v[18:21], off offset:128
	s_nop 2
	v_mov_b32_e32 v22, v108
	v_mov_b32_e32 v23, v109
	v_mov_b32_e32 v24, v110
	v_mov_b32_e32 v25, v111
	ds_read_b128 v[18:21], v0 offset:2304
	s_waitcnt lgkmcnt(0)
	v_add_f32_e32 v18, v18, v22
	v_add_f32_e32 v19, v19, v23
	v_add_f32_e32 v20, v20, v24
	v_add_f32_e32 v21, v21, v25
	v_mul_f32_e32 v18, 0xbfb8aa3b, v18
	v_mul_f32_e32 v19, 0xbfb8aa3b, v19
	v_mul_f32_e32 v20, 0xbfb8aa3b, v20
	v_mul_f32_e32 v21, 0xbfb8aa3b, v21
	v_exp_f32_e32 v18, v18
	v_exp_f32_e32 v19, v19
	v_exp_f32_e32 v20, v20
	v_exp_f32_e32 v21, v21
	v_add_f32_e32 v18, 1.0, v18
	v_add_f32_e32 v19, 1.0, v19
	v_add_f32_e32 v20, 1.0, v20
	v_add_f32_e32 v21, 1.0, v21
	v_rcp_f32_e32 v18, v18
	v_rcp_f32_e32 v19, v19
	v_rcp_f32_e32 v20, v20
	v_rcp_f32_e32 v21, v21
	v_mul_f32_e32 v18, 0xbf1b4598, v18
	v_mul_f32_e32 v19, 0xbf1b4598, v19
	v_mul_f32_e32 v20, 0xbf1b4598, v20
	v_mul_f32_e32 v21, 0xbf1b4598, v21
	v_mul_f32_e32 v18, 0x3fb8aa3b, v18
	v_mul_f32_e32 v19, 0x3fb8aa3b, v19
	v_mul_f32_e32 v20, 0x3fb8aa3b, v20
	v_mul_f32_e32 v21, 0x3fb8aa3b, v21
	v_exp_f32_e32 v18, v18
	v_exp_f32_e32 v19, v19
	v_exp_f32_e32 v20, v20
	v_exp_f32_e32 v21, v21
	global_store_dwordx4 v[56:57], v[18:21], off offset:128
	s_nop 2
	v_mov_b32_e32 v22, v108
	v_mov_b32_e32 v23, v109
	v_mov_b32_e32 v24, v110
	v_mov_b32_e32 v25, v111
	ds_read_b128 v[18:21], v0 offset:3456
	s_waitcnt lgkmcnt(0)
	v_add_f32_e32 v18, v18, v22
	v_add_f32_e32 v19, v19, v23
	v_add_f32_e32 v20, v20, v24
	v_add_f32_e32 v21, v21, v25
	v_mul_f32_e32 v18, 0xbfb8aa3b, v18
	v_mul_f32_e32 v19, 0xbfb8aa3b, v19
	v_mul_f32_e32 v20, 0xbfb8aa3b, v20
	v_mul_f32_e32 v21, 0xbfb8aa3b, v21
	v_exp_f32_e32 v18, v18
	v_exp_f32_e32 v19, v19
	v_exp_f32_e32 v20, v20
	v_exp_f32_e32 v21, v21
	v_add_f32_e32 v18, 1.0, v18
	v_add_f32_e32 v19, 1.0, v19
	v_add_f32_e32 v20, 1.0, v20
	v_add_f32_e32 v21, 1.0, v21
	v_rcp_f32_e32 v18, v18
	v_rcp_f32_e32 v19, v19
	v_rcp_f32_e32 v20, v20
	v_rcp_f32_e32 v21, v21
	v_mul_f32_e32 v18, 0xbf1b4598, v18
	v_mul_f32_e32 v19, 0xbf1b4598, v19
	v_mul_f32_e32 v20, 0xbf1b4598, v20
	v_mul_f32_e32 v21, 0xbf1b4598, v21
	v_mul_f32_e32 v18, 0x3fb8aa3b, v18
	v_mul_f32_e32 v19, 0x3fb8aa3b, v19
	v_mul_f32_e32 v20, 0x3fb8aa3b, v20
	v_mul_f32_e32 v21, 0x3fb8aa3b, v21
	v_exp_f32_e32 v18, v18
	v_exp_f32_e32 v19, v19
	v_exp_f32_e32 v20, v20
	v_exp_f32_e32 v21, v21
	global_store_dwordx4 v[50:51], v[18:21], off offset:128
	ds_write_b128 v72, v[2:5] offset:4608
	ds_write_b128 v72, v[6:9] offset:4640
	ds_write_b128 v72, v[10:13] offset:4672
	ds_write_b128 v72, v[14:17] offset:4704
	s_nop 2
	v_mov_b32_e32 v6, v108
	v_mov_b32_e32 v7, v109
	v_mov_b32_e32 v8, v110
	v_mov_b32_e32 v9, v111
	ds_read_b128 v[2:5], v0 offset:4608
	s_waitcnt lgkmcnt(0)
	v_add_f32_e32 v2, v2, v6
	v_add_f32_e32 v3, v3, v7
	v_add_f32_e32 v4, v4, v8
	v_add_f32_e32 v5, v5, v9
	v_mul_f32_e32 v2, 0xbfb8aa3b, v2
	v_mul_f32_e32 v3, 0xbfb8aa3b, v3
	v_mul_f32_e32 v4, 0xbfb8aa3b, v4
	v_mul_f32_e32 v5, 0xbfb8aa3b, v5
	v_exp_f32_e32 v2, v2
	v_exp_f32_e32 v3, v3
	v_exp_f32_e32 v4, v4
	v_exp_f32_e32 v5, v5
	v_add_f32_e32 v2, 1.0, v2
	v_add_f32_e32 v3, 1.0, v3
	v_add_f32_e32 v4, 1.0, v4
	v_add_f32_e32 v5, 1.0, v5
	v_rcp_f32_e32 v2, v2
	v_rcp_f32_e32 v3, v3
	v_rcp_f32_e32 v4, v4
	v_rcp_f32_e32 v5, v5
	v_mul_f32_e32 v2, 0xbf1b4598, v2
	v_mul_f32_e32 v3, 0xbf1b4598, v3
	v_mul_f32_e32 v4, 0xbf1b4598, v4
	v_mul_f32_e32 v5, 0xbf1b4598, v5
	v_mul_f32_e32 v2, 0x3fb8aa3b, v2
	v_mul_f32_e32 v3, 0x3fb8aa3b, v3
	v_mul_f32_e32 v4, 0x3fb8aa3b, v4
	v_mul_f32_e32 v5, 0x3fb8aa3b, v5
	v_exp_f32_e32 v2, v2
	v_exp_f32_e32 v3, v3
	v_exp_f32_e32 v4, v4
	v_exp_f32_e32 v5, v5
	global_store_dwordx4 v[40:41], v[2:5], off offset:128
	s_nop 2
	v_mov_b32_e32 v6, v108
	v_mov_b32_e32 v7, v109
	v_mov_b32_e32 v8, v110
	v_mov_b32_e32 v9, v111
	ds_read_b128 v[2:5], v0 offset:5760
	s_waitcnt lgkmcnt(0)
	v_add_f32_e32 v2, v2, v6
	v_add_f32_e32 v3, v3, v7
	v_add_f32_e32 v4, v4, v8
	v_add_f32_e32 v5, v5, v9
	v_mul_f32_e32 v2, 0xbfb8aa3b, v2
	v_mul_f32_e32 v3, 0xbfb8aa3b, v3
	v_mul_f32_e32 v4, 0xbfb8aa3b, v4
	v_mul_f32_e32 v5, 0xbfb8aa3b, v5
	v_exp_f32_e32 v2, v2
	v_exp_f32_e32 v3, v3
	v_exp_f32_e32 v4, v4
	v_exp_f32_e32 v5, v5
	v_add_f32_e32 v2, 1.0, v2
	v_add_f32_e32 v3, 1.0, v3
	v_add_f32_e32 v4, 1.0, v4
	v_add_f32_e32 v5, 1.0, v5
	v_rcp_f32_e32 v2, v2
	v_rcp_f32_e32 v3, v3
	v_rcp_f32_e32 v4, v4
	v_rcp_f32_e32 v5, v5
	v_mul_f32_e32 v2, 0xbf1b4598, v2
	v_mul_f32_e32 v3, 0xbf1b4598, v3
	v_mul_f32_e32 v4, 0xbf1b4598, v4
	v_mul_f32_e32 v5, 0xbf1b4598, v5
	v_mul_f32_e32 v2, 0x3fb8aa3b, v2
	v_mul_f32_e32 v3, 0x3fb8aa3b, v3
	v_mul_f32_e32 v4, 0x3fb8aa3b, v4
	v_mul_f32_e32 v5, 0x3fb8aa3b, v5
	v_exp_f32_e32 v2, v2
	v_exp_f32_e32 v3, v3
	v_exp_f32_e32 v4, v4
	v_exp_f32_e32 v5, v5
	global_store_dwordx4 v[38:39], v[2:5], off offset:128
	s_nop 2
	v_mov_b32_e32 v6, v108
	v_mov_b32_e32 v7, v109
	v_mov_b32_e32 v8, v110
	v_mov_b32_e32 v9, v111
	ds_read_b128 v[2:5], v0 offset:6912
	s_waitcnt lgkmcnt(0)
	v_add_f32_e32 v2, v2, v6
	v_add_f32_e32 v3, v3, v7
	v_add_f32_e32 v4, v4, v8
	v_add_f32_e32 v5, v5, v9
	v_mul_f32_e32 v2, 0xbfb8aa3b, v2
	v_mul_f32_e32 v3, 0xbfb8aa3b, v3
	v_mul_f32_e32 v4, 0xbfb8aa3b, v4
	v_mul_f32_e32 v5, 0xbfb8aa3b, v5
	v_exp_f32_e32 v2, v2
	v_exp_f32_e32 v3, v3
	v_exp_f32_e32 v4, v4
	v_exp_f32_e32 v5, v5
	v_add_f32_e32 v2, 1.0, v2
	v_add_f32_e32 v3, 1.0, v3
	v_add_f32_e32 v4, 1.0, v4
	v_add_f32_e32 v5, 1.0, v5
	v_rcp_f32_e32 v2, v2
	v_rcp_f32_e32 v3, v3
	v_rcp_f32_e32 v4, v4
	v_rcp_f32_e32 v5, v5
	v_mul_f32_e32 v2, 0xbf1b4598, v2
	v_mul_f32_e32 v3, 0xbf1b4598, v3
	v_mul_f32_e32 v4, 0xbf1b4598, v4
	v_mul_f32_e32 v5, 0xbf1b4598, v5
	v_mul_f32_e32 v2, 0x3fb8aa3b, v2
	v_mul_f32_e32 v3, 0x3fb8aa3b, v3
	v_mul_f32_e32 v4, 0x3fb8aa3b, v4
	v_mul_f32_e32 v5, 0x3fb8aa3b, v5
	v_exp_f32_e32 v2, v2
	v_exp_f32_e32 v3, v3
	v_exp_f32_e32 v4, v4
	v_exp_f32_e32 v5, v5
	global_store_dwordx4 v[36:37], v[2:5], off offset:128
	s_nop 2
	v_mov_b32_e32 v6, v108
	v_mov_b32_e32 v7, v109
	v_mov_b32_e32 v8, v110
	v_mov_b32_e32 v9, v111
	ds_read_b128 v[2:5], v0 offset:8064
	s_waitcnt lgkmcnt(0)
	v_add_f32_e32 v0, v2, v6
	v_mul_f32_e32 v0, 0xbfb8aa3b, v0
	v_exp_f32_e32 v0, v0
	s_nop 0
	v_add_f32_e32 v0, 1.0, v0
	v_rcp_f32_e32 v0, v0
	s_nop 0
	v_mul_f32_e32 v0, 0xbf1b4598, v0
	v_mul_f32_e32 v0, 0x3fb8aa3b, v0
	v_exp_f32_e32 v2, v0
	v_add_f32_e32 v0, v3, v7
	v_mul_f32_e32 v0, 0xbfb8aa3b, v0
	v_exp_f32_e32 v0, v0
	s_nop 0
	v_add_f32_e32 v0, 1.0, v0
	v_rcp_f32_e32 v0, v0
	s_nop 0
	v_mul_f32_e32 v0, 0xbf1b4598, v0
	v_mul_f32_e32 v0, 0x3fb8aa3b, v0
	v_exp_f32_e32 v3, v0
	v_add_f32_e32 v0, v4, v8
	v_mul_f32_e32 v0, 0xbfb8aa3b, v0
	v_exp_f32_e32 v0, v0
	s_nop 0
	v_add_f32_e32 v0, 1.0, v0
	v_rcp_f32_e32 v0, v0
	s_nop 0
	v_mul_f32_e32 v0, 0xbf1b4598, v0
	v_mul_f32_e32 v0, 0x3fb8aa3b, v0
	v_exp_f32_e32 v4, v0
	v_add_f32_e32 v0, v5, v9
	v_mul_f32_e32 v0, 0xbfb8aa3b, v0
	v_exp_f32_e32 v0, v0
	s_nop 0
	v_add_f32_e32 v0, 1.0, v0
	v_rcp_f32_e32 v0, v0
	s_nop 0
	v_mul_f32_e32 v0, 0xbf1b4598, v0
	v_mul_f32_e32 v0, 0x3fb8aa3b, v0
	v_exp_f32_e32 v5, v0
	global_store_dwordx4 v[34:35], v[2:5], off offset:128
	s_cbranch_scc0 .LBB0_294

.LBB0_297:
	s_and_b32 s9, s8, 1
	s_ashr_i32 s2, s8, 1
	s_lshl_b32 s3, s9, 14
	s_add_u32 s12, s6, s3
	v_mov_b32_e32 v98, v131
	v_mov_b32_e32 v99, v131
	s_addc_u32 s13, s7, 0
	s_ashr_i32 s3, s2, 31
	s_waitcnt vmcnt(10)
	v_mov_b32_e32 v8, v131
	s_lshl_b64 s[14:15], s[2:3], 15
	s_add_u32 s14, s40, s14
	v_ashrrev_i32_e32 v2, 3, v8
	v_lshrrev_b32_e32 v0, 4, v8
	v_xor_b32_e32 v0, v0, v8
	v_ashrrev_i32_e32 v3, 31, v2
	s_addc_u32 s15, s41, s15
	v_lshlrev_b64 v[4:5], 7, v[2:3]
	v_lshlrev_b32_e32 v0, 4, v0
	v_lshlrev_b64 v[2:3], 8, v[2:3]
	v_lshl_add_u64 v[4:5], s[12:13], 0, v[4:5]
	v_and_b32_e32 v0, 0x70, v0
	v_lshl_add_u64 v[2:3], s[14:15], 0, v[2:3]
	s_waitcnt vmcnt(8)
	v_lshlrev_b32_e32 v14, 4, v8
	v_and_b32_e32 v9, 31, v8
	v_lshl_add_u64 v[4:5], v[4:5], 0, v[0:1]
	v_lshl_add_u64 v[2:3], v[2:3], 0, v[0:1]
	v_lshrrev_b32_e32 v0, 1, v8
	v_readfirstlane_b32 s3, v14
	v_add_u32_e32 v15, 0x1000, v14
	v_and_or_b32 v0, v0, s16, v9
	v_lshlrev_b32_e32 v9, 7, v8
	s_mov_b32 m0, s3
	v_readfirstlane_b32 s3, v15
	v_add_u32_e32 v15, 0x2000, v14
	v_lshrrev_b32_e32 v10, 5, v8
	v_bfe_u32 v11, v8, 5, 1
	v_bfe_u32 v12, v8, 1, 3
	v_and_b32_e32 v13, 0x2f80, v9
	global_load_lds_dwordx4 v[4:5], off
	v_lshl_add_u64 v[8:9], v[4:5], 0, s[70:71]
	s_mov_b32 m0, s3
	v_readfirstlane_b32 s3, v15
	global_load_lds_dwordx4 v[8:9], off
	v_lshl_add_u64 v[8:9], v[4:5], 0, s[52:53]
	s_mov_b32 m0, s3
	v_lshl_add_u64 v[4:5], v[4:5], 0, s[60:61]
	global_load_lds_dwordx4 v[8:9], off
	v_add_u32_e32 v8, 0x3000, v14
	v_lshl_add_u64 v[6:7], v[2:3], 0, s[24:25]
	v_readfirstlane_b32 s3, v8
	s_mov_b32 m0, s3
	v_lshlrev_b32_e32 v0, 7, v0
	global_load_lds_dwordx4 v[4:5], off
	v_add_u32_e32 v4, 0x4000, v14
	v_lshrrev_b32_e32 v100, 6, v99
	v_readfirstlane_b32 s3, v4
	s_mov_b32 m0, s3
	v_lshl_add_u64 v[4:5], v[2:3], 0, s[20:21]
	global_load_lds_dwordx4 v[6:7], off
	v_add_u32_e32 v6, 0x5000, v14
	v_and_b32_e32 v101, 31, v98
	v_readfirstlane_b32 s3, v6
	v_add_u32_e32 v6, 0x6000, v14
	s_mov_b32 m0, s3
	v_readfirstlane_b32 s3, v6
	global_load_lds_dwordx4 v[4:5], off
	v_lshl_add_u64 v[4:5], v[2:3], 0, s[44:45]
	s_mov_b32 m0, s3
	v_lshl_add_u64 v[2:3], v[2:3], 0, s[46:47]
	global_load_lds_dwordx4 v[4:5], off
	v_add_u32_e32 v4, 0x7000, v14
	s_lshl_b32 s2, s2, 7
	v_readfirstlane_b32 s3, v4
	s_mov_b32 m0, s3
	s_add_i32 s8, s8, s76
	global_load_lds_dwordx4 v[2:3], off
	v_bitop3_b32 v2, v10, v12, 1 bitop3:0x6c
	v_lshlrev_b32_e32 v2, 4, v2
	v_or_b32_e32 v6, v2, v0
	v_or_b32_e32 v14, v2, v13
	v_bitop3_b32 v2, v11, v12, 2 bitop3:0x36
	v_lshlrev_b32_e32 v2, 4, v2
	s_waitcnt vmcnt(0)
	v_or_b32_e32 v18, v2, v0
	v_or_b32_e32 v19, v2, v13
	v_bitop3_b32 v2, v11, v12, 4 bitop3:0x36
	v_lshlrev_b32_e32 v2, 4, v2
	v_or_b32_e32 v86, v2, v0
	v_or_b32_e32 v94, v2, v13
	v_bitop3_b32 v2, v11, v12, 6 bitop3:0x36
	v_lshlrev_b32_e32 v2, 4, v2
	s_waitcnt vmcnt(0)
	s_waitcnt lgkmcnt(0)
	s_barrier
	v_or_b32_e32 v0, v2, v0
	v_or_b32_e32 v102, v2, v13
	ds_read_b128 v[2:5], v6 offset:0
	ds_read_b128 v[6:9], v6 offset:0x1000
	ds_read_b128 v[10:13], v14 offset:0x4000
	ds_read_b128 v[14:17], v14 offset:0x5000
	ds_read_b128 v[66:69], v18 offset:0
	ds_read_b128 v[70:73], v18 offset:0x1000
	ds_read_b128 v[74:77], v19 offset:0x4000
	ds_read_b128 v[78:81], v19 offset:0x5000
	s_cmpk_gt_i32 s8, 0xbf
	s_waitcnt lgkmcnt(4)
	ds_read_b128 v[82:85], v86 offset:0
	ds_read_b128 v[86:89], v86 offset:0x1000
	ds_read_b128 v[90:93], v94 offset:0x4000
	ds_read_b128 v[94:97], v94 offset:0x5000
	s_waitcnt lgkmcnt(4)
	s_nop 0
	v_mfma_f32_32x32x16_f16 v[50:65], v[2:5], v[10:13], 0
	v_mfma_f32_32x32x16_f16 v[18:33], v[6:9], v[10:13], 0
	v_mfma_f32_32x32x16_f16 v[34:49], v[2:5], v[14:17], 0
	v_mfma_f32_32x32x16_f16 v[2:17], v[6:9], v[14:17], 0
	v_mfma_f32_32x32x16_f16 v[50:65], v[66:69], v[74:77], v[50:65]
	v_mfma_f32_32x32x16_f16 v[18:33], v[70:73], v[74:77], v[18:33]
	v_mfma_f32_32x32x16_f16 v[2:17], v[70:73], v[78:81], v[2:17]
	v_mfma_f32_32x32x16_f16 v[34:49], v[66:69], v[78:81], v[34:49]
	ds_read_b128 v[66:69], v0 offset:0
	ds_read_b128 v[70:73], v0 offset:0x1000
	ds_read_b128 v[74:77], v102 offset:0x4000
	ds_read_b128 v[78:81], v102 offset:0x5000
	s_waitcnt lgkmcnt(4)
	v_mul_lo_u32 v0, v100, s66
	s_waitcnt lgkmcnt(0)
	v_mfma_f32_32x32x16_f16 v[50:65], v[82:85], v[90:93], v[50:65]
	s_waitcnt vmcnt(0)
	s_barrier
	v_mfma_f32_32x32x16_f16 v[18:33], v[86:89], v[90:93], v[18:33]
	v_mfma_f32_32x32x16_f16 v[2:17], v[86:89], v[94:97], v[2:17]
	v_mfma_f32_32x32x16_f16 v[34:49], v[82:85], v[94:97], v[34:49]
	v_mfma_f32_32x32x16_f16 v[50:65], v[66:69], v[74:77], v[50:65]
	v_mfma_f32_32x32x16_f16 v[18:33], v[70:73], v[74:77], v[18:33]
	v_add_u32_e32 v76, 0xa000, v0
	v_lshrrev_b32_e32 v0, 1, v98
	v_and_b32_e32 v77, 16, v0
	v_ashrrev_i32_e32 v0, 1, v99
	v_and_b32_e32 v0, 0xffffffc0, v0
	v_mfma_f32_32x32x16_f16 v[2:17], v[70:73], v[78:81], v[2:17]
	v_lshl_add_u32 v71, s9, 7, v0
	v_and_b32_e32 v0, 7, v98
	v_mul_u32_u24_e32 v70, 0x90, v101
	v_add3_u32 v70, v76, v70, v77
	s_nop 0
	ds_write_b128 v70, v[50:53]
	ds_write_b128 v70, v[54:57] offset:32
	ds_write_b128 v70, v[58:61] offset:64
	ds_write_b128 v70, v[62:65] offset:96
	v_bfe_u32 v72, v98, 3, 3
	v_mfma_f32_32x32x16_f16 v[34:49], v[66:69], v[78:81], v[34:49]
	v_lshlrev_b32_e32 v66, 2, v0
	v_lshrrev_b32_e32 v67, 6, v71
	v_or_b32_e32 v66, v71, v66
	v_mul_lo_u32 v74, v67, s4
	v_ashrrev_i32_e32 v67, 31, v66
	v_lshl_add_u64 v[68:69], v[66:67], 2, s[42:43]
	global_load_dwordx4 v[54:57], v[68:69], off
	v_lshlrev_b32_e32 v0, 4, v0
	v_or_b32_e32 v50, v76, v0
	v_mad_u32_u24 v62, v72, s67, v50
	ds_read_b128 v[50:53], v62
	v_and_or_b32 v73, v99, 64, s2
	s_load_dwordx2 s[2:3], s[28:29], 0x1c8
	v_ashrrev_i32_e32 v75, 31, v74
	v_lshlrev_b64 v[60:61], 2, v[74:75]
	v_or_b32_e32 v63, 8, v72
	v_or_b32_e32 v67, 16, v72
	s_waitcnt lgkmcnt(0)
	v_mov_b64_e32 v[58:59], s[2:3]
	v_or_b32_e32 v82, 24, v72
	s_waitcnt vmcnt(0)
	v_mov_b32_e32 v104, v54
	v_mov_b32_e32 v105, v55
	v_mov_b32_e32 v106, v56
	v_mov_b32_e32 v107, v57
	v_add_f32_e32 v50, v50, v54
	v_mul_f32_e32 v50, 0xbfb8aa3b, v50
	v_exp_f32_e32 v50, v50
	s_nop 0
	v_add_f32_e32 v50, 1.0, v50
	v_rcp_f32_e32 v50, v50
	s_nop 0
	v_mul_f32_e32 v50, 0xbf1b4598, v50
	v_mul_f32_e32 v50, 0x3fb8aa3b, v50
	v_exp_f32_e32 v54, v50
	v_add_f32_e32 v50, v51, v55
	v_mul_f32_e32 v50, 0xbfb8aa3b, v50
	v_exp_f32_e32 v50, v50
	s_nop 0
	v_add_f32_e32 v50, 1.0, v50
	v_rcp_f32_e32 v50, v50
	s_nop 0
	v_mul_f32_e32 v50, 0xbf1b4598, v50
	v_mul_f32_e32 v50, 0x3fb8aa3b, v50
	v_exp_f32_e32 v55, v50
	v_add_f32_e32 v50, v52, v56
	v_mul_f32_e32 v50, 0xbfb8aa3b, v50
	v_exp_f32_e32 v50, v50
	s_nop 0
	v_add_f32_e32 v50, 1.0, v50
	v_rcp_f32_e32 v50, v50
	s_nop 0
	v_mul_f32_e32 v50, 0xbf1b4598, v50
	v_mul_f32_e32 v50, 0x3fb8aa3b, v50
	v_exp_f32_e32 v56, v50
	v_add_f32_e32 v50, v53, v57
	v_mul_f32_e32 v50, 0xbfb8aa3b, v50
	v_exp_f32_e32 v50, v50
	s_nop 0
	v_add_f32_e32 v50, 1.0, v50
	v_rcp_f32_e32 v50, v50
	s_nop 0
	v_mul_f32_e32 v50, 0xbf1b4598, v50
	v_mul_f32_e32 v50, 0x3fb8aa3b, v50
	v_exp_f32_e32 v57, v50
	v_or_b32_e32 v50, v73, v72
	v_mad_i64_i32 v[50:51], s[2:3], v50, s17, v[58:59]
	v_lshl_add_u64 v[50:51], v[50:51], 0, v[60:61]
	v_lshl_add_u64 v[52:53], v[50:51], 0, v[0:1]
	v_lshl_add_u64 v[50:51], v[52:53], 0, s[48:49]
	v_add_co_u32_e32 v52, vcc, s50, v52
	s_nop 1
	v_addc_co_u32_e32 v53, vcc, 0, v53, vcc
	global_store_dwordx4 v[52:53], v[54:57], off
	s_nop 2
	v_mov_b32_e32 v74, v104
	v_mov_b32_e32 v75, v105
	v_mov_b32_e32 v76, v106
	v_mov_b32_e32 v77, v107
	ds_read_b128 v[52:55], v62 offset:1152
	s_waitcnt lgkmcnt(0)
	v_add_f32_e32 v52, v52, v74
	v_mul_f32_e32 v52, 0xbfb8aa3b, v52
	v_exp_f32_e32 v52, v52
	s_nop 0
	v_add_f32_e32 v52, 1.0, v52
	v_rcp_f32_e32 v52, v52
	s_nop 0
	v_mul_f32_e32 v52, 0xbf1b4598, v52
	v_mul_f32_e32 v52, 0x3fb8aa3b, v52
	v_exp_f32_e32 v74, v52
	v_add_f32_e32 v52, v53, v75
	v_mul_f32_e32 v52, 0xbfb8aa3b, v52
	v_exp_f32_e32 v52, v52
	s_nop 0
	v_add_f32_e32 v52, 1.0, v52
	v_rcp_f32_e32 v52, v52
	s_nop 0
	v_mul_f32_e32 v52, 0xbf1b4598, v52
	v_mul_f32_e32 v52, 0x3fb8aa3b, v52
	v_exp_f32_e32 v75, v52
	v_add_f32_e32 v52, v54, v76
	v_mul_f32_e32 v52, 0xbfb8aa3b, v52
	v_exp_f32_e32 v52, v52
	s_nop 0
	v_add_f32_e32 v52, 1.0, v52
	v_rcp_f32_e32 v52, v52
	s_nop 0
	v_mul_f32_e32 v52, 0xbf1b4598, v52
	v_mul_f32_e32 v52, 0x3fb8aa3b, v52
	v_exp_f32_e32 v76, v52
	v_add_f32_e32 v52, v55, v77
	v_mul_f32_e32 v52, 0xbfb8aa3b, v52
	v_exp_f32_e32 v52, v52
	s_nop 0
	v_add_f32_e32 v52, 1.0, v52
	v_rcp_f32_e32 v52, v52
	s_nop 0
	v_mul_f32_e32 v52, 0xbf1b4598, v52
	v_mul_f32_e32 v52, 0x3fb8aa3b, v52
	v_exp_f32_e32 v77, v52
	v_or_b32_e32 v52, v63, v73
	v_mad_i64_i32 v[52:53], s[2:3], v52, s17, v[58:59]
	v_lshl_add_u64 v[52:53], v[52:53], 0, v[60:61]
	v_lshl_add_u64 v[52:53], v[52:53], 0, v[0:1]
	v_lshl_add_u64 v[54:55], v[52:53], 0, s[48:49]
	v_add_co_u32_e32 v52, vcc, s50, v52
	s_nop 1
	v_addc_co_u32_e32 v53, vcc, 0, v53, vcc
	global_store_dwordx4 v[52:53], v[74:77], off
	s_nop 2
	v_mov_b32_e32 v78, v104
	v_mov_b32_e32 v79, v105
	v_mov_b32_e32 v80, v106
	v_mov_b32_e32 v81, v107
	ds_read_b128 v[74:77], v62 offset:2304
	s_waitcnt lgkmcnt(0)
	v_add_f32_e32 v52, v74, v78
	v_mul_f32_e32 v52, 0xbfb8aa3b, v52
	v_exp_f32_e32 v52, v52
	s_nop 0
	v_add_f32_e32 v52, 1.0, v52
	v_rcp_f32_e32 v52, v52
	s_nop 0
	v_mul_f32_e32 v52, 0xbf1b4598, v52
	v_mul_f32_e32 v52, 0x3fb8aa3b, v52
	v_exp_f32_e32 v74, v52
	v_add_f32_e32 v52, v75, v79
	v_mul_f32_e32 v52, 0xbfb8aa3b, v52
	v_exp_f32_e32 v52, v52
	s_nop 0
	v_add_f32_e32 v52, 1.0, v52
	v_rcp_f32_e32 v52, v52
	s_nop 0
	v_mul_f32_e32 v52, 0xbf1b4598, v52
	v_mul_f32_e32 v52, 0x3fb8aa3b, v52
	v_exp_f32_e32 v75, v52
	v_add_f32_e32 v52, v76, v80
	v_mul_f32_e32 v52, 0xbfb8aa3b, v52
	v_exp_f32_e32 v52, v52
	s_nop 0
	v_add_f32_e32 v52, 1.0, v52
	v_rcp_f32_e32 v52, v52
	s_nop 0
	v_mul_f32_e32 v52, 0xbf1b4598, v52
	v_mul_f32_e32 v52, 0x3fb8aa3b, v52
	v_exp_f32_e32 v76, v52
	v_add_f32_e32 v52, v77, v81
	v_mul_f32_e32 v52, 0xbfb8aa3b, v52
	v_exp_f32_e32 v52, v52
	s_nop 0
	v_add_f32_e32 v52, 1.0, v52
	v_rcp_f32_e32 v52, v52
	s_nop 0
	v_mul_f32_e32 v52, 0xbf1b4598, v52
	v_mul_f32_e32 v52, 0x3fb8aa3b, v52
	v_exp_f32_e32 v77, v52
	v_or_b32_e32 v52, v67, v73
	v_mad_i64_i32 v[52:53], s[2:3], v52, s17, v[58:59]
	v_lshl_add_u64 v[52:53], v[52:53], 0, v[60:61]
	v_lshl_add_u64 v[52:53], v[52:53], 0, v[0:1]
	v_lshl_add_u64 v[56:57], v[52:53], 0, s[48:49]
	v_add_co_u32_e32 v52, vcc, s50, v52
	s_nop 1
	v_addc_co_u32_e32 v53, vcc, 0, v53, vcc
	global_store_dwordx4 v[52:53], v[74:77], off
	s_nop 2
	v_mov_b32_e32 v78, v104
	v_mov_b32_e32 v79, v105
	v_mov_b32_e32 v80, v106
	v_mov_b32_e32 v81, v107
	ds_read_b128 v[74:77], v62 offset:3456
	s_waitcnt lgkmcnt(0)
	v_add_f32_e32 v52, v74, v78
	v_mul_f32_e32 v52, 0xbfb8aa3b, v52
	v_exp_f32_e32 v52, v52
	s_nop 0
	v_add_f32_e32 v52, 1.0, v52
	v_rcp_f32_e32 v52, v52
	s_nop 0
	v_mul_f32_e32 v52, 0xbf1b4598, v52
	v_mul_f32_e32 v52, 0x3fb8aa3b, v52
	v_exp_f32_e32 v74, v52
	v_add_f32_e32 v52, v75, v79
	v_mul_f32_e32 v52, 0xbfb8aa3b, v52
	v_exp_f32_e32 v52, v52
	s_nop 0
	v_add_f32_e32 v52, 1.0, v52
	v_rcp_f32_e32 v52, v52
	s_nop 0
	v_mul_f32_e32 v52, 0xbf1b4598, v52
	v_mul_f32_e32 v52, 0x3fb8aa3b, v52
	v_exp_f32_e32 v75, v52
	v_add_f32_e32 v52, v76, v80
	v_mul_f32_e32 v52, 0xbfb8aa3b, v52
	v_exp_f32_e32 v52, v52
	s_nop 0
	v_add_f32_e32 v52, 1.0, v52
	v_rcp_f32_e32 v52, v52
	s_nop 0
	v_mul_f32_e32 v52, 0xbf1b4598, v52
	v_mul_f32_e32 v52, 0x3fb8aa3b, v52
	v_exp_f32_e32 v76, v52
	v_add_f32_e32 v52, v77, v81
	v_mul_f32_e32 v52, 0xbfb8aa3b, v52
	v_exp_f32_e32 v52, v52
	s_nop 0
	v_add_f32_e32 v52, 1.0, v52
	v_rcp_f32_e32 v52, v52
	s_nop 0
	v_mul_f32_e32 v52, 0xbf1b4598, v52
	v_mul_f32_e32 v52, 0x3fb8aa3b, v52
	v_exp_f32_e32 v77, v52
	v_or_b32_e32 v52, v82, v73
	v_mad_i64_i32 v[52:53], s[2:3], v52, s17, v[58:59]
	v_lshl_add_u64 v[52:53], v[52:53], 0, v[60:61]
	v_lshl_add_u64 v[64:65], v[52:53], 0, v[0:1]
	v_lshl_add_u64 v[52:53], v[64:65], 0, s[48:49]
	v_add_co_u32_e32 v64, vcc, s50, v64
	s_nop 1
	v_addc_co_u32_e32 v65, vcc, 0, v65, vcc
	global_store_dwordx4 v[64:65], v[74:77], off
	ds_write_b128 v70, v[34:37] offset:4608
	ds_write_b128 v70, v[38:41] offset:4640
	ds_write_b128 v70, v[42:45] offset:4672
	ds_write_b128 v70, v[46:49] offset:4704
	s_nop 2
	v_mov_b32_e32 v38, v104
	v_mov_b32_e32 v39, v105
	v_mov_b32_e32 v40, v106
	v_mov_b32_e32 v41, v107
	ds_read_b128 v[34:37], v62 offset:4608
	v_or_b32_e32 v64, 32, v73
	s_waitcnt lgkmcnt(0)
	v_add_f32_e32 v34, v34, v38
	v_add_f32_e32 v35, v35, v39
	v_add_f32_e32 v36, v36, v40
	v_add_f32_e32 v37, v37, v41
	v_mul_f32_e32 v34, 0xbfb8aa3b, v34
	v_mul_f32_e32 v35, 0xbfb8aa3b, v35
	v_mul_f32_e32 v36, 0xbfb8aa3b, v36
	v_mul_f32_e32 v37, 0xbfb8aa3b, v37
	v_exp_f32_e32 v34, v34
	v_exp_f32_e32 v35, v35
	v_exp_f32_e32 v36, v36
	v_exp_f32_e32 v37, v37
	v_add_f32_e32 v34, 1.0, v34
	v_add_f32_e32 v35, 1.0, v35
	v_add_f32_e32 v36, 1.0, v36
	v_add_f32_e32 v37, 1.0, v37
	v_rcp_f32_e32 v34, v34
	v_rcp_f32_e32 v35, v35
	v_rcp_f32_e32 v36, v36
	v_rcp_f32_e32 v37, v37
	v_mul_f32_e32 v34, 0xbf1b4598, v34
	v_mul_f32_e32 v35, 0xbf1b4598, v35
	v_mul_f32_e32 v36, 0xbf1b4598, v36
	v_mul_f32_e32 v37, 0xbf1b4598, v37
	v_or_b32_e32 v38, v64, v72
	v_mul_f32_e32 v34, 0x3fb8aa3b, v34
	v_mul_f32_e32 v35, 0x3fb8aa3b, v35
	v_mul_f32_e32 v36, 0x3fb8aa3b, v36
	v_mul_f32_e32 v37, 0x3fb8aa3b, v37
	v_mad_i64_i32 v[38:39], s[2:3], v38, s17, v[58:59]
	v_exp_f32_e32 v34, v34
	v_exp_f32_e32 v35, v35
	v_exp_f32_e32 v36, v36
	v_exp_f32_e32 v37, v37
	v_lshl_add_u64 v[38:39], v[38:39], 0, v[60:61]
	v_lshl_add_u64 v[38:39], v[38:39], 0, v[0:1]
	v_lshl_add_u64 v[40:41], v[38:39], 0, s[48:49]
	v_add_co_u32_e32 v38, vcc, s50, v38
	s_nop 1
	v_addc_co_u32_e32 v39, vcc, 0, v39, vcc
	global_store_dwordx4 v[38:39], v[34:37], off
	s_nop 2
	v_mov_b32_e32 v42, v104
	v_mov_b32_e32 v43, v105
	v_mov_b32_e32 v44, v106
	v_mov_b32_e32 v45, v107
	ds_read_b128 v[34:37], v62 offset:5760
	s_waitcnt lgkmcnt(0)
	v_add_f32_e32 v34, v34, v42
	v_mul_f32_e32 v34, 0xbfb8aa3b, v34
	v_exp_f32_e32 v34, v34
	s_nop 0
	v_add_f32_e32 v34, 1.0, v34
	v_rcp_f32_e32 v34, v34
	s_nop 0
	v_mul_f32_e32 v34, 0xbf1b4598, v34
	v_mul_f32_e32 v34, 0x3fb8aa3b, v34
	v_exp_f32_e32 v42, v34
	v_add_f32_e32 v34, v35, v43
	v_mul_f32_e32 v34, 0xbfb8aa3b, v34
	v_exp_f32_e32 v34, v34
	s_nop 0
	v_add_f32_e32 v34, 1.0, v34
	v_rcp_f32_e32 v34, v34
	s_nop 0
	v_mul_f32_e32 v34, 0xbf1b4598, v34
	v_mul_f32_e32 v34, 0x3fb8aa3b, v34
	v_exp_f32_e32 v43, v34
	v_add_f32_e32 v34, v36, v44
	v_mul_f32_e32 v34, 0xbfb8aa3b, v34
	v_exp_f32_e32 v34, v34
	s_nop 0
	v_add_f32_e32 v34, 1.0, v34
	v_rcp_f32_e32 v34, v34
	s_nop 0
	v_mul_f32_e32 v34, 0xbf1b4598, v34
	v_mul_f32_e32 v34, 0x3fb8aa3b, v34
	v_exp_f32_e32 v44, v34
	v_add_f32_e32 v34, v37, v45
	v_mul_f32_e32 v34, 0xbfb8aa3b, v34
	v_exp_f32_e32 v34, v34
	s_nop 0
	v_add_f32_e32 v34, 1.0, v34
	v_rcp_f32_e32 v34, v34
	s_nop 0
	v_mul_f32_e32 v34, 0xbf1b4598, v34
	v_mul_f32_e32 v34, 0x3fb8aa3b, v34
	v_exp_f32_e32 v45, v34
	v_or_b32_e32 v34, v64, v63
	v_mad_i64_i32 v[34:35], s[2:3], v34, s17, v[58:59]
	v_lshl_add_u64 v[34:35], v[34:35], 0, v[60:61]
	v_lshl_add_u64 v[34:35], v[34:35], 0, v[0:1]
	v_lshl_add_u64 v[36:37], v[34:35], 0, s[48:49]
	v_add_co_u32_e32 v34, vcc, s50, v34
	s_nop 1
	v_addc_co_u32_e32 v35, vcc, 0, v35, vcc
	global_store_dwordx4 v[34:35], v[42:45], off
	s_nop 2
	v_mov_b32_e32 v46, v104
	v_mov_b32_e32 v47, v105
	v_mov_b32_e32 v48, v106
	v_mov_b32_e32 v49, v107
	ds_read_b128 v[42:45], v62 offset:6912
	s_waitcnt lgkmcnt(0)
	v_add_f32_e32 v34, v42, v46
	v_mul_f32_e32 v34, 0xbfb8aa3b, v34
	v_exp_f32_e32 v34, v34
	s_nop 0
	v_add_f32_e32 v34, 1.0, v34
	v_rcp_f32_e32 v34, v34
	s_nop 0
	v_mul_f32_e32 v34, 0xbf1b4598, v34
	v_mul_f32_e32 v34, 0x3fb8aa3b, v34
	v_exp_f32_e32 v42, v34
	v_add_f32_e32 v34, v43, v47
	v_mul_f32_e32 v34, 0xbfb8aa3b, v34
	v_exp_f32_e32 v34, v34
	s_nop 0
	v_add_f32_e32 v34, 1.0, v34
	v_rcp_f32_e32 v34, v34
	s_nop 0
	v_mul_f32_e32 v34, 0xbf1b4598, v34
	v_mul_f32_e32 v34, 0x3fb8aa3b, v34
	v_exp_f32_e32 v43, v34
	v_add_f32_e32 v34, v44, v48
	v_mul_f32_e32 v34, 0xbfb8aa3b, v34
	v_exp_f32_e32 v34, v34
	s_nop 0
	v_add_f32_e32 v34, 1.0, v34
	v_rcp_f32_e32 v34, v34
	s_nop 0
	v_mul_f32_e32 v34, 0xbf1b4598, v34
	v_mul_f32_e32 v34, 0x3fb8aa3b, v34
	v_exp_f32_e32 v44, v34
	v_add_f32_e32 v34, v45, v49
	v_mul_f32_e32 v34, 0xbfb8aa3b, v34
	v_exp_f32_e32 v34, v34
	s_nop 0
	v_add_f32_e32 v34, 1.0, v34
	v_rcp_f32_e32 v34, v34
	s_nop 0
	v_mul_f32_e32 v34, 0xbf1b4598, v34
	v_mul_f32_e32 v34, 0x3fb8aa3b, v34
	v_exp_f32_e32 v45, v34
	v_or_b32_e32 v34, v64, v67
	v_mad_i64_i32 v[34:35], s[2:3], v34, s17, v[58:59]
	v_lshl_add_u64 v[34:35], v[34:35], 0, v[60:61]
	v_lshl_add_u64 v[34:35], v[34:35], 0, v[0:1]
	v_lshl_add_u64 v[38:39], v[34:35], 0, s[48:49]
	v_add_co_u32_e32 v34, vcc, s50, v34
	v_ashrrev_i32_e32 v67, 31, v71
	s_nop 0
	v_addc_co_u32_e32 v35, vcc, 0, v35, vcc
	global_store_dwordx4 v[34:35], v[42:45], off
	s_nop 2
	v_mov_b32_e32 v46, v104
	v_mov_b32_e32 v47, v105
	v_mov_b32_e32 v48, v106
	v_mov_b32_e32 v49, v107
	ds_read_b128 v[42:45], v62 offset:8064
	s_waitcnt lgkmcnt(0)
	v_add_f32_e32 v34, v42, v46
	v_mul_f32_e32 v34, 0xbfb8aa3b, v34
	v_exp_f32_e32 v34, v34
	s_nop 0
	v_add_f32_e32 v34, 1.0, v34
	v_rcp_f32_e32 v34, v34
	s_nop 0
	v_mul_f32_e32 v34, 0xbf1b4598, v34
	v_mul_f32_e32 v34, 0x3fb8aa3b, v34
	v_exp_f32_e32 v42, v34
	v_add_f32_e32 v34, v43, v47
	v_mul_f32_e32 v34, 0xbfb8aa3b, v34
	v_exp_f32_e32 v34, v34
	s_nop 0
	v_add_f32_e32 v34, 1.0, v34
	v_rcp_f32_e32 v34, v34
	s_nop 0
	v_mul_f32_e32 v34, 0xbf1b4598, v34
	v_mul_f32_e32 v34, 0x3fb8aa3b, v34
	v_exp_f32_e32 v43, v34
	v_add_f32_e32 v34, v44, v48
	v_mul_f32_e32 v34, 0xbfb8aa3b, v34
	v_exp_f32_e32 v34, v34
	s_nop 0
	v_add_f32_e32 v34, 1.0, v34
	v_rcp_f32_e32 v34, v34
	s_nop 0
	v_mul_f32_e32 v34, 0xbf1b4598, v34
	v_mul_f32_e32 v34, 0x3fb8aa3b, v34
	v_exp_f32_e32 v44, v34
	v_add_f32_e32 v34, v45, v49
	v_mul_f32_e32 v34, 0xbfb8aa3b, v34
	v_exp_f32_e32 v34, v34
	s_nop 0
	v_add_f32_e32 v34, 1.0, v34
	v_rcp_f32_e32 v34, v34
	s_nop 0
	v_mul_f32_e32 v34, 0xbf1b4598, v34
	v_mul_f32_e32 v34, 0x3fb8aa3b, v34
	v_exp_f32_e32 v45, v34
	v_or_b32_e32 v34, v64, v82
	v_mad_i64_i32 v[34:35], s[2:3], v34, s17, v[58:59]
	v_lshl_add_u64 v[34:35], v[34:35], 0, v[60:61]
	v_lshl_add_u64 v[46:47], v[34:35], 0, v[0:1]
	v_lshl_add_u64 v[34:35], v[46:47], 0, s[48:49]
	v_add_co_u32_e32 v46, vcc, s50, v46
	s_nop 1
	v_addc_co_u32_e32 v47, vcc, 0, v47, vcc
	global_store_dwordx4 v[46:47], v[42:45], off
	ds_write_b128 v70, v[18:21]
	ds_write_b128 v70, v[22:25] offset:32
	ds_write_b128 v70, v[26:29] offset:64
	ds_write_b128 v70, v[30:33] offset:96
	v_lshl_add_u64 v[42:43], v[66:67], 2, s[42:43]
	global_load_dwordx4 v[22:25], v[42:43], off offset:128
	ds_read_b128 v[18:21], v62
	s_waitcnt vmcnt(0) lgkmcnt(0)
	v_mov_b32_e32 v108, v22
	v_mov_b32_e32 v109, v23
	v_mov_b32_e32 v110, v24
	v_mov_b32_e32 v111, v25
	v_add_f32_e32 v0, v18, v22
	v_mul_f32_e32 v0, 0xbfb8aa3b, v0
	v_exp_f32_e32 v0, v0
	s_nop 0
	v_add_f32_e32 v0, 1.0, v0
	v_rcp_f32_e32 v0, v0
	s_nop 0
	v_mul_f32_e32 v0, 0xbf1b4598, v0
	v_mul_f32_e32 v0, 0x3fb8aa3b, v0
	v_exp_f32_e32 v18, v0
	v_add_f32_e32 v0, v19, v23
	v_mul_f32_e32 v0, 0xbfb8aa3b, v0
	v_exp_f32_e32 v0, v0
	s_nop 0
	v_add_f32_e32 v0, 1.0, v0
	v_rcp_f32_e32 v0, v0
	s_nop 0
	v_mul_f32_e32 v0, 0xbf1b4598, v0
	v_mul_f32_e32 v0, 0x3fb8aa3b, v0
	v_exp_f32_e32 v19, v0
	v_add_f32_e32 v0, v20, v24
	v_mul_f32_e32 v0, 0xbfb8aa3b, v0
	v_exp_f32_e32 v0, v0
	s_nop 0
	v_add_f32_e32 v0, 1.0, v0
	v_rcp_f32_e32 v0, v0
	s_nop 0
	v_mul_f32_e32 v0, 0xbf1b4598, v0
	v_mul_f32_e32 v0, 0x3fb8aa3b, v0
	v_exp_f32_e32 v20, v0
	v_add_f32_e32 v0, v21, v25
	v_mul_f32_e32 v0, 0xbfb8aa3b, v0
	v_exp_f32_e32 v0, v0
	s_nop 0
	v_add_f32_e32 v0, 1.0, v0
	v_rcp_f32_e32 v0, v0
	s_nop 0
	v_mul_f32_e32 v0, 0xbf1b4598, v0
	v_mul_f32_e32 v0, 0x3fb8aa3b, v0
	v_exp_f32_e32 v21, v0
	global_store_dwordx4 v[50:51], v[18:21], off offset:128
	s_nop 2
	v_mov_b32_e32 v22, v108
	v_mov_b32_e32 v23, v109
	v_mov_b32_e32 v24, v110
	v_mov_b32_e32 v25, v111
	ds_read_b128 v[18:21], v62 offset:1152
	s_waitcnt lgkmcnt(0)
	v_add_f32_e32 v0, v18, v22
	v_mul_f32_e32 v0, 0xbfb8aa3b, v0
	v_exp_f32_e32 v0, v0
	s_nop 0
	v_add_f32_e32 v0, 1.0, v0
	v_rcp_f32_e32 v0, v0
	s_nop 0
	v_mul_f32_e32 v0, 0xbf1b4598, v0
	v_mul_f32_e32 v0, 0x3fb8aa3b, v0
	v_exp_f32_e32 v18, v0
	v_add_f32_e32 v0, v19, v23
	v_mul_f32_e32 v0, 0xbfb8aa3b, v0
	v_exp_f32_e32 v0, v0
	s_nop 0
	v_add_f32_e32 v0, 1.0, v0
	v_rcp_f32_e32 v0, v0
	s_nop 0
	v_mul_f32_e32 v0, 0xbf1b4598, v0
	v_mul_f32_e32 v0, 0x3fb8aa3b, v0
	v_exp_f32_e32 v19, v0
	v_add_f32_e32 v0, v20, v24
	v_mul_f32_e32 v0, 0xbfb8aa3b, v0
	v_exp_f32_e32 v0, v0
	s_nop 0
	v_add_f32_e32 v0, 1.0, v0
	v_rcp_f32_e32 v0, v0
	s_nop 0
	v_mul_f32_e32 v0, 0xbf1b4598, v0
	v_mul_f32_e32 v0, 0x3fb8aa3b, v0
	v_exp_f32_e32 v20, v0
	v_add_f32_e32 v0, v21, v25
	v_mul_f32_e32 v0, 0xbfb8aa3b, v0
	v_exp_f32_e32 v0, v0
	s_nop 0
	v_add_f32_e32 v0, 1.0, v0
	v_rcp_f32_e32 v0, v0
	s_nop 0
	v_mul_f32_e32 v0, 0xbf1b4598, v0
	v_mul_f32_e32 v0, 0x3fb8aa3b, v0
	v_exp_f32_e32 v21, v0
	global_store_dwordx4 v[54:55], v[18:21], off offset:128
	s_nop 2
	v_mov_b32_e32 v22, v108
	v_mov_b32_e32 v23, v109
	v_mov_b32_e32 v24, v110
	v_mov_b32_e32 v25, v111
	ds_read_b128 v[18:21], v62 offset:2304
	s_waitcnt lgkmcnt(0)
	v_add_f32_e32 v0, v18, v22
	v_mul_f32_e32 v0, 0xbfb8aa3b, v0
	v_exp_f32_e32 v0, v0
	s_nop 0
	v_add_f32_e32 v0, 1.0, v0
	v_rcp_f32_e32 v0, v0
	s_nop 0
	v_mul_f32_e32 v0, 0xbf1b4598, v0
	v_mul_f32_e32 v0, 0x3fb8aa3b, v0
	v_exp_f32_e32 v18, v0
	v_add_f32_e32 v0, v19, v23
	v_mul_f32_e32 v0, 0xbfb8aa3b, v0
	v_exp_f32_e32 v0, v0
	s_nop 0
	v_add_f32_e32 v0, 1.0, v0
	v_rcp_f32_e32 v0, v0
	s_nop 0
	v_mul_f32_e32 v0, 0xbf1b4598, v0
	v_mul_f32_e32 v0, 0x3fb8aa3b, v0
	v_exp_f32_e32 v19, v0
	v_add_f32_e32 v0, v20, v24
	v_mul_f32_e32 v0, 0xbfb8aa3b, v0
	v_exp_f32_e32 v0, v0
	s_nop 0
	v_add_f32_e32 v0, 1.0, v0
	v_rcp_f32_e32 v0, v0
	s_nop 0
	v_mul_f32_e32 v0, 0xbf1b4598, v0
	v_mul_f32_e32 v0, 0x3fb8aa3b, v0
	v_exp_f32_e32 v20, v0
	v_add_f32_e32 v0, v21, v25
	v_mul_f32_e32 v0, 0xbfb8aa3b, v0
	v_exp_f32_e32 v0, v0
	s_nop 0
	v_add_f32_e32 v0, 1.0, v0
	v_rcp_f32_e32 v0, v0
	s_nop 0
	v_mul_f32_e32 v0, 0xbf1b4598, v0
	v_mul_f32_e32 v0, 0x3fb8aa3b, v0
	v_exp_f32_e32 v21, v0
	global_store_dwordx4 v[56:57], v[18:21], off offset:128
	s_nop 2
	v_mov_b32_e32 v22, v108
	v_mov_b32_e32 v23, v109
	v_mov_b32_e32 v24, v110
	v_mov_b32_e32 v25, v111
	ds_read_b128 v[18:21], v62 offset:3456
	s_waitcnt lgkmcnt(0)
	v_add_f32_e32 v0, v18, v22
	v_mul_f32_e32 v0, 0xbfb8aa3b, v0
	v_exp_f32_e32 v0, v0
	s_nop 0
	v_add_f32_e32 v0, 1.0, v0
	v_rcp_f32_e32 v0, v0
	s_nop 0
	v_mul_f32_e32 v0, 0xbf1b4598, v0
	v_mul_f32_e32 v0, 0x3fb8aa3b, v0
	v_exp_f32_e32 v18, v0
	v_add_f32_e32 v0, v19, v23
	v_mul_f32_e32 v0, 0xbfb8aa3b, v0
	v_exp_f32_e32 v0, v0
	s_nop 0
	v_add_f32_e32 v0, 1.0, v0
	v_rcp_f32_e32 v0, v0
	s_nop 0
	v_mul_f32_e32 v0, 0xbf1b4598, v0
	v_mul_f32_e32 v0, 0x3fb8aa3b, v0
	v_exp_f32_e32 v19, v0
	v_add_f32_e32 v0, v20, v24
	v_mul_f32_e32 v0, 0xbfb8aa3b, v0
	v_exp_f32_e32 v0, v0
	s_nop 0
	v_add_f32_e32 v0, 1.0, v0
	v_rcp_f32_e32 v0, v0
	s_nop 0
	v_mul_f32_e32 v0, 0xbf1b4598, v0
	v_mul_f32_e32 v0, 0x3fb8aa3b, v0
	v_exp_f32_e32 v20, v0
	v_add_f32_e32 v0, v21, v25
	v_mul_f32_e32 v0, 0xbfb8aa3b, v0
	v_exp_f32_e32 v0, v0
	s_nop 0
	v_add_f32_e32 v0, 1.0, v0
	v_rcp_f32_e32 v0, v0
	s_nop 0
	v_mul_f32_e32 v0, 0xbf1b4598, v0
	v_mul_f32_e32 v0, 0x3fb8aa3b, v0
	v_exp_f32_e32 v21, v0
	global_store_dwordx4 v[52:53], v[18:21], off offset:128
	ds_write_b128 v70, v[2:5] offset:4608
	ds_write_b128 v70, v[6:9] offset:4640
	ds_write_b128 v70, v[10:13] offset:4672
	ds_write_b128 v70, v[14:17] offset:4704
	s_nop 2
	v_mov_b32_e32 v6, v108
	v_mov_b32_e32 v7, v109
	v_mov_b32_e32 v8, v110
	v_mov_b32_e32 v9, v111
	ds_read_b128 v[2:5], v62 offset:4608
	s_waitcnt lgkmcnt(0)
	v_add_f32_e32 v0, v2, v6
	v_mul_f32_e32 v0, 0xbfb8aa3b, v0
	v_exp_f32_e32 v0, v0
	s_nop 0
	v_add_f32_e32 v0, 1.0, v0
	v_rcp_f32_e32 v0, v0
	s_nop 0
	v_mul_f32_e32 v0, 0xbf1b4598, v0
	v_mul_f32_e32 v0, 0x3fb8aa3b, v0
	v_exp_f32_e32 v2, v0
	v_add_f32_e32 v0, v3, v7
	v_mul_f32_e32 v0, 0xbfb8aa3b, v0
	v_exp_f32_e32 v0, v0
	s_nop 0
	v_add_f32_e32 v0, 1.0, v0
	v_rcp_f32_e32 v0, v0
	s_nop 0
	v_mul_f32_e32 v0, 0xbf1b4598, v0
	v_mul_f32_e32 v0, 0x3fb8aa3b, v0
	v_exp_f32_e32 v3, v0
	v_add_f32_e32 v0, v4, v8
	v_mul_f32_e32 v0, 0xbfb8aa3b, v0
	v_exp_f32_e32 v0, v0
	s_nop 0
	v_add_f32_e32 v0, 1.0, v0
	v_rcp_f32_e32 v0, v0
	s_nop 0
	v_mul_f32_e32 v0, 0xbf1b4598, v0
	v_mul_f32_e32 v0, 0x3fb8aa3b, v0
	v_exp_f32_e32 v4, v0
	v_add_f32_e32 v0, v5, v9
	v_mul_f32_e32 v0, 0xbfb8aa3b, v0
	v_exp_f32_e32 v0, v0
	s_nop 0
	v_add_f32_e32 v0, 1.0, v0
	v_rcp_f32_e32 v0, v0
	s_nop 0
	v_mul_f32_e32 v0, 0xbf1b4598, v0
	v_mul_f32_e32 v0, 0x3fb8aa3b, v0
	v_exp_f32_e32 v5, v0
	global_store_dwordx4 v[40:41], v[2:5], off offset:128
	s_nop 2
	v_mov_b32_e32 v6, v108
	v_mov_b32_e32 v7, v109
	v_mov_b32_e32 v8, v110
	v_mov_b32_e32 v9, v111
	ds_read_b128 v[2:5], v62 offset:5760
	s_waitcnt lgkmcnt(0)
	v_add_f32_e32 v0, v2, v6
	v_mul_f32_e32 v0, 0xbfb8aa3b, v0
	v_exp_f32_e32 v0, v0
	s_nop 0
	v_add_f32_e32 v0, 1.0, v0
	v_rcp_f32_e32 v0, v0
	s_nop 0
	v_mul_f32_e32 v0, 0xbf1b4598, v0
	v_mul_f32_e32 v0, 0x3fb8aa3b, v0
	v_exp_f32_e32 v2, v0
	v_add_f32_e32 v0, v3, v7
	v_mul_f32_e32 v0, 0xbfb8aa3b, v0
	v_exp_f32_e32 v0, v0
	s_nop 0
	v_add_f32_e32 v0, 1.0, v0
	v_rcp_f32_e32 v0, v0
	s_nop 0
	v_mul_f32_e32 v0, 0xbf1b4598, v0
	v_mul_f32_e32 v0, 0x3fb8aa3b, v0
	v_exp_f32_e32 v3, v0
	v_add_f32_e32 v0, v4, v8
	v_mul_f32_e32 v0, 0xbfb8aa3b, v0
	v_exp_f32_e32 v0, v0
	s_nop 0
	v_add_f32_e32 v0, 1.0, v0
	v_rcp_f32_e32 v0, v0
	s_nop 0
	v_mul_f32_e32 v0, 0xbf1b4598, v0
	v_mul_f32_e32 v0, 0x3fb8aa3b, v0
	v_exp_f32_e32 v4, v0
	v_add_f32_e32 v0, v5, v9
	v_mul_f32_e32 v0, 0xbfb8aa3b, v0
	v_exp_f32_e32 v0, v0
	s_nop 0
	v_add_f32_e32 v0, 1.0, v0
	v_rcp_f32_e32 v0, v0
	s_nop 0
	v_mul_f32_e32 v0, 0xbf1b4598, v0
	v_mul_f32_e32 v0, 0x3fb8aa3b, v0
	v_exp_f32_e32 v5, v0
	global_store_dwordx4 v[36:37], v[2:5], off offset:128
	s_nop 2
	v_mov_b32_e32 v6, v108
	v_mov_b32_e32 v7, v109
	v_mov_b32_e32 v8, v110
	v_mov_b32_e32 v9, v111
	ds_read_b128 v[2:5], v62 offset:6912
	s_waitcnt lgkmcnt(0)
	v_add_f32_e32 v0, v2, v6
	v_mul_f32_e32 v0, 0xbfb8aa3b, v0
	v_exp_f32_e32 v0, v0
	s_nop 0
	v_add_f32_e32 v0, 1.0, v0
	v_rcp_f32_e32 v0, v0
	s_nop 0
	v_mul_f32_e32 v0, 0xbf1b4598, v0
	v_mul_f32_e32 v0, 0x3fb8aa3b, v0
	v_exp_f32_e32 v2, v0
	v_add_f32_e32 v0, v3, v7
	v_mul_f32_e32 v0, 0xbfb8aa3b, v0
	v_exp_f32_e32 v0, v0
	s_nop 0
	v_add_f32_e32 v0, 1.0, v0
	v_rcp_f32_e32 v0, v0
	s_nop 0
	v_mul_f32_e32 v0, 0xbf1b4598, v0
	v_mul_f32_e32 v0, 0x3fb8aa3b, v0
	v_exp_f32_e32 v3, v0
	v_add_f32_e32 v0, v4, v8
	v_mul_f32_e32 v0, 0xbfb8aa3b, v0
	v_exp_f32_e32 v0, v0
	s_nop 0
	v_add_f32_e32 v0, 1.0, v0
	v_rcp_f32_e32 v0, v0
	s_nop 0
	v_mul_f32_e32 v0, 0xbf1b4598, v0
	v_mul_f32_e32 v0, 0x3fb8aa3b, v0
	v_exp_f32_e32 v4, v0
	v_add_f32_e32 v0, v5, v9
	v_mul_f32_e32 v0, 0xbfb8aa3b, v0
	v_exp_f32_e32 v0, v0
	s_nop 0
	v_add_f32_e32 v0, 1.0, v0
	v_rcp_f32_e32 v0, v0
	s_nop 0
	v_mul_f32_e32 v0, 0xbf1b4598, v0
	v_mul_f32_e32 v0, 0x3fb8aa3b, v0
	v_exp_f32_e32 v5, v0
	global_store_dwordx4 v[38:39], v[2:5], off offset:128
	s_nop 2
	v_mov_b32_e32 v6, v108
	v_mov_b32_e32 v7, v109
	v_mov_b32_e32 v8, v110
	v_mov_b32_e32 v9, v111
	ds_read_b128 v[2:5], v62 offset:8064
	s_waitcnt lgkmcnt(0)
	v_add_f32_e32 v0, v2, v6
	v_mul_f32_e32 v0, 0xbfb8aa3b, v0
	v_exp_f32_e32 v0, v0
	s_nop 0
	v_add_f32_e32 v0, 1.0, v0
	v_rcp_f32_e32 v0, v0
	s_nop 0
	v_mul_f32_e32 v0, 0xbf1b4598, v0
	v_mul_f32_e32 v0, 0x3fb8aa3b, v0
	v_exp_f32_e32 v2, v0
	v_add_f32_e32 v0, v3, v7
	v_mul_f32_e32 v0, 0xbfb8aa3b, v0
	v_exp_f32_e32 v0, v0
	s_nop 0
	v_add_f32_e32 v0, 1.0, v0
	v_rcp_f32_e32 v0, v0
	s_nop 0
	v_mul_f32_e32 v0, 0xbf1b4598, v0
	v_mul_f32_e32 v0, 0x3fb8aa3b, v0
	v_exp_f32_e32 v3, v0
	v_add_f32_e32 v0, v4, v8
	v_mul_f32_e32 v0, 0xbfb8aa3b, v0
	v_exp_f32_e32 v0, v0
	s_nop 0
	v_add_f32_e32 v0, 1.0, v0
	v_rcp_f32_e32 v0, v0
	s_nop 0
	v_mul_f32_e32 v0, 0xbf1b4598, v0
	v_mul_f32_e32 v0, 0x3fb8aa3b, v0
	v_exp_f32_e32 v4, v0
	v_add_f32_e32 v0, v5, v9
	v_mul_f32_e32 v0, 0xbfb8aa3b, v0
	v_exp_f32_e32 v0, v0
	s_nop 0
	v_add_f32_e32 v0, 1.0, v0
	v_rcp_f32_e32 v0, v0
	s_nop 0
	v_mul_f32_e32 v0, 0xbf1b4598, v0
	v_mul_f32_e32 v0, 0x3fb8aa3b, v0
	v_exp_f32_e32 v5, v0
	global_store_dwordx4 v[34:35], v[2:5], off offset:128
	s_cbranch_scc0 .LBB0_297

.LBB0_300:
	s_and_b32 s9, s8, 1
	s_ashr_i32 s2, s8, 1
	s_lshl_b32 s3, s9, 14
	s_add_u32 s12, s6, s3
	v_mov_b32_e32 v66, v131
	v_mov_b32_e32 v67, v131
	s_addc_u32 s13, s7, 0
	s_ashr_i32 s3, s2, 31
	s_waitcnt vmcnt(10)
	v_mov_b32_e32 v6, v131
	s_lshl_b64 s[14:15], s[2:3], 15
	s_add_u32 s14, s44, s14
	v_ashrrev_i32_e32 v2, 3, v6
	v_lshrrev_b32_e32 v0, 4, v6
	v_xor_b32_e32 v0, v0, v6
	v_ashrrev_i32_e32 v3, 31, v2
	s_addc_u32 s15, s45, s15
	v_lshlrev_b64 v[4:5], 7, v[2:3]
	v_lshlrev_b32_e32 v0, 4, v0
	v_lshlrev_b64 v[2:3], 8, v[2:3]
	v_lshl_add_u64 v[4:5], s[12:13], 0, v[4:5]
	v_and_b32_e32 v0, 0x70, v0
	v_lshl_add_u64 v[2:3], s[14:15], 0, v[2:3]
	s_waitcnt vmcnt(9)
	v_lshlrev_b32_e32 v12, 4, v6
	v_and_b32_e32 v7, 31, v6
	v_lshl_add_u64 v[4:5], v[4:5], 0, v[0:1]
	v_lshl_add_u64 v[2:3], v[2:3], 0, v[0:1]
	v_lshrrev_b32_e32 v0, 1, v6
	v_readfirstlane_b32 s3, v12
	v_add_u32_e32 v13, 0x1000, v12
	v_and_or_b32 v0, v0, s16, v7
	v_lshlrev_b32_e32 v7, 7, v6
	s_mov_b32 m0, s3
	v_readfirstlane_b32 s3, v13
	v_add_u32_e32 v13, 0x2000, v12
	v_lshrrev_b32_e32 v8, 5, v6
	v_bfe_u32 v9, v6, 5, 1
	v_bfe_u32 v10, v6, 1, 3
	v_and_b32_e32 v11, 0x2f80, v7
	global_load_lds_dwordx4 v[4:5], off
	v_lshl_add_u64 v[6:7], v[4:5], 0, s[70:71]
	s_mov_b32 m0, s3
	v_readfirstlane_b32 s3, v13
	global_load_lds_dwordx4 v[6:7], off
	v_lshl_add_u64 v[6:7], v[4:5], 0, s[52:53]
	s_mov_b32 m0, s3
	v_lshl_add_u64 v[4:5], v[4:5], 0, s[60:61]
	global_load_lds_dwordx4 v[6:7], off
	v_add_u32_e32 v6, 0x3000, v12
	v_lshlrev_b32_e32 v0, 7, v0
	v_readfirstlane_b32 s3, v6
	s_mov_b32 m0, s3
	v_add_u32_e32 v6, 0x5000, v12
	global_load_lds_dwordx4 v[4:5], off
	v_add_u32_e32 v4, 0x4000, v12
	v_lshrrev_b32_e32 v100, 6, v67
	v_readfirstlane_b32 s3, v4
	s_mov_b32 m0, s3
	v_readfirstlane_b32 s3, v6
	v_add_u32_e32 v6, 0x6000, v12
	global_load_lds_dwordx4 v[2:3], off
	v_lshl_add_u64 v[4:5], v[2:3], 0, s[52:53]
	s_mov_b32 m0, s3
	v_readfirstlane_b32 s3, v6
	global_load_lds_dwordx4 v[4:5], off
	v_lshl_add_u64 v[4:5], v[2:3], 0, s[20:21]
	s_mov_b32 m0, s3
	v_lshl_add_u64 v[2:3], v[2:3], 0, s[56:57]
	global_load_lds_dwordx4 v[4:5], off
	v_add_u32_e32 v4, 0x7000, v12
	v_and_b32_e32 v101, 31, v66
	v_readfirstlane_b32 s3, v4
	s_mov_b32 m0, s3
	s_lshl_b32 s2, s2, 7
	global_load_lds_dwordx4 v[2:3], off
	v_bitop3_b32 v2, v8, v10, 1 bitop3:0x6c
	v_lshlrev_b32_e32 v2, 4, v2
	v_or_b32_e32 v6, v2, v0
	s_waitcnt vmcnt(0)
	v_or_b32_e32 v14, v2, v11
	v_bitop3_b32 v2, v9, v10, 2 bitop3:0x36
	v_lshlrev_b32_e32 v2, 4, v2
	v_or_b32_e32 v18, v2, v0
	v_or_b32_e32 v19, v2, v11
	v_bitop3_b32 v2, v9, v10, 4 bitop3:0x36
	v_lshlrev_b32_e32 v2, 4, v2
	v_or_b32_e32 v88, v2, v0
	v_or_b32_e32 v96, v2, v11
	v_bitop3_b32 v2, v9, v10, 6 bitop3:0x36
	v_lshlrev_b32_e32 v2, 4, v2
	s_waitcnt vmcnt(0)
	s_waitcnt lgkmcnt(0)
	s_barrier
	v_or_b32_e32 v0, v2, v0
	v_or_b32_e32 v102, v2, v11
	ds_read_b128 v[2:5], v6 offset:0
	ds_read_b128 v[6:9], v6 offset:0x1000
	ds_read_b128 v[10:13], v14 offset:0x4000
	ds_read_b128 v[14:17], v14 offset:0x5000
	ds_read_b128 v[68:71], v18 offset:0
	ds_read_b128 v[72:75], v18 offset:0x1000
	ds_read_b128 v[76:79], v19 offset:0x4000
	ds_read_b128 v[80:83], v19 offset:0x5000
	s_add_i32 s8, s8, s76
	s_waitcnt lgkmcnt(4)
	ds_read_b128 v[84:87], v88 offset:0
	ds_read_b128 v[88:91], v88 offset:0x1000
	ds_read_b128 v[92:95], v96 offset:0x4000
	ds_read_b128 v[96:99], v96 offset:0x5000
	s_waitcnt lgkmcnt(4)
	s_nop 0
	v_mfma_f32_32x32x16_f16 v[50:65], v[2:5], v[10:13], 0
	s_cmpk_gt_i32 s8, 0xbf
	v_mfma_f32_32x32x16_f16 v[34:49], v[2:5], v[14:17], 0
	v_mfma_f32_32x32x16_f16 v[18:33], v[6:9], v[10:13], 0
	v_mfma_f32_32x32x16_f16 v[2:17], v[6:9], v[14:17], 0
	v_mfma_f32_32x32x16_f16 v[18:33], v[72:75], v[76:79], v[18:33]
	v_mfma_f32_32x32x16_f16 v[2:17], v[72:75], v[80:83], v[2:17]
	v_mfma_f32_32x32x16_f16 v[50:65], v[68:71], v[76:79], v[50:65]
	v_mfma_f32_32x32x16_f16 v[34:49], v[68:71], v[80:83], v[34:49]
	ds_read_b128 v[68:71], v0 offset:0
	ds_read_b128 v[72:75], v0 offset:0x1000
	ds_read_b128 v[76:79], v102 offset:0x4000
	ds_read_b128 v[80:83], v102 offset:0x5000
	s_waitcnt lgkmcnt(4)
	v_mul_lo_u32 v0, v100, s66
	s_waitcnt lgkmcnt(0)
	v_mfma_f32_32x32x16_f16 v[18:33], v[88:91], v[92:95], v[18:33]
	s_waitcnt vmcnt(0)
	s_barrier
	v_mfma_f32_32x32x16_f16 v[2:17], v[88:91], v[96:99], v[2:17]
	v_mfma_f32_32x32x16_f16 v[50:65], v[84:87], v[92:95], v[50:65]
	v_mfma_f32_32x32x16_f16 v[34:49], v[84:87], v[96:99], v[34:49]
	v_mfma_f32_32x32x16_f16 v[18:33], v[72:75], v[76:79], v[18:33]
	v_mfma_f32_32x32x16_f16 v[2:17], v[72:75], v[80:83], v[2:17]
	v_add_u32_e32 v72, 0xa000, v0
	v_lshrrev_b32_e32 v0, 1, v66
	v_and_b32_e32 v74, 16, v0
	v_ashrrev_i32_e32 v0, 1, v67
	v_and_b32_e32 v0, 0xffffffc0, v0
	v_mul_u32_u24_e32 v73, 0x90, v101
	v_lshl_add_u32 v101, s9, 7, v0
	v_mfma_f32_32x32x16_f16 v[50:65], v[68:71], v[76:79], v[50:65]
	v_bfe_u32 v78, v66, 3, 3
	v_and_b32_e32 v0, 7, v66
	v_lshrrev_b32_e32 v66, 6, v101
	v_mul_lo_u32 v66, v66, s4
	v_and_or_b32 v79, v67, 64, s2
	v_ashrrev_i32_e32 v67, 31, v66
	v_lshlrev_b64 v[66:67], 2, v[66:67]
	v_mfma_f32_32x32x16_f16 v[34:49], v[68:71], v[80:83], v[34:49]
	s_nop 15
	s_nop 15
	v_readlane_b32 s12, v224, 34
	v_readlane_b32 s13, v224, 35
	s_sub_i32 s9, s8, s76
	s_and_b32 s2, s9, 1
	s_lshr_b32 s9, s9, 1
	s_load_dwordx2 s[14:15], s[12:13], 0x88
	v_and_b32_e32 v69, 7, v131
	v_bfe_u32 v68, v131, 3, 3
	v_lshrrev_b32_e32 v70, 6, v131
	v_mul_u32_u24_e32 v0, 0x2400, v70
	v_add_u32_e32 v0, 0xa000, v0
	v_and_b32_e32 v66, 31, v131
	v_mul_u32_u24_e32 v66, 0x90, v66
	v_bfe_u32 v67, v131, 5, 1
	v_lshl_add_u32 v66, v67, 4, v66
	v_add_u32_e32 v66, v66, v0
	v_mul_u32_u24_e32 v67, 0x90, v68
	v_lshl_add_u32 v67, v69, 4, v67
	v_add_u32_e32 v67, v67, v0
	v_lshrrev_b32_e32 v0, 1, v70
	v_and_b32_e32 v70, 1, v70
	s_lshl_b32 s3, s9, 7
	v_lshl_add_u32 v71, v70, 6, v68
	v_add_u32_e32 v71, s3, v71
	s_lshl_b32 s3, s2, 7
	v_lshl_add_u32 v70, v0, 6, s3
	v_lshl_add_u32 v70, v69, 2, v70
	v_lshlrev_b32_e32 v70, 2, v70
	s_lshl_b32 s3, s2, 1
	v_add_u32_e32 v0, s3, v0
	v_mul_u32_u24_e32 v0, 0xc0, v0
	v_lshl_add_u32 v69, v69, 2, v0
	v_lshlrev_b32_e32 v69, 2, v69
	s_lshl_b32 s3, s38, 1
	s_add_i32 s3, s3, 0
	s_lshl_b32 s3, s3, 10
	s_waitcnt lgkmcnt(0)
	s_add_u32 s14, s14, s3
	s_addc_u32 s15, s15, 0
	s_load_dwordx2 s[2:3], s[12:13], 0xa8
	global_load_dwordx4 v[72:75], v70, s[14:15]
	s_lshl_b32 s9, s38, 10
	s_waitcnt lgkmcnt(0)
	s_add_u32 s2, s2, s9
	s_addc_u32 s3, s3, 0
	global_load_dwordx4 v[76:79], v70, s[2:3]
	s_waitcnt vmcnt(0)
	s_load_dwordx2 s[14:15], s[12:13], 0x1d8
	s_load_dwordx2 s[2:3], s[12:13], 0x1c8
	s_load_dwordx2 s[12:13], s[12:13], 0x1d0
	s_waitcnt lgkmcnt(0)
	ds_write_b128 v66, v[50:53] offset:0
	ds_write_b128 v66, v[54:57] offset:32
	ds_write_b128 v66, v[58:61] offset:64
	ds_write_b128 v66, v[62:65] offset:96
	ds_read_b128 v[80:83], v67 offset:0
	ds_read_b128 v[84:87], v67 offset:1152
	ds_read_b128 v[88:91], v67 offset:2304
	ds_read_b128 v[92:95], v67 offset:3456
	v_add_u32_e32 v0, 0, v71
	v_mul_u32_u24_e32 v128, 0xc00, v0
	v_add_u32_e32 v128, v128, v69
	global_load_dwordx4 v[96:99], v128, s[12:13] offset:0
	v_lshl_add_u32 v129, v0, 10, v70
	global_load_dwordx4 v[112:115], v129, s[14:15] offset:0
	v_add_u32_e32 v0, 8, v71
	v_mul_u32_u24_e32 v128, 0xc00, v0
	v_add_u32_e32 v128, v128, v69
	global_load_dwordx4 v[100:103], v128, s[12:13] offset:0
	v_lshl_add_u32 v129, v0, 10, v70
	global_load_dwordx4 v[116:119], v129, s[14:15] offset:0
	v_add_u32_e32 v0, 16, v71
	v_mul_u32_u24_e32 v128, 0xc00, v0
	v_add_u32_e32 v128, v128, v69
	global_load_dwordx4 v[104:107], v128, s[12:13] offset:0
	v_lshl_add_u32 v129, v0, 10, v70
	global_load_dwordx4 v[120:123], v129, s[14:15] offset:0
	v_add_u32_e32 v0, 24, v71
	v_mul_u32_u24_e32 v128, 0xc00, v0
	v_add_u32_e32 v128, v128, v69
	global_load_dwordx4 v[108:111], v128, s[12:13] offset:0
	v_lshl_add_u32 v129, v0, 10, v70
	global_load_dwordx4 v[124:127], v129, s[14:15] offset:0
	s_waitcnt vmcnt(0) lgkmcnt(0)
	v_add_f32_e32 v80, v80, v72
	v_mul_f32_e32 v80, 0xbfb8aa3b, v80
	v_exp_f32_e32 v80, v80
	s_nop 0
	v_add_f32_e32 v80, 1.0, v80
	v_rcp_f32_e32 v80, v80
	s_nop 0
	v_xor_b32_e32 v128, 0x80000000, v80
	v_mul_f32_e32 v96, v96, v128
	v_add_f32_e32 v80, -1.0, v80
	v_fma_f32 v80, v76, v80, 1.0
	v_mul_f32_e32 v112, v112, v80
	v_add_f32_e32 v81, v81, v73
	v_mul_f32_e32 v81, 0xbfb8aa3b, v81
	v_exp_f32_e32 v81, v81
	s_nop 0
	v_add_f32_e32 v81, 1.0, v81
	v_rcp_f32_e32 v81, v81
	s_nop 0
	v_xor_b32_e32 v128, 0x80000000, v81
	v_mul_f32_e32 v97, v97, v128
	v_add_f32_e32 v81, -1.0, v81
	v_fma_f32 v81, v77, v81, 1.0
	v_mul_f32_e32 v113, v113, v81
	v_add_f32_e32 v82, v82, v74
	v_mul_f32_e32 v82, 0xbfb8aa3b, v82
	v_exp_f32_e32 v82, v82
	s_nop 0
	v_add_f32_e32 v82, 1.0, v82
	v_rcp_f32_e32 v82, v82
	s_nop 0
	v_xor_b32_e32 v128, 0x80000000, v82
	v_mul_f32_e32 v98, v98, v128
	v_add_f32_e32 v82, -1.0, v82
	v_fma_f32 v82, v78, v82, 1.0
	v_mul_f32_e32 v114, v114, v82
	v_add_f32_e32 v83, v83, v75
	v_mul_f32_e32 v83, 0xbfb8aa3b, v83
	v_exp_f32_e32 v83, v83
	s_nop 0
	v_add_f32_e32 v83, 1.0, v83
	v_rcp_f32_e32 v83, v83
	s_nop 0
	v_xor_b32_e32 v128, 0x80000000, v83
	v_mul_f32_e32 v99, v99, v128
	v_add_f32_e32 v83, -1.0, v83
	v_fma_f32 v83, v79, v83, 1.0
	v_mul_f32_e32 v115, v115, v83
	v_add_f32_e32 v84, v84, v72
	v_mul_f32_e32 v84, 0xbfb8aa3b, v84
	v_exp_f32_e32 v84, v84
	s_nop 0
	v_add_f32_e32 v84, 1.0, v84
	v_rcp_f32_e32 v84, v84
	s_nop 0
	v_xor_b32_e32 v128, 0x80000000, v84
	v_mul_f32_e32 v100, v100, v128
	v_add_f32_e32 v84, -1.0, v84
	v_fma_f32 v84, v76, v84, 1.0
	v_mul_f32_e32 v116, v116, v84
	v_add_f32_e32 v85, v85, v73
	v_mul_f32_e32 v85, 0xbfb8aa3b, v85
	v_exp_f32_e32 v85, v85
	s_nop 0
	v_add_f32_e32 v85, 1.0, v85
	v_rcp_f32_e32 v85, v85
	s_nop 0
	v_xor_b32_e32 v128, 0x80000000, v85
	v_mul_f32_e32 v101, v101, v128
	v_add_f32_e32 v85, -1.0, v85
	v_fma_f32 v85, v77, v85, 1.0
	v_mul_f32_e32 v117, v117, v85
	v_add_f32_e32 v86, v86, v74
	v_mul_f32_e32 v86, 0xbfb8aa3b, v86
	v_exp_f32_e32 v86, v86
	s_nop 0
	v_add_f32_e32 v86, 1.0, v86
	v_rcp_f32_e32 v86, v86
	s_nop 0
	v_xor_b32_e32 v128, 0x80000000, v86
	v_mul_f32_e32 v102, v102, v128
	v_add_f32_e32 v86, -1.0, v86
	v_fma_f32 v86, v78, v86, 1.0
	v_mul_f32_e32 v118, v118, v86
	v_add_f32_e32 v87, v87, v75
	v_mul_f32_e32 v87, 0xbfb8aa3b, v87
	v_exp_f32_e32 v87, v87
	s_nop 0
	v_add_f32_e32 v87, 1.0, v87
	v_rcp_f32_e32 v87, v87
	s_nop 0
	v_xor_b32_e32 v128, 0x80000000, v87
	v_mul_f32_e32 v103, v103, v128
	v_add_f32_e32 v87, -1.0, v87
	v_fma_f32 v87, v79, v87, 1.0
	v_mul_f32_e32 v119, v119, v87
	v_add_f32_e32 v88, v88, v72
	v_mul_f32_e32 v88, 0xbfb8aa3b, v88
	v_exp_f32_e32 v88, v88
	s_nop 0
	v_add_f32_e32 v88, 1.0, v88
	v_rcp_f32_e32 v88, v88
	s_nop 0
	v_xor_b32_e32 v128, 0x80000000, v88
	v_mul_f32_e32 v104, v104, v128
	v_add_f32_e32 v88, -1.0, v88
	v_fma_f32 v88, v76, v88, 1.0
	v_mul_f32_e32 v120, v120, v88
	v_add_f32_e32 v89, v89, v73
	v_mul_f32_e32 v89, 0xbfb8aa3b, v89
	v_exp_f32_e32 v89, v89
	s_nop 0
	v_add_f32_e32 v89, 1.0, v89
	v_rcp_f32_e32 v89, v89
	s_nop 0
	v_xor_b32_e32 v128, 0x80000000, v89
	v_mul_f32_e32 v105, v105, v128
	v_add_f32_e32 v89, -1.0, v89
	v_fma_f32 v89, v77, v89, 1.0
	v_mul_f32_e32 v121, v121, v89
	v_add_f32_e32 v90, v90, v74
	v_mul_f32_e32 v90, 0xbfb8aa3b, v90
	v_exp_f32_e32 v90, v90
	s_nop 0
	v_add_f32_e32 v90, 1.0, v90
	v_rcp_f32_e32 v90, v90
	s_nop 0
	v_xor_b32_e32 v128, 0x80000000, v90
	v_mul_f32_e32 v106, v106, v128
	v_add_f32_e32 v90, -1.0, v90
	v_fma_f32 v90, v78, v90, 1.0
	v_mul_f32_e32 v122, v122, v90
	v_add_f32_e32 v91, v91, v75
	v_mul_f32_e32 v91, 0xbfb8aa3b, v91
	v_exp_f32_e32 v91, v91
	s_nop 0
	v_add_f32_e32 v91, 1.0, v91
	v_rcp_f32_e32 v91, v91
	s_nop 0
	v_xor_b32_e32 v128, 0x80000000, v91
	v_mul_f32_e32 v107, v107, v128
	v_add_f32_e32 v91, -1.0, v91
	v_fma_f32 v91, v79, v91, 1.0
	v_mul_f32_e32 v123, v123, v91
	v_add_f32_e32 v92, v92, v72
	v_mul_f32_e32 v92, 0xbfb8aa3b, v92
	v_exp_f32_e32 v92, v92
	s_nop 0
	v_add_f32_e32 v92, 1.0, v92
	v_rcp_f32_e32 v92, v92
	s_nop 0
	v_xor_b32_e32 v128, 0x80000000, v92
	v_mul_f32_e32 v108, v108, v128
	v_add_f32_e32 v92, -1.0, v92
	v_fma_f32 v92, v76, v92, 1.0
	v_mul_f32_e32 v124, v124, v92
	v_add_f32_e32 v93, v93, v73
	v_mul_f32_e32 v93, 0xbfb8aa3b, v93
	v_exp_f32_e32 v93, v93
	s_nop 0
	v_add_f32_e32 v93, 1.0, v93
	v_rcp_f32_e32 v93, v93
	s_nop 0
	v_xor_b32_e32 v128, 0x80000000, v93
	v_mul_f32_e32 v109, v109, v128
	v_add_f32_e32 v93, -1.0, v93
	v_fma_f32 v93, v77, v93, 1.0
	v_mul_f32_e32 v125, v125, v93
	v_add_f32_e32 v94, v94, v74
	v_mul_f32_e32 v94, 0xbfb8aa3b, v94
	v_exp_f32_e32 v94, v94
	s_nop 0
	v_add_f32_e32 v94, 1.0, v94
	v_rcp_f32_e32 v94, v94
	s_nop 0
	v_xor_b32_e32 v128, 0x80000000, v94
	v_mul_f32_e32 v110, v110, v128
	v_add_f32_e32 v94, -1.0, v94
	v_fma_f32 v94, v78, v94, 1.0
	v_mul_f32_e32 v126, v126, v94
	v_add_f32_e32 v95, v95, v75
	v_mul_f32_e32 v95, 0xbfb8aa3b, v95
	v_exp_f32_e32 v95, v95
	s_nop 0
	v_add_f32_e32 v95, 1.0, v95
	v_rcp_f32_e32 v95, v95
	s_nop 0
	v_xor_b32_e32 v128, 0x80000000, v95
	v_mul_f32_e32 v111, v111, v128
	v_add_f32_e32 v95, -1.0, v95
	v_fma_f32 v95, v79, v95, 1.0
	v_mul_f32_e32 v127, v127, v95
	v_add_u32_e32 v0, 0, v71
	v_mul_u32_u24_e32 v128, 0xc00, v0
	v_add_u32_e32 v128, v128, v69
	global_store_dwordx4 v128, v[96:99], s[2:3] offset:256
	global_store_dwordx4 v128, v[112:115], s[2:3] offset:512
	v_add_u32_e32 v0, 8, v71
	v_mul_u32_u24_e32 v128, 0xc00, v0
	v_add_u32_e32 v128, v128, v69
	global_store_dwordx4 v128, v[100:103], s[2:3] offset:256
	global_store_dwordx4 v128, v[116:119], s[2:3] offset:512
	v_add_u32_e32 v0, 16, v71
	v_mul_u32_u24_e32 v128, 0xc00, v0
	v_add_u32_e32 v128, v128, v69
	global_store_dwordx4 v128, v[104:107], s[2:3] offset:256
	global_store_dwordx4 v128, v[120:123], s[2:3] offset:512
	v_add_u32_e32 v0, 24, v71
	v_mul_u32_u24_e32 v128, 0xc00, v0
	v_add_u32_e32 v128, v128, v69
	global_store_dwordx4 v128, v[108:111], s[2:3] offset:256
	global_store_dwordx4 v128, v[124:127], s[2:3] offset:512
	ds_write_b128 v66, v[34:37] offset:4608
	ds_write_b128 v66, v[38:41] offset:4640
	ds_write_b128 v66, v[42:45] offset:4672
	ds_write_b128 v66, v[46:49] offset:4704
	ds_read_b128 v[80:83], v67 offset:4608
	ds_read_b128 v[84:87], v67 offset:5760
	ds_read_b128 v[88:91], v67 offset:6912
	ds_read_b128 v[92:95], v67 offset:8064
	v_add_u32_e32 v0, 32, v71
	v_mul_u32_u24_e32 v128, 0xc00, v0
	v_add_u32_e32 v128, v128, v69
	global_load_dwordx4 v[96:99], v128, s[12:13] offset:0
	v_lshl_add_u32 v129, v0, 10, v70
	global_load_dwordx4 v[112:115], v129, s[14:15] offset:0
	v_add_u32_e32 v0, 40, v71
	v_mul_u32_u24_e32 v128, 0xc00, v0
	v_add_u32_e32 v128, v128, v69
	global_load_dwordx4 v[100:103], v128, s[12:13] offset:0
	v_lshl_add_u32 v129, v0, 10, v70
	global_load_dwordx4 v[116:119], v129, s[14:15] offset:0
	v_add_u32_e32 v0, 48, v71
	v_mul_u32_u24_e32 v128, 0xc00, v0
	v_add_u32_e32 v128, v128, v69
	global_load_dwordx4 v[104:107], v128, s[12:13] offset:0
	v_lshl_add_u32 v129, v0, 10, v70
	global_load_dwordx4 v[120:123], v129, s[14:15] offset:0
	v_add_u32_e32 v0, 56, v71
	v_mul_u32_u24_e32 v128, 0xc00, v0
	v_add_u32_e32 v128, v128, v69
	global_load_dwordx4 v[108:111], v128, s[12:13] offset:0
	v_lshl_add_u32 v129, v0, 10, v70
	global_load_dwordx4 v[124:127], v129, s[14:15] offset:0
	s_waitcnt vmcnt(0) lgkmcnt(0)
	v_add_f32_e32 v80, v80, v72
	v_mul_f32_e32 v80, 0xbfb8aa3b, v80
	v_exp_f32_e32 v80, v80
	s_nop 0
	v_add_f32_e32 v80, 1.0, v80
	v_rcp_f32_e32 v80, v80
	s_nop 0
	v_xor_b32_e32 v128, 0x80000000, v80
	v_mul_f32_e32 v96, v96, v128
	v_add_f32_e32 v80, -1.0, v80
	v_fma_f32 v80, v76, v80, 1.0
	v_mul_f32_e32 v112, v112, v80
	v_add_f32_e32 v81, v81, v73
	v_mul_f32_e32 v81, 0xbfb8aa3b, v81
	v_exp_f32_e32 v81, v81
	s_nop 0
	v_add_f32_e32 v81, 1.0, v81
	v_rcp_f32_e32 v81, v81
	s_nop 0
	v_xor_b32_e32 v128, 0x80000000, v81
	v_mul_f32_e32 v97, v97, v128
	v_add_f32_e32 v81, -1.0, v81
	v_fma_f32 v81, v77, v81, 1.0
	v_mul_f32_e32 v113, v113, v81
	v_add_f32_e32 v82, v82, v74
	v_mul_f32_e32 v82, 0xbfb8aa3b, v82
	v_exp_f32_e32 v82, v82
	s_nop 0
	v_add_f32_e32 v82, 1.0, v82
	v_rcp_f32_e32 v82, v82
	s_nop 0
	v_xor_b32_e32 v128, 0x80000000, v82
	v_mul_f32_e32 v98, v98, v128
	v_add_f32_e32 v82, -1.0, v82
	v_fma_f32 v82, v78, v82, 1.0
	v_mul_f32_e32 v114, v114, v82
	v_add_f32_e32 v83, v83, v75
	v_mul_f32_e32 v83, 0xbfb8aa3b, v83
	v_exp_f32_e32 v83, v83
	s_nop 0
	v_add_f32_e32 v83, 1.0, v83
	v_rcp_f32_e32 v83, v83
	s_nop 0
	v_xor_b32_e32 v128, 0x80000000, v83
	v_mul_f32_e32 v99, v99, v128
	v_add_f32_e32 v83, -1.0, v83
	v_fma_f32 v83, v79, v83, 1.0
	v_mul_f32_e32 v115, v115, v83
	v_add_f32_e32 v84, v84, v72
	v_mul_f32_e32 v84, 0xbfb8aa3b, v84
	v_exp_f32_e32 v84, v84
	s_nop 0
	v_add_f32_e32 v84, 1.0, v84
	v_rcp_f32_e32 v84, v84
	s_nop 0
	v_xor_b32_e32 v128, 0x80000000, v84
	v_mul_f32_e32 v100, v100, v128
	v_add_f32_e32 v84, -1.0, v84
	v_fma_f32 v84, v76, v84, 1.0
	v_mul_f32_e32 v116, v116, v84
	v_add_f32_e32 v85, v85, v73
	v_mul_f32_e32 v85, 0xbfb8aa3b, v85
	v_exp_f32_e32 v85, v85
	s_nop 0
	v_add_f32_e32 v85, 1.0, v85
	v_rcp_f32_e32 v85, v85
	s_nop 0
	v_xor_b32_e32 v128, 0x80000000, v85
	v_mul_f32_e32 v101, v101, v128
	v_add_f32_e32 v85, -1.0, v85
	v_fma_f32 v85, v77, v85, 1.0
	v_mul_f32_e32 v117, v117, v85
	v_add_f32_e32 v86, v86, v74
	v_mul_f32_e32 v86, 0xbfb8aa3b, v86
	v_exp_f32_e32 v86, v86
	s_nop 0
	v_add_f32_e32 v86, 1.0, v86
	v_rcp_f32_e32 v86, v86
	s_nop 0
	v_xor_b32_e32 v128, 0x80000000, v86
	v_mul_f32_e32 v102, v102, v128
	v_add_f32_e32 v86, -1.0, v86
	v_fma_f32 v86, v78, v86, 1.0
	v_mul_f32_e32 v118, v118, v86
	v_add_f32_e32 v87, v87, v75
	v_mul_f32_e32 v87, 0xbfb8aa3b, v87
	v_exp_f32_e32 v87, v87
	s_nop 0
	v_add_f32_e32 v87, 1.0, v87
	v_rcp_f32_e32 v87, v87
	s_nop 0
	v_xor_b32_e32 v128, 0x80000000, v87
	v_mul_f32_e32 v103, v103, v128
	v_add_f32_e32 v87, -1.0, v87
	v_fma_f32 v87, v79, v87, 1.0
	v_mul_f32_e32 v119, v119, v87
	v_add_f32_e32 v88, v88, v72
	v_mul_f32_e32 v88, 0xbfb8aa3b, v88
	v_exp_f32_e32 v88, v88
	s_nop 0
	v_add_f32_e32 v88, 1.0, v88
	v_rcp_f32_e32 v88, v88
	s_nop 0
	v_xor_b32_e32 v128, 0x80000000, v88
	v_mul_f32_e32 v104, v104, v128
	v_add_f32_e32 v88, -1.0, v88
	v_fma_f32 v88, v76, v88, 1.0
	v_mul_f32_e32 v120, v120, v88
	v_add_f32_e32 v89, v89, v73
	v_mul_f32_e32 v89, 0xbfb8aa3b, v89
	v_exp_f32_e32 v89, v89
	s_nop 0
	v_add_f32_e32 v89, 1.0, v89
	v_rcp_f32_e32 v89, v89
	s_nop 0
	v_xor_b32_e32 v128, 0x80000000, v89
	v_mul_f32_e32 v105, v105, v128
	v_add_f32_e32 v89, -1.0, v89
	v_fma_f32 v89, v77, v89, 1.0
	v_mul_f32_e32 v121, v121, v89
	v_add_f32_e32 v90, v90, v74
	v_mul_f32_e32 v90, 0xbfb8aa3b, v90
	v_exp_f32_e32 v90, v90
	s_nop 0
	v_add_f32_e32 v90, 1.0, v90
	v_rcp_f32_e32 v90, v90
	s_nop 0
	v_xor_b32_e32 v128, 0x80000000, v90
	v_mul_f32_e32 v106, v106, v128
	v_add_f32_e32 v90, -1.0, v90
	v_fma_f32 v90, v78, v90, 1.0
	v_mul_f32_e32 v122, v122, v90
	v_add_f32_e32 v91, v91, v75
	v_mul_f32_e32 v91, 0xbfb8aa3b, v91
	v_exp_f32_e32 v91, v91
	s_nop 0
	v_add_f32_e32 v91, 1.0, v91
	v_rcp_f32_e32 v91, v91
	s_nop 0
	v_xor_b32_e32 v128, 0x80000000, v91
	v_mul_f32_e32 v107, v107, v128
	v_add_f32_e32 v91, -1.0, v91
	v_fma_f32 v91, v79, v91, 1.0
	v_mul_f32_e32 v123, v123, v91
	v_add_f32_e32 v92, v92, v72
	v_mul_f32_e32 v92, 0xbfb8aa3b, v92
	v_exp_f32_e32 v92, v92
	s_nop 0
	v_add_f32_e32 v92, 1.0, v92
	v_rcp_f32_e32 v92, v92
	s_nop 0
	v_xor_b32_e32 v128, 0x80000000, v92
	v_mul_f32_e32 v108, v108, v128
	v_add_f32_e32 v92, -1.0, v92
	v_fma_f32 v92, v76, v92, 1.0
	v_mul_f32_e32 v124, v124, v92
	v_add_f32_e32 v93, v93, v73
	v_mul_f32_e32 v93, 0xbfb8aa3b, v93
	v_exp_f32_e32 v93, v93
	s_nop 0
	v_add_f32_e32 v93, 1.0, v93
	v_rcp_f32_e32 v93, v93
	s_nop 0
	v_xor_b32_e32 v128, 0x80000000, v93
	v_mul_f32_e32 v109, v109, v128
	v_add_f32_e32 v93, -1.0, v93
	v_fma_f32 v93, v77, v93, 1.0
	v_mul_f32_e32 v125, v125, v93
	v_add_f32_e32 v94, v94, v74
	v_mul_f32_e32 v94, 0xbfb8aa3b, v94
	v_exp_f32_e32 v94, v94
	s_nop 0
	v_add_f32_e32 v94, 1.0, v94
	v_rcp_f32_e32 v94, v94
	s_nop 0
	v_xor_b32_e32 v128, 0x80000000, v94
	v_mul_f32_e32 v110, v110, v128
	v_add_f32_e32 v94, -1.0, v94
	v_fma_f32 v94, v78, v94, 1.0
	v_mul_f32_e32 v126, v126, v94
	v_add_f32_e32 v95, v95, v75
	v_mul_f32_e32 v95, 0xbfb8aa3b, v95
	v_exp_f32_e32 v95, v95
	s_nop 0
	v_add_f32_e32 v95, 1.0, v95
	v_rcp_f32_e32 v95, v95
	s_nop 0
	v_xor_b32_e32 v128, 0x80000000, v95
	v_mul_f32_e32 v111, v111, v128
	v_add_f32_e32 v95, -1.0, v95
	v_fma_f32 v95, v79, v95, 1.0
	v_mul_f32_e32 v127, v127, v95
	v_add_u32_e32 v0, 32, v71
	v_mul_u32_u24_e32 v128, 0xc00, v0
	v_add_u32_e32 v128, v128, v69
	global_store_dwordx4 v128, v[96:99], s[2:3] offset:256
	global_store_dwordx4 v128, v[112:115], s[2:3] offset:512
	v_add_u32_e32 v0, 40, v71
	v_mul_u32_u24_e32 v128, 0xc00, v0
	v_add_u32_e32 v128, v128, v69
	global_store_dwordx4 v128, v[100:103], s[2:3] offset:256
	global_store_dwordx4 v128, v[116:119], s[2:3] offset:512
	v_add_u32_e32 v0, 48, v71
	v_mul_u32_u24_e32 v128, 0xc00, v0
	v_add_u32_e32 v128, v128, v69
	global_store_dwordx4 v128, v[104:107], s[2:3] offset:256
	global_store_dwordx4 v128, v[120:123], s[2:3] offset:512
	v_add_u32_e32 v0, 56, v71
	v_mul_u32_u24_e32 v128, 0xc00, v0
	v_add_u32_e32 v128, v128, v69
	global_store_dwordx4 v128, v[108:111], s[2:3] offset:256
	global_store_dwordx4 v128, v[124:127], s[2:3] offset:512
	v_readlane_b32 s14, v224, 34
	v_readlane_b32 s15, v224, 35
	s_load_dwordx2 s[14:15], s[14:15], 0x88
	s_lshl_b32 s9, s38, 1
	s_add_i32 s9, s9, 0
	s_lshl_b32 s9, s9, 10
	s_waitcnt lgkmcnt(0)
	s_add_u32 s14, s14, s9
	s_addc_u32 s15, s15, 0
	global_load_dwordx4 v[72:75], v70, s[14:15] offset:128
	v_readlane_b32 s14, v224, 34
	v_readlane_b32 s15, v224, 35
	s_load_dwordx2 s[14:15], s[14:15], 0xa8
	s_lshl_b32 s9, s38, 10
	s_waitcnt lgkmcnt(0)
	s_add_u32 s14, s14, s9
	s_addc_u32 s15, s15, 0
	global_load_dwordx4 v[76:79], v70, s[14:15] offset:128
	v_readlane_b32 s14, v224, 34
	v_readlane_b32 s15, v224, 35
	s_load_dwordx2 s[14:15], s[14:15], 0x1d8
	s_waitcnt lgkmcnt(0)
	ds_write_b128 v66, v[18:21] offset:0
	ds_write_b128 v66, v[22:25] offset:32
	ds_write_b128 v66, v[26:29] offset:64
	ds_write_b128 v66, v[30:33] offset:96
	ds_read_b128 v[80:83], v67 offset:0
	ds_read_b128 v[84:87], v67 offset:1152
	ds_read_b128 v[88:91], v67 offset:2304
	ds_read_b128 v[92:95], v67 offset:3456
	v_add_u32_e32 v0, 0, v71
	v_mul_u32_u24_e32 v128, 0xc00, v0
	v_add_u32_e32 v128, v128, v69
	global_load_dwordx4 v[96:99], v128, s[12:13] offset:128
	v_lshl_add_u32 v129, v0, 10, v70
	global_load_dwordx4 v[112:115], v129, s[14:15] offset:128
	v_add_u32_e32 v0, 8, v71
	v_mul_u32_u24_e32 v128, 0xc00, v0
	v_add_u32_e32 v128, v128, v69
	global_load_dwordx4 v[100:103], v128, s[12:13] offset:128
	v_lshl_add_u32 v129, v0, 10, v70
	global_load_dwordx4 v[116:119], v129, s[14:15] offset:128
	v_add_u32_e32 v0, 16, v71
	v_mul_u32_u24_e32 v128, 0xc00, v0
	v_add_u32_e32 v128, v128, v69
	global_load_dwordx4 v[104:107], v128, s[12:13] offset:128
	v_lshl_add_u32 v129, v0, 10, v70
	global_load_dwordx4 v[120:123], v129, s[14:15] offset:128
	v_add_u32_e32 v0, 24, v71
	v_mul_u32_u24_e32 v128, 0xc00, v0
	v_add_u32_e32 v128, v128, v69
	global_load_dwordx4 v[108:111], v128, s[12:13] offset:128
	v_lshl_add_u32 v129, v0, 10, v70
	global_load_dwordx4 v[124:127], v129, s[14:15] offset:128
	s_waitcnt vmcnt(0) lgkmcnt(0)
	v_add_f32_e32 v80, v80, v72
	v_mul_f32_e32 v80, 0xbfb8aa3b, v80
	v_exp_f32_e32 v80, v80
	s_nop 0
	v_add_f32_e32 v80, 1.0, v80
	v_rcp_f32_e32 v80, v80
	s_nop 0
	v_xor_b32_e32 v128, 0x80000000, v80
	v_mul_f32_e32 v96, v96, v128
	v_add_f32_e32 v80, -1.0, v80
	v_fma_f32 v80, v76, v80, 1.0
	v_mul_f32_e32 v112, v112, v80
	v_add_f32_e32 v81, v81, v73
	v_mul_f32_e32 v81, 0xbfb8aa3b, v81
	v_exp_f32_e32 v81, v81
	s_nop 0
	v_add_f32_e32 v81, 1.0, v81
	v_rcp_f32_e32 v81, v81
	s_nop 0
	v_xor_b32_e32 v128, 0x80000000, v81
	v_mul_f32_e32 v97, v97, v128
	v_add_f32_e32 v81, -1.0, v81
	v_fma_f32 v81, v77, v81, 1.0
	v_mul_f32_e32 v113, v113, v81
	v_add_f32_e32 v82, v82, v74
	v_mul_f32_e32 v82, 0xbfb8aa3b, v82
	v_exp_f32_e32 v82, v82
	s_nop 0
	v_add_f32_e32 v82, 1.0, v82
	v_rcp_f32_e32 v82, v82
	s_nop 0
	v_xor_b32_e32 v128, 0x80000000, v82
	v_mul_f32_e32 v98, v98, v128
	v_add_f32_e32 v82, -1.0, v82
	v_fma_f32 v82, v78, v82, 1.0
	v_mul_f32_e32 v114, v114, v82
	v_add_f32_e32 v83, v83, v75
	v_mul_f32_e32 v83, 0xbfb8aa3b, v83
	v_exp_f32_e32 v83, v83
	s_nop 0
	v_add_f32_e32 v83, 1.0, v83
	v_rcp_f32_e32 v83, v83
	s_nop 0
	v_xor_b32_e32 v128, 0x80000000, v83
	v_mul_f32_e32 v99, v99, v128
	v_add_f32_e32 v83, -1.0, v83
	v_fma_f32 v83, v79, v83, 1.0
	v_mul_f32_e32 v115, v115, v83
	v_add_f32_e32 v84, v84, v72
	v_mul_f32_e32 v84, 0xbfb8aa3b, v84
	v_exp_f32_e32 v84, v84
	s_nop 0
	v_add_f32_e32 v84, 1.0, v84
	v_rcp_f32_e32 v84, v84
	s_nop 0
	v_xor_b32_e32 v128, 0x80000000, v84
	v_mul_f32_e32 v100, v100, v128
	v_add_f32_e32 v84, -1.0, v84
	v_fma_f32 v84, v76, v84, 1.0
	v_mul_f32_e32 v116, v116, v84
	v_add_f32_e32 v85, v85, v73
	v_mul_f32_e32 v85, 0xbfb8aa3b, v85
	v_exp_f32_e32 v85, v85
	s_nop 0
	v_add_f32_e32 v85, 1.0, v85
	v_rcp_f32_e32 v85, v85
	s_nop 0
	v_xor_b32_e32 v128, 0x80000000, v85
	v_mul_f32_e32 v101, v101, v128
	v_add_f32_e32 v85, -1.0, v85
	v_fma_f32 v85, v77, v85, 1.0
	v_mul_f32_e32 v117, v117, v85
	v_add_f32_e32 v86, v86, v74
	v_mul_f32_e32 v86, 0xbfb8aa3b, v86
	v_exp_f32_e32 v86, v86
	s_nop 0
	v_add_f32_e32 v86, 1.0, v86
	v_rcp_f32_e32 v86, v86
	s_nop 0
	v_xor_b32_e32 v128, 0x80000000, v86
	v_mul_f32_e32 v102, v102, v128
	v_add_f32_e32 v86, -1.0, v86
	v_fma_f32 v86, v78, v86, 1.0
	v_mul_f32_e32 v118, v118, v86
	v_add_f32_e32 v87, v87, v75
	v_mul_f32_e32 v87, 0xbfb8aa3b, v87
	v_exp_f32_e32 v87, v87
	s_nop 0
	v_add_f32_e32 v87, 1.0, v87
	v_rcp_f32_e32 v87, v87
	s_nop 0
	v_xor_b32_e32 v128, 0x80000000, v87
	v_mul_f32_e32 v103, v103, v128
	v_add_f32_e32 v87, -1.0, v87
	v_fma_f32 v87, v79, v87, 1.0
	v_mul_f32_e32 v119, v119, v87
	v_add_f32_e32 v88, v88, v72
	v_mul_f32_e32 v88, 0xbfb8aa3b, v88
	v_exp_f32_e32 v88, v88
	s_nop 0
	v_add_f32_e32 v88, 1.0, v88
	v_rcp_f32_e32 v88, v88
	s_nop 0
	v_xor_b32_e32 v128, 0x80000000, v88
	v_mul_f32_e32 v104, v104, v128
	v_add_f32_e32 v88, -1.0, v88
	v_fma_f32 v88, v76, v88, 1.0
	v_mul_f32_e32 v120, v120, v88
	v_add_f32_e32 v89, v89, v73
	v_mul_f32_e32 v89, 0xbfb8aa3b, v89
	v_exp_f32_e32 v89, v89
	s_nop 0
	v_add_f32_e32 v89, 1.0, v89
	v_rcp_f32_e32 v89, v89
	s_nop 0
	v_xor_b32_e32 v128, 0x80000000, v89
	v_mul_f32_e32 v105, v105, v128
	v_add_f32_e32 v89, -1.0, v89
	v_fma_f32 v89, v77, v89, 1.0
	v_mul_f32_e32 v121, v121, v89
	v_add_f32_e32 v90, v90, v74
	v_mul_f32_e32 v90, 0xbfb8aa3b, v90
	v_exp_f32_e32 v90, v90
	s_nop 0
	v_add_f32_e32 v90, 1.0, v90
	v_rcp_f32_e32 v90, v90
	s_nop 0
	v_xor_b32_e32 v128, 0x80000000, v90
	v_mul_f32_e32 v106, v106, v128
	v_add_f32_e32 v90, -1.0, v90
	v_fma_f32 v90, v78, v90, 1.0
	v_mul_f32_e32 v122, v122, v90
	v_add_f32_e32 v91, v91, v75
	v_mul_f32_e32 v91, 0xbfb8aa3b, v91
	v_exp_f32_e32 v91, v91
	s_nop 0
	v_add_f32_e32 v91, 1.0, v91
	v_rcp_f32_e32 v91, v91
	s_nop 0
	v_xor_b32_e32 v128, 0x80000000, v91
	v_mul_f32_e32 v107, v107, v128
	v_add_f32_e32 v91, -1.0, v91
	v_fma_f32 v91, v79, v91, 1.0
	v_mul_f32_e32 v123, v123, v91
	v_add_f32_e32 v92, v92, v72
	v_mul_f32_e32 v92, 0xbfb8aa3b, v92
	v_exp_f32_e32 v92, v92
	s_nop 0
	v_add_f32_e32 v92, 1.0, v92
	v_rcp_f32_e32 v92, v92
	s_nop 0
	v_xor_b32_e32 v128, 0x80000000, v92
	v_mul_f32_e32 v108, v108, v128
	v_add_f32_e32 v92, -1.0, v92
	v_fma_f32 v92, v76, v92, 1.0
	v_mul_f32_e32 v124, v124, v92
	v_add_f32_e32 v93, v93, v73
	v_mul_f32_e32 v93, 0xbfb8aa3b, v93
	v_exp_f32_e32 v93, v93
	s_nop 0
	v_add_f32_e32 v93, 1.0, v93
	v_rcp_f32_e32 v93, v93
	s_nop 0
	v_xor_b32_e32 v128, 0x80000000, v93
	v_mul_f32_e32 v109, v109, v128
	v_add_f32_e32 v93, -1.0, v93
	v_fma_f32 v93, v77, v93, 1.0
	v_mul_f32_e32 v125, v125, v93
	v_add_f32_e32 v94, v94, v74
	v_mul_f32_e32 v94, 0xbfb8aa3b, v94
	v_exp_f32_e32 v94, v94
	s_nop 0
	v_add_f32_e32 v94, 1.0, v94
	v_rcp_f32_e32 v94, v94
	s_nop 0
	v_xor_b32_e32 v128, 0x80000000, v94
	v_mul_f32_e32 v110, v110, v128
	v_add_f32_e32 v94, -1.0, v94
	v_fma_f32 v94, v78, v94, 1.0
	v_mul_f32_e32 v126, v126, v94
	v_add_f32_e32 v95, v95, v75
	v_mul_f32_e32 v95, 0xbfb8aa3b, v95
	v_exp_f32_e32 v95, v95
	s_nop 0
	v_add_f32_e32 v95, 1.0, v95
	v_rcp_f32_e32 v95, v95
	s_nop 0
	v_xor_b32_e32 v128, 0x80000000, v95
	v_mul_f32_e32 v111, v111, v128
	v_add_f32_e32 v95, -1.0, v95
	v_fma_f32 v95, v79, v95, 1.0
	v_mul_f32_e32 v127, v127, v95
	v_add_u32_e32 v0, 0, v71
	v_mul_u32_u24_e32 v128, 0xc00, v0
	v_add_u32_e32 v128, v128, v69
	global_store_dwordx4 v128, v[96:99], s[2:3] offset:384
	global_store_dwordx4 v128, v[112:115], s[2:3] offset:640
	v_add_u32_e32 v0, 8, v71
	v_mul_u32_u24_e32 v128, 0xc00, v0
	v_add_u32_e32 v128, v128, v69
	global_store_dwordx4 v128, v[100:103], s[2:3] offset:384
	global_store_dwordx4 v128, v[116:119], s[2:3] offset:640
	v_add_u32_e32 v0, 16, v71
	v_mul_u32_u24_e32 v128, 0xc00, v0
	v_add_u32_e32 v128, v128, v69
	global_store_dwordx4 v128, v[104:107], s[2:3] offset:384
	global_store_dwordx4 v128, v[120:123], s[2:3] offset:640
	v_add_u32_e32 v0, 24, v71
	v_mul_u32_u24_e32 v128, 0xc00, v0
	v_add_u32_e32 v128, v128, v69
	global_store_dwordx4 v128, v[108:111], s[2:3] offset:384
	global_store_dwordx4 v128, v[124:127], s[2:3] offset:640
	ds_write_b128 v66, v[2:5] offset:4608
	ds_write_b128 v66, v[6:9] offset:4640
	ds_write_b128 v66, v[10:13] offset:4672
	ds_write_b128 v66, v[14:17] offset:4704
	ds_read_b128 v[80:83], v67 offset:4608
	ds_read_b128 v[84:87], v67 offset:5760
	ds_read_b128 v[88:91], v67 offset:6912
	ds_read_b128 v[92:95], v67 offset:8064
	v_add_u32_e32 v0, 32, v71
	v_mul_u32_u24_e32 v128, 0xc00, v0
	v_add_u32_e32 v128, v128, v69
	global_load_dwordx4 v[96:99], v128, s[12:13] offset:128
	v_lshl_add_u32 v129, v0, 10, v70
	global_load_dwordx4 v[112:115], v129, s[14:15] offset:128
	v_add_u32_e32 v0, 40, v71
	v_mul_u32_u24_e32 v128, 0xc00, v0
	v_add_u32_e32 v128, v128, v69
	global_load_dwordx4 v[100:103], v128, s[12:13] offset:128
	v_lshl_add_u32 v129, v0, 10, v70
	global_load_dwordx4 v[116:119], v129, s[14:15] offset:128
	v_add_u32_e32 v0, 48, v71
	v_mul_u32_u24_e32 v128, 0xc00, v0
	v_add_u32_e32 v128, v128, v69
	global_load_dwordx4 v[104:107], v128, s[12:13] offset:128
	v_lshl_add_u32 v129, v0, 10, v70
	global_load_dwordx4 v[120:123], v129, s[14:15] offset:128
	v_add_u32_e32 v0, 56, v71
	v_mul_u32_u24_e32 v128, 0xc00, v0
	v_add_u32_e32 v128, v128, v69
	global_load_dwordx4 v[108:111], v128, s[12:13] offset:128
	v_lshl_add_u32 v129, v0, 10, v70
	global_load_dwordx4 v[124:127], v129, s[14:15] offset:128
	s_waitcnt vmcnt(0) lgkmcnt(0)
	v_add_f32_e32 v80, v80, v72
	v_mul_f32_e32 v80, 0xbfb8aa3b, v80
	v_exp_f32_e32 v80, v80
	s_nop 0
	v_add_f32_e32 v80, 1.0, v80
	v_rcp_f32_e32 v80, v80
	s_nop 0
	v_xor_b32_e32 v128, 0x80000000, v80
	v_mul_f32_e32 v96, v96, v128
	v_add_f32_e32 v80, -1.0, v80
	v_fma_f32 v80, v76, v80, 1.0
	v_mul_f32_e32 v112, v112, v80
	v_add_f32_e32 v81, v81, v73
	v_mul_f32_e32 v81, 0xbfb8aa3b, v81
	v_exp_f32_e32 v81, v81
	s_nop 0
	v_add_f32_e32 v81, 1.0, v81
	v_rcp_f32_e32 v81, v81
	s_nop 0
	v_xor_b32_e32 v128, 0x80000000, v81
	v_mul_f32_e32 v97, v97, v128
	v_add_f32_e32 v81, -1.0, v81
	v_fma_f32 v81, v77, v81, 1.0
	v_mul_f32_e32 v113, v113, v81
	v_add_f32_e32 v82, v82, v74
	v_mul_f32_e32 v82, 0xbfb8aa3b, v82
	v_exp_f32_e32 v82, v82
	s_nop 0
	v_add_f32_e32 v82, 1.0, v82
	v_rcp_f32_e32 v82, v82
	s_nop 0
	v_xor_b32_e32 v128, 0x80000000, v82
	v_mul_f32_e32 v98, v98, v128
	v_add_f32_e32 v82, -1.0, v82
	v_fma_f32 v82, v78, v82, 1.0
	v_mul_f32_e32 v114, v114, v82
	v_add_f32_e32 v83, v83, v75
	v_mul_f32_e32 v83, 0xbfb8aa3b, v83
	v_exp_f32_e32 v83, v83
	s_nop 0
	v_add_f32_e32 v83, 1.0, v83
	v_rcp_f32_e32 v83, v83
	s_nop 0
	v_xor_b32_e32 v128, 0x80000000, v83
	v_mul_f32_e32 v99, v99, v128
	v_add_f32_e32 v83, -1.0, v83
	v_fma_f32 v83, v79, v83, 1.0
	v_mul_f32_e32 v115, v115, v83
	v_add_f32_e32 v84, v84, v72
	v_mul_f32_e32 v84, 0xbfb8aa3b, v84
	v_exp_f32_e32 v84, v84
	s_nop 0
	v_add_f32_e32 v84, 1.0, v84
	v_rcp_f32_e32 v84, v84
	s_nop 0
	v_xor_b32_e32 v128, 0x80000000, v84
	v_mul_f32_e32 v100, v100, v128
	v_add_f32_e32 v84, -1.0, v84
	v_fma_f32 v84, v76, v84, 1.0
	v_mul_f32_e32 v116, v116, v84
	v_add_f32_e32 v85, v85, v73
	v_mul_f32_e32 v85, 0xbfb8aa3b, v85
	v_exp_f32_e32 v85, v85
	s_nop 0
	v_add_f32_e32 v85, 1.0, v85
	v_rcp_f32_e32 v85, v85
	s_nop 0
	v_xor_b32_e32 v128, 0x80000000, v85
	v_mul_f32_e32 v101, v101, v128
	v_add_f32_e32 v85, -1.0, v85
	v_fma_f32 v85, v77, v85, 1.0
	v_mul_f32_e32 v117, v117, v85
	v_add_f32_e32 v86, v86, v74
	v_mul_f32_e32 v86, 0xbfb8aa3b, v86
	v_exp_f32_e32 v86, v86
	s_nop 0
	v_add_f32_e32 v86, 1.0, v86
	v_rcp_f32_e32 v86, v86
	s_nop 0
	v_xor_b32_e32 v128, 0x80000000, v86
	v_mul_f32_e32 v102, v102, v128
	v_add_f32_e32 v86, -1.0, v86
	v_fma_f32 v86, v78, v86, 1.0
	v_mul_f32_e32 v118, v118, v86
	v_add_f32_e32 v87, v87, v75
	v_mul_f32_e32 v87, 0xbfb8aa3b, v87
	v_exp_f32_e32 v87, v87
	s_nop 0
	v_add_f32_e32 v87, 1.0, v87
	v_rcp_f32_e32 v87, v87
	s_nop 0
	v_xor_b32_e32 v128, 0x80000000, v87
	v_mul_f32_e32 v103, v103, v128
	v_add_f32_e32 v87, -1.0, v87
	v_fma_f32 v87, v79, v87, 1.0
	v_mul_f32_e32 v119, v119, v87
	v_add_f32_e32 v88, v88, v72
	v_mul_f32_e32 v88, 0xbfb8aa3b, v88
	v_exp_f32_e32 v88, v88
	s_nop 0
	v_add_f32_e32 v88, 1.0, v88
	v_rcp_f32_e32 v88, v88
	s_nop 0
	v_xor_b32_e32 v128, 0x80000000, v88
	v_mul_f32_e32 v104, v104, v128
	v_add_f32_e32 v88, -1.0, v88
	v_fma_f32 v88, v76, v88, 1.0
	v_mul_f32_e32 v120, v120, v88
	v_add_f32_e32 v89, v89, v73
	v_mul_f32_e32 v89, 0xbfb8aa3b, v89
	v_exp_f32_e32 v89, v89
	s_nop 0
	v_add_f32_e32 v89, 1.0, v89
	v_rcp_f32_e32 v89, v89
	s_nop 0
	v_xor_b32_e32 v128, 0x80000000, v89
	v_mul_f32_e32 v105, v105, v128
	v_add_f32_e32 v89, -1.0, v89
	v_fma_f32 v89, v77, v89, 1.0
	v_mul_f32_e32 v121, v121, v89
	v_add_f32_e32 v90, v90, v74
	v_mul_f32_e32 v90, 0xbfb8aa3b, v90
	v_exp_f32_e32 v90, v90
	s_nop 0
	v_add_f32_e32 v90, 1.0, v90
	v_rcp_f32_e32 v90, v90
	s_nop 0
	v_xor_b32_e32 v128, 0x80000000, v90
	v_mul_f32_e32 v106, v106, v128
	v_add_f32_e32 v90, -1.0, v90
	v_fma_f32 v90, v78, v90, 1.0
	v_mul_f32_e32 v122, v122, v90
	v_add_f32_e32 v91, v91, v75
	v_mul_f32_e32 v91, 0xbfb8aa3b, v91
	v_exp_f32_e32 v91, v91
	s_nop 0
	v_add_f32_e32 v91, 1.0, v91
	v_rcp_f32_e32 v91, v91
	s_nop 0
	v_xor_b32_e32 v128, 0x80000000, v91
	v_mul_f32_e32 v107, v107, v128
	v_add_f32_e32 v91, -1.0, v91
	v_fma_f32 v91, v79, v91, 1.0
	v_mul_f32_e32 v123, v123, v91
	v_add_f32_e32 v92, v92, v72
	v_mul_f32_e32 v92, 0xbfb8aa3b, v92
	v_exp_f32_e32 v92, v92
	s_nop 0
	v_add_f32_e32 v92, 1.0, v92
	v_rcp_f32_e32 v92, v92
	s_nop 0
	v_xor_b32_e32 v128, 0x80000000, v92
	v_mul_f32_e32 v108, v108, v128
	v_add_f32_e32 v92, -1.0, v92
	v_fma_f32 v92, v76, v92, 1.0
	v_mul_f32_e32 v124, v124, v92
	v_add_f32_e32 v93, v93, v73
	v_mul_f32_e32 v93, 0xbfb8aa3b, v93
	v_exp_f32_e32 v93, v93
	s_nop 0
	v_add_f32_e32 v93, 1.0, v93
	v_rcp_f32_e32 v93, v93
	s_nop 0
	v_xor_b32_e32 v128, 0x80000000, v93
	v_mul_f32_e32 v109, v109, v128
	v_add_f32_e32 v93, -1.0, v93
	v_fma_f32 v93, v77, v93, 1.0
	v_mul_f32_e32 v125, v125, v93
	v_add_f32_e32 v94, v94, v74
	v_mul_f32_e32 v94, 0xbfb8aa3b, v94
	v_exp_f32_e32 v94, v94
	s_nop 0
	v_add_f32_e32 v94, 1.0, v94
	v_rcp_f32_e32 v94, v94
	s_nop 0
	v_xor_b32_e32 v128, 0x80000000, v94
	v_mul_f32_e32 v110, v110, v128
	v_add_f32_e32 v94, -1.0, v94
	v_fma_f32 v94, v78, v94, 1.0
	v_mul_f32_e32 v126, v126, v94
	v_add_f32_e32 v95, v95, v75
	v_mul_f32_e32 v95, 0xbfb8aa3b, v95
	v_exp_f32_e32 v95, v95
	s_nop 0
	v_add_f32_e32 v95, 1.0, v95
	v_rcp_f32_e32 v95, v95
	s_nop 0
	v_xor_b32_e32 v128, 0x80000000, v95
	v_mul_f32_e32 v111, v111, v128
	v_add_f32_e32 v95, -1.0, v95
	v_fma_f32 v95, v79, v95, 1.0
	v_mul_f32_e32 v127, v127, v95
	v_add_u32_e32 v0, 32, v71
	v_mul_u32_u24_e32 v128, 0xc00, v0
	v_add_u32_e32 v128, v128, v69
	global_store_dwordx4 v128, v[96:99], s[2:3] offset:384
	global_store_dwordx4 v128, v[112:115], s[2:3] offset:640
	v_add_u32_e32 v0, 40, v71
	v_mul_u32_u24_e32 v128, 0xc00, v0
	v_add_u32_e32 v128, v128, v69
	global_store_dwordx4 v128, v[100:103], s[2:3] offset:384
	global_store_dwordx4 v128, v[116:119], s[2:3] offset:640
	v_add_u32_e32 v0, 48, v71
	v_mul_u32_u24_e32 v128, 0xc00, v0
	v_add_u32_e32 v128, v128, v69
	global_store_dwordx4 v128, v[104:107], s[2:3] offset:384
	global_store_dwordx4 v128, v[120:123], s[2:3] offset:640
	v_add_u32_e32 v0, 56, v71
	v_mul_u32_u24_e32 v128, 0xc00, v0
	v_add_u32_e32 v128, v128, v69
	global_store_dwordx4 v128, v[108:111], s[2:3] offset:384
	global_store_dwordx4 v128, v[124:127], s[2:3] offset:640
	s_cmpk_gt_i32 s8, 0xbf
	s_cbranch_scc0 .LBB0_300

.LBB0_303:
	s_and_b32 s9, s8, 1
	s_ashr_i32 s2, s8, 1
	s_lshl_b32 s3, s9, 14
	s_add_u32 s12, s6, s3
	v_mov_b32_e32 v98, v131
	v_mov_b32_e32 v99, v131
	s_addc_u32 s13, s7, 0
	s_ashr_i32 s3, s2, 31
	s_waitcnt vmcnt(10)
	v_mov_b32_e32 v8, v131
	s_lshl_b64 s[14:15], s[2:3], 15
	s_add_u32 s14, s44, s14
	v_ashrrev_i32_e32 v2, 3, v8
	v_lshrrev_b32_e32 v0, 4, v8
	v_xor_b32_e32 v0, v0, v8
	v_ashrrev_i32_e32 v3, 31, v2
	s_addc_u32 s15, s45, s15
	v_lshlrev_b64 v[4:5], 7, v[2:3]
	v_lshlrev_b32_e32 v0, 4, v0
	v_lshlrev_b64 v[2:3], 8, v[2:3]
	v_lshl_add_u64 v[4:5], s[12:13], 0, v[4:5]
	v_and_b32_e32 v0, 0x70, v0
	v_lshl_add_u64 v[2:3], s[14:15], 0, v[2:3]
	s_waitcnt vmcnt(8)
	v_lshlrev_b32_e32 v14, 4, v8
	v_and_b32_e32 v9, 31, v8
	v_lshl_add_u64 v[4:5], v[4:5], 0, v[0:1]
	v_lshl_add_u64 v[2:3], v[2:3], 0, v[0:1]
	v_lshrrev_b32_e32 v0, 1, v8
	v_readfirstlane_b32 s3, v14
	v_add_u32_e32 v15, 0x1000, v14
	v_and_or_b32 v0, v0, s16, v9
	v_lshlrev_b32_e32 v9, 7, v8
	s_mov_b32 m0, s3
	v_readfirstlane_b32 s3, v15
	v_add_u32_e32 v15, 0x2000, v14
	v_lshrrev_b32_e32 v10, 5, v8
	v_bfe_u32 v11, v8, 5, 1
	v_bfe_u32 v12, v8, 1, 3
	v_and_b32_e32 v13, 0x2f80, v9
	global_load_lds_dwordx4 v[4:5], off
	v_lshl_add_u64 v[8:9], v[4:5], 0, s[70:71]
	s_mov_b32 m0, s3
	v_readfirstlane_b32 s3, v15
	global_load_lds_dwordx4 v[8:9], off
	v_lshl_add_u64 v[8:9], v[4:5], 0, s[52:53]
	s_mov_b32 m0, s3
	v_lshl_add_u64 v[4:5], v[4:5], 0, s[60:61]
	global_load_lds_dwordx4 v[8:9], off
	v_add_u32_e32 v8, 0x3000, v14
	v_lshl_add_u64 v[6:7], v[2:3], 0, s[24:25]
	v_readfirstlane_b32 s3, v8
	s_mov_b32 m0, s3
	v_lshlrev_b32_e32 v0, 7, v0
	global_load_lds_dwordx4 v[4:5], off
	v_add_u32_e32 v4, 0x4000, v14
	v_lshrrev_b32_e32 v100, 6, v99
	v_readfirstlane_b32 s3, v4
	s_mov_b32 m0, s3
	v_lshl_add_u64 v[4:5], v[2:3], 0, s[56:57]
	global_load_lds_dwordx4 v[6:7], off
	v_add_u32_e32 v6, 0x5000, v14
	v_and_b32_e32 v101, 31, v98
	v_readfirstlane_b32 s3, v6
	v_add_u32_e32 v6, 0x6000, v14
	s_mov_b32 m0, s3
	v_readfirstlane_b32 s3, v6
	global_load_lds_dwordx4 v[4:5], off
	v_lshl_add_u64 v[4:5], v[2:3], 0, s[58:59]
	s_mov_b32 m0, s3
	v_lshl_add_u64 v[2:3], v[2:3], 0, s[72:73]
	global_load_lds_dwordx4 v[4:5], off
	v_add_u32_e32 v4, 0x7000, v14
	s_lshl_b32 s2, s2, 7
	v_readfirstlane_b32 s3, v4
	s_mov_b32 m0, s3
	s_add_i32 s8, s8, s76
	global_load_lds_dwordx4 v[2:3], off
	v_bitop3_b32 v2, v10, v12, 1 bitop3:0x6c
	v_lshlrev_b32_e32 v2, 4, v2
	v_or_b32_e32 v6, v2, v0
	v_or_b32_e32 v14, v2, v13
	v_bitop3_b32 v2, v11, v12, 2 bitop3:0x36
	v_lshlrev_b32_e32 v2, 4, v2
	s_waitcnt vmcnt(0)
	v_or_b32_e32 v18, v2, v0
	v_or_b32_e32 v19, v2, v13
	v_bitop3_b32 v2, v11, v12, 4 bitop3:0x36
	v_lshlrev_b32_e32 v2, 4, v2
	v_or_b32_e32 v86, v2, v0
	v_or_b32_e32 v94, v2, v13
	v_bitop3_b32 v2, v11, v12, 6 bitop3:0x36
	v_lshlrev_b32_e32 v2, 4, v2
	s_waitcnt vmcnt(0)
	s_waitcnt lgkmcnt(0)
	s_barrier
	v_or_b32_e32 v0, v2, v0
	v_or_b32_e32 v102, v2, v13
	ds_read_b128 v[2:5], v6 offset:0
	ds_read_b128 v[6:9], v6 offset:0x1000
	ds_read_b128 v[10:13], v14 offset:0x4000
	ds_read_b128 v[14:17], v14 offset:0x5000
	ds_read_b128 v[66:69], v18 offset:0
	ds_read_b128 v[70:73], v18 offset:0x1000
	ds_read_b128 v[74:77], v19 offset:0x4000
	ds_read_b128 v[78:81], v19 offset:0x5000
	s_cmpk_gt_i32 s8, 0xbf
	s_waitcnt lgkmcnt(4)
	ds_read_b128 v[82:85], v86 offset:0
	ds_read_b128 v[86:89], v86 offset:0x1000
	ds_read_b128 v[90:93], v94 offset:0x4000
	ds_read_b128 v[94:97], v94 offset:0x5000
	s_waitcnt lgkmcnt(4)
	s_nop 0
	v_mfma_f32_32x32x16_f16 v[50:65], v[2:5], v[10:13], 0
	v_mfma_f32_32x32x16_f16 v[34:49], v[2:5], v[14:17], 0
	v_mfma_f32_32x32x16_f16 v[18:33], v[6:9], v[10:13], 0
	v_mfma_f32_32x32x16_f16 v[2:17], v[6:9], v[14:17], 0
	v_mfma_f32_32x32x16_f16 v[18:33], v[70:73], v[74:77], v[18:33]
	v_mfma_f32_32x32x16_f16 v[2:17], v[70:73], v[78:81], v[2:17]
	v_mfma_f32_32x32x16_f16 v[50:65], v[66:69], v[74:77], v[50:65]
	v_mfma_f32_32x32x16_f16 v[34:49], v[66:69], v[78:81], v[34:49]
	ds_read_b128 v[66:69], v0 offset:0
	ds_read_b128 v[70:73], v0 offset:0x1000
	ds_read_b128 v[74:77], v102 offset:0x4000
	ds_read_b128 v[78:81], v102 offset:0x5000
	s_waitcnt lgkmcnt(4)
	v_mul_lo_u32 v0, v100, s66
	s_waitcnt lgkmcnt(0)
	v_mfma_f32_32x32x16_f16 v[18:33], v[86:89], v[90:93], v[18:33]
	s_waitcnt vmcnt(0)
	s_barrier
	v_mfma_f32_32x32x16_f16 v[2:17], v[86:89], v[94:97], v[2:17]
	v_mfma_f32_32x32x16_f16 v[50:65], v[82:85], v[90:93], v[50:65]
	v_mfma_f32_32x32x16_f16 v[34:49], v[82:85], v[94:97], v[34:49]
	v_bfe_u32 v82, v98, 3, 3
	v_and_or_b32 v83, v99, 64, s2
	v_or_b32_e32 v105, 24, v82
	v_mfma_f32_32x32x16_f16 v[18:33], v[70:73], v[74:77], v[18:33]
	v_mfma_f32_32x32x16_f16 v[2:17], v[70:73], v[78:81], v[2:17]
	v_add_u32_e32 v72, 0xa000, v0
	v_lshrrev_b32_e32 v0, 1, v98
	v_mul_u32_u24_e32 v73, 0x90, v101
	v_mov_b64_e32 v[100:101], s[40:41]
	v_mfma_f32_32x32x16_f16 v[50:65], v[66:69], v[74:77], v[50:65]
	v_and_b32_e32 v74, 16, v0
	v_ashrrev_i32_e32 v0, 1, v99
	v_and_b32_e32 v0, 0xffffffc0, v0
	v_lshl_add_u32 v104, s9, 7, v0
	v_and_b32_e32 v0, 7, v98
	v_lshlrev_b32_e32 v70, 2, v0
	v_lshlrev_b32_e32 v0, 4, v0
	v_mfma_f32_32x32x16_f16 v[34:49], v[66:69], v[78:81], v[34:49]
	s_nop 15
	s_nop 15
	v_readlane_b32 s12, v224, 34
	v_readlane_b32 s13, v224, 35
	s_sub_i32 s9, s8, s76
	s_and_b32 s2, s9, 1
	s_lshr_b32 s9, s9, 1
	s_load_dwordx2 s[14:15], s[12:13], 0x88
	v_and_b32_e32 v69, 7, v131
	v_bfe_u32 v68, v131, 3, 3
	v_lshrrev_b32_e32 v70, 6, v131
	v_mul_u32_u24_e32 v0, 0x2400, v70
	v_add_u32_e32 v0, 0xa000, v0
	v_and_b32_e32 v66, 31, v131
	v_mul_u32_u24_e32 v66, 0x90, v66
	v_bfe_u32 v67, v131, 5, 1
	v_lshl_add_u32 v66, v67, 4, v66
	v_add_u32_e32 v66, v66, v0
	v_mul_u32_u24_e32 v67, 0x90, v68
	v_lshl_add_u32 v67, v69, 4, v67
	v_add_u32_e32 v67, v67, v0
	v_lshrrev_b32_e32 v0, 1, v70
	v_and_b32_e32 v70, 1, v70
	s_lshl_b32 s3, s9, 7
	v_lshl_add_u32 v71, v70, 6, v68
	v_add_u32_e32 v71, s3, v71
	s_lshl_b32 s3, s2, 7
	v_lshl_add_u32 v70, v0, 6, s3
	v_lshl_add_u32 v70, v69, 2, v70
	v_lshlrev_b32_e32 v70, 2, v70
	s_lshl_b32 s3, s2, 1
	v_add_u32_e32 v0, s3, v0
	v_mul_u32_u24_e32 v0, 0xc0, v0
	v_lshl_add_u32 v69, v69, 2, v0
	v_lshlrev_b32_e32 v69, 2, v69
	s_lshl_b32 s3, s38, 1
	s_add_i32 s3, s3, 1
	s_lshl_b32 s3, s3, 10
	s_waitcnt lgkmcnt(0)
	s_add_u32 s14, s14, s3
	s_addc_u32 s15, s15, 0
	s_load_dwordx2 s[2:3], s[12:13], 0xa8
	global_load_dwordx4 v[72:75], v70, s[14:15]
	s_lshl_b32 s9, s38, 10
	s_waitcnt lgkmcnt(0)
	s_add_u32 s2, s2, s9
	s_addc_u32 s3, s3, 0
	global_load_dwordx4 v[76:79], v70, s[2:3]
	s_waitcnt vmcnt(0)
	s_load_dwordx2 s[14:15], s[12:13], 0x1d8
	s_load_dwordx2 s[2:3], s[12:13], 0x1c8
	s_load_dwordx2 s[12:13], s[12:13], 0x1d0
	s_waitcnt lgkmcnt(0)
	s_add_u32 s2, s2, 0x2400000
	s_addc_u32 s3, s3, 0
	ds_write_b128 v66, v[50:53] offset:0
	ds_write_b128 v66, v[54:57] offset:32
	ds_write_b128 v66, v[58:61] offset:64
	ds_write_b128 v66, v[62:65] offset:96
	ds_read_b128 v[80:83], v67 offset:0
	ds_read_b128 v[84:87], v67 offset:1152
	ds_read_b128 v[88:91], v67 offset:2304
	ds_read_b128 v[92:95], v67 offset:3456
	v_add_u32_e32 v0, 0, v71
	v_mul_u32_u24_e32 v128, 0xc00, v0
	v_add_u32_e32 v128, v128, v69
	global_load_dwordx4 v[96:99], v128, s[12:13] offset:0
	v_lshl_add_u32 v129, v0, 10, v70
	global_load_dwordx4 v[112:115], v129, s[14:15] offset:0
	v_add_u32_e32 v0, 8, v71
	v_mul_u32_u24_e32 v128, 0xc00, v0
	v_add_u32_e32 v128, v128, v69
	global_load_dwordx4 v[100:103], v128, s[12:13] offset:0
	v_lshl_add_u32 v129, v0, 10, v70
	global_load_dwordx4 v[116:119], v129, s[14:15] offset:0
	v_add_u32_e32 v0, 16, v71
	v_mul_u32_u24_e32 v128, 0xc00, v0
	v_add_u32_e32 v128, v128, v69
	global_load_dwordx4 v[104:107], v128, s[12:13] offset:0
	v_lshl_add_u32 v129, v0, 10, v70
	global_load_dwordx4 v[120:123], v129, s[14:15] offset:0
	v_add_u32_e32 v0, 24, v71
	v_mul_u32_u24_e32 v128, 0xc00, v0
	v_add_u32_e32 v128, v128, v69
	global_load_dwordx4 v[108:111], v128, s[12:13] offset:0
	v_lshl_add_u32 v129, v0, 10, v70
	global_load_dwordx4 v[124:127], v129, s[14:15] offset:0
	s_waitcnt vmcnt(0) lgkmcnt(0)
	v_add_f32_e32 v80, v80, v72
	v_mul_f32_e32 v80, 0xbfb8aa3b, v80
	v_exp_f32_e32 v80, v80
	s_nop 0
	v_add_f32_e32 v80, 1.0, v80
	v_rcp_f32_e32 v80, v80
	s_nop 0
	v_xor_b32_e32 v128, 0x80000000, v80
	v_mul_f32_e32 v96, v96, v128
	v_add_f32_e32 v80, -1.0, v80
	v_fma_f32 v80, v76, v80, 1.0
	v_mul_f32_e32 v112, v112, v80
	v_add_f32_e32 v81, v81, v73
	v_mul_f32_e32 v81, 0xbfb8aa3b, v81
	v_exp_f32_e32 v81, v81
	s_nop 0
	v_add_f32_e32 v81, 1.0, v81
	v_rcp_f32_e32 v81, v81
	s_nop 0
	v_xor_b32_e32 v128, 0x80000000, v81
	v_mul_f32_e32 v97, v97, v128
	v_add_f32_e32 v81, -1.0, v81
	v_fma_f32 v81, v77, v81, 1.0
	v_mul_f32_e32 v113, v113, v81
	v_add_f32_e32 v82, v82, v74
	v_mul_f32_e32 v82, 0xbfb8aa3b, v82
	v_exp_f32_e32 v82, v82
	s_nop 0
	v_add_f32_e32 v82, 1.0, v82
	v_rcp_f32_e32 v82, v82
	s_nop 0
	v_xor_b32_e32 v128, 0x80000000, v82
	v_mul_f32_e32 v98, v98, v128
	v_add_f32_e32 v82, -1.0, v82
	v_fma_f32 v82, v78, v82, 1.0
	v_mul_f32_e32 v114, v114, v82
	v_add_f32_e32 v83, v83, v75
	v_mul_f32_e32 v83, 0xbfb8aa3b, v83
	v_exp_f32_e32 v83, v83
	s_nop 0
	v_add_f32_e32 v83, 1.0, v83
	v_rcp_f32_e32 v83, v83
	s_nop 0
	v_xor_b32_e32 v128, 0x80000000, v83
	v_mul_f32_e32 v99, v99, v128
	v_add_f32_e32 v83, -1.0, v83
	v_fma_f32 v83, v79, v83, 1.0
	v_mul_f32_e32 v115, v115, v83
	v_add_f32_e32 v84, v84, v72
	v_mul_f32_e32 v84, 0xbfb8aa3b, v84
	v_exp_f32_e32 v84, v84
	s_nop 0
	v_add_f32_e32 v84, 1.0, v84
	v_rcp_f32_e32 v84, v84
	s_nop 0
	v_xor_b32_e32 v128, 0x80000000, v84
	v_mul_f32_e32 v100, v100, v128
	v_add_f32_e32 v84, -1.0, v84
	v_fma_f32 v84, v76, v84, 1.0
	v_mul_f32_e32 v116, v116, v84
	v_add_f32_e32 v85, v85, v73
	v_mul_f32_e32 v85, 0xbfb8aa3b, v85
	v_exp_f32_e32 v85, v85
	s_nop 0
	v_add_f32_e32 v85, 1.0, v85
	v_rcp_f32_e32 v85, v85
	s_nop 0
	v_xor_b32_e32 v128, 0x80000000, v85
	v_mul_f32_e32 v101, v101, v128
	v_add_f32_e32 v85, -1.0, v85
	v_fma_f32 v85, v77, v85, 1.0
	v_mul_f32_e32 v117, v117, v85
	v_add_f32_e32 v86, v86, v74
	v_mul_f32_e32 v86, 0xbfb8aa3b, v86
	v_exp_f32_e32 v86, v86
	s_nop 0
	v_add_f32_e32 v86, 1.0, v86
	v_rcp_f32_e32 v86, v86
	s_nop 0
	v_xor_b32_e32 v128, 0x80000000, v86
	v_mul_f32_e32 v102, v102, v128
	v_add_f32_e32 v86, -1.0, v86
	v_fma_f32 v86, v78, v86, 1.0
	v_mul_f32_e32 v118, v118, v86
	v_add_f32_e32 v87, v87, v75
	v_mul_f32_e32 v87, 0xbfb8aa3b, v87
	v_exp_f32_e32 v87, v87
	s_nop 0
	v_add_f32_e32 v87, 1.0, v87
	v_rcp_f32_e32 v87, v87
	s_nop 0
	v_xor_b32_e32 v128, 0x80000000, v87
	v_mul_f32_e32 v103, v103, v128
	v_add_f32_e32 v87, -1.0, v87
	v_fma_f32 v87, v79, v87, 1.0
	v_mul_f32_e32 v119, v119, v87
	v_add_f32_e32 v88, v88, v72
	v_mul_f32_e32 v88, 0xbfb8aa3b, v88
	v_exp_f32_e32 v88, v88
	s_nop 0
	v_add_f32_e32 v88, 1.0, v88
	v_rcp_f32_e32 v88, v88
	s_nop 0
	v_xor_b32_e32 v128, 0x80000000, v88
	v_mul_f32_e32 v104, v104, v128
	v_add_f32_e32 v88, -1.0, v88
	v_fma_f32 v88, v76, v88, 1.0
	v_mul_f32_e32 v120, v120, v88
	v_add_f32_e32 v89, v89, v73
	v_mul_f32_e32 v89, 0xbfb8aa3b, v89
	v_exp_f32_e32 v89, v89
	s_nop 0
	v_add_f32_e32 v89, 1.0, v89
	v_rcp_f32_e32 v89, v89
	s_nop 0
	v_xor_b32_e32 v128, 0x80000000, v89
	v_mul_f32_e32 v105, v105, v128
	v_add_f32_e32 v89, -1.0, v89
	v_fma_f32 v89, v77, v89, 1.0
	v_mul_f32_e32 v121, v121, v89
	v_add_f32_e32 v90, v90, v74
	v_mul_f32_e32 v90, 0xbfb8aa3b, v90
	v_exp_f32_e32 v90, v90
	s_nop 0
	v_add_f32_e32 v90, 1.0, v90
	v_rcp_f32_e32 v90, v90
	s_nop 0
	v_xor_b32_e32 v128, 0x80000000, v90
	v_mul_f32_e32 v106, v106, v128
	v_add_f32_e32 v90, -1.0, v90
	v_fma_f32 v90, v78, v90, 1.0
	v_mul_f32_e32 v122, v122, v90
	v_add_f32_e32 v91, v91, v75
	v_mul_f32_e32 v91, 0xbfb8aa3b, v91
	v_exp_f32_e32 v91, v91
	s_nop 0
	v_add_f32_e32 v91, 1.0, v91
	v_rcp_f32_e32 v91, v91
	s_nop 0
	v_xor_b32_e32 v128, 0x80000000, v91
	v_mul_f32_e32 v107, v107, v128
	v_add_f32_e32 v91, -1.0, v91
	v_fma_f32 v91, v79, v91, 1.0
	v_mul_f32_e32 v123, v123, v91
	v_add_f32_e32 v92, v92, v72
	v_mul_f32_e32 v92, 0xbfb8aa3b, v92
	v_exp_f32_e32 v92, v92
	s_nop 0
	v_add_f32_e32 v92, 1.0, v92
	v_rcp_f32_e32 v92, v92
	s_nop 0
	v_xor_b32_e32 v128, 0x80000000, v92
	v_mul_f32_e32 v108, v108, v128
	v_add_f32_e32 v92, -1.0, v92
	v_fma_f32 v92, v76, v92, 1.0
	v_mul_f32_e32 v124, v124, v92
	v_add_f32_e32 v93, v93, v73
	v_mul_f32_e32 v93, 0xbfb8aa3b, v93
	v_exp_f32_e32 v93, v93
	s_nop 0
	v_add_f32_e32 v93, 1.0, v93
	v_rcp_f32_e32 v93, v93
	s_nop 0
	v_xor_b32_e32 v128, 0x80000000, v93
	v_mul_f32_e32 v109, v109, v128
	v_add_f32_e32 v93, -1.0, v93
	v_fma_f32 v93, v77, v93, 1.0
	v_mul_f32_e32 v125, v125, v93
	v_add_f32_e32 v94, v94, v74
	v_mul_f32_e32 v94, 0xbfb8aa3b, v94
	v_exp_f32_e32 v94, v94
	s_nop 0
	v_add_f32_e32 v94, 1.0, v94
	v_rcp_f32_e32 v94, v94
	s_nop 0
	v_xor_b32_e32 v128, 0x80000000, v94
	v_mul_f32_e32 v110, v110, v128
	v_add_f32_e32 v94, -1.0, v94
	v_fma_f32 v94, v78, v94, 1.0
	v_mul_f32_e32 v126, v126, v94
	v_add_f32_e32 v95, v95, v75
	v_mul_f32_e32 v95, 0xbfb8aa3b, v95
	v_exp_f32_e32 v95, v95
	s_nop 0
	v_add_f32_e32 v95, 1.0, v95
	v_rcp_f32_e32 v95, v95
	s_nop 0
	v_xor_b32_e32 v128, 0x80000000, v95
	v_mul_f32_e32 v111, v111, v128
	v_add_f32_e32 v95, -1.0, v95
	v_fma_f32 v95, v79, v95, 1.0
	v_mul_f32_e32 v127, v127, v95
	v_add_u32_e32 v0, 0, v71
	v_mul_u32_u24_e32 v128, 0xc00, v0
	v_add_u32_e32 v128, v128, v69
	global_store_dwordx4 v128, v[96:99], s[2:3] offset:256
	global_store_dwordx4 v128, v[112:115], s[2:3] offset:512
	v_add_u32_e32 v0, 8, v71
	v_mul_u32_u24_e32 v128, 0xc00, v0
	v_add_u32_e32 v128, v128, v69
	global_store_dwordx4 v128, v[100:103], s[2:3] offset:256
	global_store_dwordx4 v128, v[116:119], s[2:3] offset:512
	v_add_u32_e32 v0, 16, v71
	v_mul_u32_u24_e32 v128, 0xc00, v0
	v_add_u32_e32 v128, v128, v69
	global_store_dwordx4 v128, v[104:107], s[2:3] offset:256
	global_store_dwordx4 v128, v[120:123], s[2:3] offset:512
	v_add_u32_e32 v0, 24, v71
	v_mul_u32_u24_e32 v128, 0xc00, v0
	v_add_u32_e32 v128, v128, v69
	global_store_dwordx4 v128, v[108:111], s[2:3] offset:256
	global_store_dwordx4 v128, v[124:127], s[2:3] offset:512
	ds_write_b128 v66, v[34:37] offset:4608
	ds_write_b128 v66, v[38:41] offset:4640
	ds_write_b128 v66, v[42:45] offset:4672
	ds_write_b128 v66, v[46:49] offset:4704
	ds_read_b128 v[80:83], v67 offset:4608
	ds_read_b128 v[84:87], v67 offset:5760
	ds_read_b128 v[88:91], v67 offset:6912
	ds_read_b128 v[92:95], v67 offset:8064
	v_add_u32_e32 v0, 32, v71
	v_mul_u32_u24_e32 v128, 0xc00, v0
	v_add_u32_e32 v128, v128, v69
	global_load_dwordx4 v[96:99], v128, s[12:13] offset:0
	v_lshl_add_u32 v129, v0, 10, v70
	global_load_dwordx4 v[112:115], v129, s[14:15] offset:0
	v_add_u32_e32 v0, 40, v71
	v_mul_u32_u24_e32 v128, 0xc00, v0
	v_add_u32_e32 v128, v128, v69
	global_load_dwordx4 v[100:103], v128, s[12:13] offset:0
	v_lshl_add_u32 v129, v0, 10, v70
	global_load_dwordx4 v[116:119], v129, s[14:15] offset:0
	v_add_u32_e32 v0, 48, v71
	v_mul_u32_u24_e32 v128, 0xc00, v0
	v_add_u32_e32 v128, v128, v69
	global_load_dwordx4 v[104:107], v128, s[12:13] offset:0
	v_lshl_add_u32 v129, v0, 10, v70
	global_load_dwordx4 v[120:123], v129, s[14:15] offset:0
	v_add_u32_e32 v0, 56, v71
	v_mul_u32_u24_e32 v128, 0xc00, v0
	v_add_u32_e32 v128, v128, v69
	global_load_dwordx4 v[108:111], v128, s[12:13] offset:0
	v_lshl_add_u32 v129, v0, 10, v70
	global_load_dwordx4 v[124:127], v129, s[14:15] offset:0
	s_waitcnt vmcnt(0) lgkmcnt(0)
	v_add_f32_e32 v80, v80, v72
	v_mul_f32_e32 v80, 0xbfb8aa3b, v80
	v_exp_f32_e32 v80, v80
	s_nop 0
	v_add_f32_e32 v80, 1.0, v80
	v_rcp_f32_e32 v80, v80
	s_nop 0
	v_xor_b32_e32 v128, 0x80000000, v80
	v_mul_f32_e32 v96, v96, v128
	v_add_f32_e32 v80, -1.0, v80
	v_fma_f32 v80, v76, v80, 1.0
	v_mul_f32_e32 v112, v112, v80
	v_add_f32_e32 v81, v81, v73
	v_mul_f32_e32 v81, 0xbfb8aa3b, v81
	v_exp_f32_e32 v81, v81
	s_nop 0
	v_add_f32_e32 v81, 1.0, v81
	v_rcp_f32_e32 v81, v81
	s_nop 0
	v_xor_b32_e32 v128, 0x80000000, v81
	v_mul_f32_e32 v97, v97, v128
	v_add_f32_e32 v81, -1.0, v81
	v_fma_f32 v81, v77, v81, 1.0
	v_mul_f32_e32 v113, v113, v81
	v_add_f32_e32 v82, v82, v74
	v_mul_f32_e32 v82, 0xbfb8aa3b, v82
	v_exp_f32_e32 v82, v82
	s_nop 0
	v_add_f32_e32 v82, 1.0, v82
	v_rcp_f32_e32 v82, v82
	s_nop 0
	v_xor_b32_e32 v128, 0x80000000, v82
	v_mul_f32_e32 v98, v98, v128
	v_add_f32_e32 v82, -1.0, v82
	v_fma_f32 v82, v78, v82, 1.0
	v_mul_f32_e32 v114, v114, v82
	v_add_f32_e32 v83, v83, v75
	v_mul_f32_e32 v83, 0xbfb8aa3b, v83
	v_exp_f32_e32 v83, v83
	s_nop 0
	v_add_f32_e32 v83, 1.0, v83
	v_rcp_f32_e32 v83, v83
	s_nop 0
	v_xor_b32_e32 v128, 0x80000000, v83
	v_mul_f32_e32 v99, v99, v128
	v_add_f32_e32 v83, -1.0, v83
	v_fma_f32 v83, v79, v83, 1.0
	v_mul_f32_e32 v115, v115, v83
	v_add_f32_e32 v84, v84, v72
	v_mul_f32_e32 v84, 0xbfb8aa3b, v84
	v_exp_f32_e32 v84, v84
	s_nop 0
	v_add_f32_e32 v84, 1.0, v84
	v_rcp_f32_e32 v84, v84
	s_nop 0
	v_xor_b32_e32 v128, 0x80000000, v84
	v_mul_f32_e32 v100, v100, v128
	v_add_f32_e32 v84, -1.0, v84
	v_fma_f32 v84, v76, v84, 1.0
	v_mul_f32_e32 v116, v116, v84
	v_add_f32_e32 v85, v85, v73
	v_mul_f32_e32 v85, 0xbfb8aa3b, v85
	v_exp_f32_e32 v85, v85
	s_nop 0
	v_add_f32_e32 v85, 1.0, v85
	v_rcp_f32_e32 v85, v85
	s_nop 0
	v_xor_b32_e32 v128, 0x80000000, v85
	v_mul_f32_e32 v101, v101, v128
	v_add_f32_e32 v85, -1.0, v85
	v_fma_f32 v85, v77, v85, 1.0
	v_mul_f32_e32 v117, v117, v85
	v_add_f32_e32 v86, v86, v74
	v_mul_f32_e32 v86, 0xbfb8aa3b, v86
	v_exp_f32_e32 v86, v86
	s_nop 0
	v_add_f32_e32 v86, 1.0, v86
	v_rcp_f32_e32 v86, v86
	s_nop 0
	v_xor_b32_e32 v128, 0x80000000, v86
	v_mul_f32_e32 v102, v102, v128
	v_add_f32_e32 v86, -1.0, v86
	v_fma_f32 v86, v78, v86, 1.0
	v_mul_f32_e32 v118, v118, v86
	v_add_f32_e32 v87, v87, v75
	v_mul_f32_e32 v87, 0xbfb8aa3b, v87
	v_exp_f32_e32 v87, v87
	s_nop 0
	v_add_f32_e32 v87, 1.0, v87
	v_rcp_f32_e32 v87, v87
	s_nop 0
	v_xor_b32_e32 v128, 0x80000000, v87
	v_mul_f32_e32 v103, v103, v128
	v_add_f32_e32 v87, -1.0, v87
	v_fma_f32 v87, v79, v87, 1.0
	v_mul_f32_e32 v119, v119, v87
	v_add_f32_e32 v88, v88, v72
	v_mul_f32_e32 v88, 0xbfb8aa3b, v88
	v_exp_f32_e32 v88, v88
	s_nop 0
	v_add_f32_e32 v88, 1.0, v88
	v_rcp_f32_e32 v88, v88
	s_nop 0
	v_xor_b32_e32 v128, 0x80000000, v88
	v_mul_f32_e32 v104, v104, v128
	v_add_f32_e32 v88, -1.0, v88
	v_fma_f32 v88, v76, v88, 1.0
	v_mul_f32_e32 v120, v120, v88
	v_add_f32_e32 v89, v89, v73
	v_mul_f32_e32 v89, 0xbfb8aa3b, v89
	v_exp_f32_e32 v89, v89
	s_nop 0
	v_add_f32_e32 v89, 1.0, v89
	v_rcp_f32_e32 v89, v89
	s_nop 0
	v_xor_b32_e32 v128, 0x80000000, v89
	v_mul_f32_e32 v105, v105, v128
	v_add_f32_e32 v89, -1.0, v89
	v_fma_f32 v89, v77, v89, 1.0
	v_mul_f32_e32 v121, v121, v89
	v_add_f32_e32 v90, v90, v74
	v_mul_f32_e32 v90, 0xbfb8aa3b, v90
	v_exp_f32_e32 v90, v90
	s_nop 0
	v_add_f32_e32 v90, 1.0, v90
	v_rcp_f32_e32 v90, v90
	s_nop 0
	v_xor_b32_e32 v128, 0x80000000, v90
	v_mul_f32_e32 v106, v106, v128
	v_add_f32_e32 v90, -1.0, v90
	v_fma_f32 v90, v78, v90, 1.0
	v_mul_f32_e32 v122, v122, v90
	v_add_f32_e32 v91, v91, v75
	v_mul_f32_e32 v91, 0xbfb8aa3b, v91
	v_exp_f32_e32 v91, v91
	s_nop 0
	v_add_f32_e32 v91, 1.0, v91
	v_rcp_f32_e32 v91, v91
	s_nop 0
	v_xor_b32_e32 v128, 0x80000000, v91
	v_mul_f32_e32 v107, v107, v128
	v_add_f32_e32 v91, -1.0, v91
	v_fma_f32 v91, v79, v91, 1.0
	v_mul_f32_e32 v123, v123, v91
	v_add_f32_e32 v92, v92, v72
	v_mul_f32_e32 v92, 0xbfb8aa3b, v92
	v_exp_f32_e32 v92, v92
	s_nop 0
	v_add_f32_e32 v92, 1.0, v92
	v_rcp_f32_e32 v92, v92
	s_nop 0
	v_xor_b32_e32 v128, 0x80000000, v92
	v_mul_f32_e32 v108, v108, v128
	v_add_f32_e32 v92, -1.0, v92
	v_fma_f32 v92, v76, v92, 1.0
	v_mul_f32_e32 v124, v124, v92
	v_add_f32_e32 v93, v93, v73
	v_mul_f32_e32 v93, 0xbfb8aa3b, v93
	v_exp_f32_e32 v93, v93
	s_nop 0
	v_add_f32_e32 v93, 1.0, v93
	v_rcp_f32_e32 v93, v93
	s_nop 0
	v_xor_b32_e32 v128, 0x80000000, v93
	v_mul_f32_e32 v109, v109, v128
	v_add_f32_e32 v93, -1.0, v93
	v_fma_f32 v93, v77, v93, 1.0
	v_mul_f32_e32 v125, v125, v93
	v_add_f32_e32 v94, v94, v74
	v_mul_f32_e32 v94, 0xbfb8aa3b, v94
	v_exp_f32_e32 v94, v94
	s_nop 0
	v_add_f32_e32 v94, 1.0, v94
	v_rcp_f32_e32 v94, v94
	s_nop 0
	v_xor_b32_e32 v128, 0x80000000, v94
	v_mul_f32_e32 v110, v110, v128
	v_add_f32_e32 v94, -1.0, v94
	v_fma_f32 v94, v78, v94, 1.0
	v_mul_f32_e32 v126, v126, v94
	v_add_f32_e32 v95, v95, v75
	v_mul_f32_e32 v95, 0xbfb8aa3b, v95
	v_exp_f32_e32 v95, v95
	s_nop 0
	v_add_f32_e32 v95, 1.0, v95
	v_rcp_f32_e32 v95, v95
	s_nop 0
	v_xor_b32_e32 v128, 0x80000000, v95
	v_mul_f32_e32 v111, v111, v128
	v_add_f32_e32 v95, -1.0, v95
	v_fma_f32 v95, v79, v95, 1.0
	v_mul_f32_e32 v127, v127, v95
	v_add_u32_e32 v0, 32, v71
	v_mul_u32_u24_e32 v128, 0xc00, v0
	v_add_u32_e32 v128, v128, v69
	global_store_dwordx4 v128, v[96:99], s[2:3] offset:256
	global_store_dwordx4 v128, v[112:115], s[2:3] offset:512
	v_add_u32_e32 v0, 40, v71
	v_mul_u32_u24_e32 v128, 0xc00, v0
	v_add_u32_e32 v128, v128, v69
	global_store_dwordx4 v128, v[100:103], s[2:3] offset:256
	global_store_dwordx4 v128, v[116:119], s[2:3] offset:512
	v_add_u32_e32 v0, 48, v71
	v_mul_u32_u24_e32 v128, 0xc00, v0
	v_add_u32_e32 v128, v128, v69
	global_store_dwordx4 v128, v[104:107], s[2:3] offset:256
	global_store_dwordx4 v128, v[120:123], s[2:3] offset:512
	v_add_u32_e32 v0, 56, v71
	v_mul_u32_u24_e32 v128, 0xc00, v0
	v_add_u32_e32 v128, v128, v69
	global_store_dwordx4 v128, v[108:111], s[2:3] offset:256
	global_store_dwordx4 v128, v[124:127], s[2:3] offset:512
	v_readlane_b32 s14, v224, 34
	v_readlane_b32 s15, v224, 35
	s_load_dwordx2 s[14:15], s[14:15], 0x88
	s_lshl_b32 s9, s38, 1
	s_add_i32 s9, s9, 1
	s_lshl_b32 s9, s9, 10
	s_waitcnt lgkmcnt(0)
	s_add_u32 s14, s14, s9
	s_addc_u32 s15, s15, 0
	global_load_dwordx4 v[72:75], v70, s[14:15] offset:128
	v_readlane_b32 s14, v224, 34
	v_readlane_b32 s15, v224, 35
	s_load_dwordx2 s[14:15], s[14:15], 0xa8
	s_lshl_b32 s9, s38, 10
	s_waitcnt lgkmcnt(0)
	s_add_u32 s14, s14, s9
	s_addc_u32 s15, s15, 0
	global_load_dwordx4 v[76:79], v70, s[14:15] offset:128
	v_readlane_b32 s14, v224, 34
	v_readlane_b32 s15, v224, 35
	s_load_dwordx2 s[14:15], s[14:15], 0x1d8
	s_waitcnt lgkmcnt(0)
	ds_write_b128 v66, v[18:21] offset:0
	ds_write_b128 v66, v[22:25] offset:32
	ds_write_b128 v66, v[26:29] offset:64
	ds_write_b128 v66, v[30:33] offset:96
	ds_read_b128 v[80:83], v67 offset:0
	ds_read_b128 v[84:87], v67 offset:1152
	ds_read_b128 v[88:91], v67 offset:2304
	ds_read_b128 v[92:95], v67 offset:3456
	v_add_u32_e32 v0, 0, v71
	v_mul_u32_u24_e32 v128, 0xc00, v0
	v_add_u32_e32 v128, v128, v69
	global_load_dwordx4 v[96:99], v128, s[12:13] offset:128
	v_lshl_add_u32 v129, v0, 10, v70
	global_load_dwordx4 v[112:115], v129, s[14:15] offset:128
	v_add_u32_e32 v0, 8, v71
	v_mul_u32_u24_e32 v128, 0xc00, v0
	v_add_u32_e32 v128, v128, v69
	global_load_dwordx4 v[100:103], v128, s[12:13] offset:128
	v_lshl_add_u32 v129, v0, 10, v70
	global_load_dwordx4 v[116:119], v129, s[14:15] offset:128
	v_add_u32_e32 v0, 16, v71
	v_mul_u32_u24_e32 v128, 0xc00, v0
	v_add_u32_e32 v128, v128, v69
	global_load_dwordx4 v[104:107], v128, s[12:13] offset:128
	v_lshl_add_u32 v129, v0, 10, v70
	global_load_dwordx4 v[120:123], v129, s[14:15] offset:128
	v_add_u32_e32 v0, 24, v71
	v_mul_u32_u24_e32 v128, 0xc00, v0
	v_add_u32_e32 v128, v128, v69
	global_load_dwordx4 v[108:111], v128, s[12:13] offset:128
	v_lshl_add_u32 v129, v0, 10, v70
	global_load_dwordx4 v[124:127], v129, s[14:15] offset:128
	s_waitcnt vmcnt(0) lgkmcnt(0)
	v_add_f32_e32 v80, v80, v72
	v_mul_f32_e32 v80, 0xbfb8aa3b, v80
	v_exp_f32_e32 v80, v80
	s_nop 0
	v_add_f32_e32 v80, 1.0, v80
	v_rcp_f32_e32 v80, v80
	s_nop 0
	v_xor_b32_e32 v128, 0x80000000, v80
	v_mul_f32_e32 v96, v96, v128
	v_add_f32_e32 v80, -1.0, v80
	v_fma_f32 v80, v76, v80, 1.0
	v_mul_f32_e32 v112, v112, v80
	v_add_f32_e32 v81, v81, v73
	v_mul_f32_e32 v81, 0xbfb8aa3b, v81
	v_exp_f32_e32 v81, v81
	s_nop 0
	v_add_f32_e32 v81, 1.0, v81
	v_rcp_f32_e32 v81, v81
	s_nop 0
	v_xor_b32_e32 v128, 0x80000000, v81
	v_mul_f32_e32 v97, v97, v128
	v_add_f32_e32 v81, -1.0, v81
	v_fma_f32 v81, v77, v81, 1.0
	v_mul_f32_e32 v113, v113, v81
	v_add_f32_e32 v82, v82, v74
	v_mul_f32_e32 v82, 0xbfb8aa3b, v82
	v_exp_f32_e32 v82, v82
	s_nop 0
	v_add_f32_e32 v82, 1.0, v82
	v_rcp_f32_e32 v82, v82
	s_nop 0
	v_xor_b32_e32 v128, 0x80000000, v82
	v_mul_f32_e32 v98, v98, v128
	v_add_f32_e32 v82, -1.0, v82
	v_fma_f32 v82, v78, v82, 1.0
	v_mul_f32_e32 v114, v114, v82
	v_add_f32_e32 v83, v83, v75
	v_mul_f32_e32 v83, 0xbfb8aa3b, v83
	v_exp_f32_e32 v83, v83
	s_nop 0
	v_add_f32_e32 v83, 1.0, v83
	v_rcp_f32_e32 v83, v83
	s_nop 0
	v_xor_b32_e32 v128, 0x80000000, v83
	v_mul_f32_e32 v99, v99, v128
	v_add_f32_e32 v83, -1.0, v83
	v_fma_f32 v83, v79, v83, 1.0
	v_mul_f32_e32 v115, v115, v83
	v_add_f32_e32 v84, v84, v72
	v_mul_f32_e32 v84, 0xbfb8aa3b, v84
	v_exp_f32_e32 v84, v84
	s_nop 0
	v_add_f32_e32 v84, 1.0, v84
	v_rcp_f32_e32 v84, v84
	s_nop 0
	v_xor_b32_e32 v128, 0x80000000, v84
	v_mul_f32_e32 v100, v100, v128
	v_add_f32_e32 v84, -1.0, v84
	v_fma_f32 v84, v76, v84, 1.0
	v_mul_f32_e32 v116, v116, v84
	v_add_f32_e32 v85, v85, v73
	v_mul_f32_e32 v85, 0xbfb8aa3b, v85
	v_exp_f32_e32 v85, v85
	s_nop 0
	v_add_f32_e32 v85, 1.0, v85
	v_rcp_f32_e32 v85, v85
	s_nop 0
	v_xor_b32_e32 v128, 0x80000000, v85
	v_mul_f32_e32 v101, v101, v128
	v_add_f32_e32 v85, -1.0, v85
	v_fma_f32 v85, v77, v85, 1.0
	v_mul_f32_e32 v117, v117, v85
	v_add_f32_e32 v86, v86, v74
	v_mul_f32_e32 v86, 0xbfb8aa3b, v86
	v_exp_f32_e32 v86, v86
	s_nop 0
	v_add_f32_e32 v86, 1.0, v86
	v_rcp_f32_e32 v86, v86
	s_nop 0
	v_xor_b32_e32 v128, 0x80000000, v86
	v_mul_f32_e32 v102, v102, v128
	v_add_f32_e32 v86, -1.0, v86
	v_fma_f32 v86, v78, v86, 1.0
	v_mul_f32_e32 v118, v118, v86
	v_add_f32_e32 v87, v87, v75
	v_mul_f32_e32 v87, 0xbfb8aa3b, v87
	v_exp_f32_e32 v87, v87
	s_nop 0
	v_add_f32_e32 v87, 1.0, v87
	v_rcp_f32_e32 v87, v87
	s_nop 0
	v_xor_b32_e32 v128, 0x80000000, v87
	v_mul_f32_e32 v103, v103, v128
	v_add_f32_e32 v87, -1.0, v87
	v_fma_f32 v87, v79, v87, 1.0
	v_mul_f32_e32 v119, v119, v87
	v_add_f32_e32 v88, v88, v72
	v_mul_f32_e32 v88, 0xbfb8aa3b, v88
	v_exp_f32_e32 v88, v88
	s_nop 0
	v_add_f32_e32 v88, 1.0, v88
	v_rcp_f32_e32 v88, v88
	s_nop 0
	v_xor_b32_e32 v128, 0x80000000, v88
	v_mul_f32_e32 v104, v104, v128
	v_add_f32_e32 v88, -1.0, v88
	v_fma_f32 v88, v76, v88, 1.0
	v_mul_f32_e32 v120, v120, v88
	v_add_f32_e32 v89, v89, v73
	v_mul_f32_e32 v89, 0xbfb8aa3b, v89
	v_exp_f32_e32 v89, v89
	s_nop 0
	v_add_f32_e32 v89, 1.0, v89
	v_rcp_f32_e32 v89, v89
	s_nop 0
	v_xor_b32_e32 v128, 0x80000000, v89
	v_mul_f32_e32 v105, v105, v128
	v_add_f32_e32 v89, -1.0, v89
	v_fma_f32 v89, v77, v89, 1.0
	v_mul_f32_e32 v121, v121, v89
	v_add_f32_e32 v90, v90, v74
	v_mul_f32_e32 v90, 0xbfb8aa3b, v90
	v_exp_f32_e32 v90, v90
	s_nop 0
	v_add_f32_e32 v90, 1.0, v90
	v_rcp_f32_e32 v90, v90
	s_nop 0
	v_xor_b32_e32 v128, 0x80000000, v90
	v_mul_f32_e32 v106, v106, v128
	v_add_f32_e32 v90, -1.0, v90
	v_fma_f32 v90, v78, v90, 1.0
	v_mul_f32_e32 v122, v122, v90
	v_add_f32_e32 v91, v91, v75
	v_mul_f32_e32 v91, 0xbfb8aa3b, v91
	v_exp_f32_e32 v91, v91
	s_nop 0
	v_add_f32_e32 v91, 1.0, v91
	v_rcp_f32_e32 v91, v91
	s_nop 0
	v_xor_b32_e32 v128, 0x80000000, v91
	v_mul_f32_e32 v107, v107, v128
	v_add_f32_e32 v91, -1.0, v91
	v_fma_f32 v91, v79, v91, 1.0
	v_mul_f32_e32 v123, v123, v91
	v_add_f32_e32 v92, v92, v72
	v_mul_f32_e32 v92, 0xbfb8aa3b, v92
	v_exp_f32_e32 v92, v92
	s_nop 0
	v_add_f32_e32 v92, 1.0, v92
	v_rcp_f32_e32 v92, v92
	s_nop 0
	v_xor_b32_e32 v128, 0x80000000, v92
	v_mul_f32_e32 v108, v108, v128
	v_add_f32_e32 v92, -1.0, v92
	v_fma_f32 v92, v76, v92, 1.0
	v_mul_f32_e32 v124, v124, v92
	v_add_f32_e32 v93, v93, v73
	v_mul_f32_e32 v93, 0xbfb8aa3b, v93
	v_exp_f32_e32 v93, v93
	s_nop 0
	v_add_f32_e32 v93, 1.0, v93
	v_rcp_f32_e32 v93, v93
	s_nop 0
	v_xor_b32_e32 v128, 0x80000000, v93
	v_mul_f32_e32 v109, v109, v128
	v_add_f32_e32 v93, -1.0, v93
	v_fma_f32 v93, v77, v93, 1.0
	v_mul_f32_e32 v125, v125, v93
	v_add_f32_e32 v94, v94, v74
	v_mul_f32_e32 v94, 0xbfb8aa3b, v94
	v_exp_f32_e32 v94, v94
	s_nop 0
	v_add_f32_e32 v94, 1.0, v94
	v_rcp_f32_e32 v94, v94
	s_nop 0
	v_xor_b32_e32 v128, 0x80000000, v94
	v_mul_f32_e32 v110, v110, v128
	v_add_f32_e32 v94, -1.0, v94
	v_fma_f32 v94, v78, v94, 1.0
	v_mul_f32_e32 v126, v126, v94
	v_add_f32_e32 v95, v95, v75
	v_mul_f32_e32 v95, 0xbfb8aa3b, v95
	v_exp_f32_e32 v95, v95
	s_nop 0
	v_add_f32_e32 v95, 1.0, v95
	v_rcp_f32_e32 v95, v95
	s_nop 0
	v_xor_b32_e32 v128, 0x80000000, v95
	v_mul_f32_e32 v111, v111, v128
	v_add_f32_e32 v95, -1.0, v95
	v_fma_f32 v95, v79, v95, 1.0
	v_mul_f32_e32 v127, v127, v95
	v_add_u32_e32 v0, 0, v71
	v_mul_u32_u24_e32 v128, 0xc00, v0
	v_add_u32_e32 v128, v128, v69
	global_store_dwordx4 v128, v[96:99], s[2:3] offset:384
	global_store_dwordx4 v128, v[112:115], s[2:3] offset:640
	v_add_u32_e32 v0, 8, v71
	v_mul_u32_u24_e32 v128, 0xc00, v0
	v_add_u32_e32 v128, v128, v69
	global_store_dwordx4 v128, v[100:103], s[2:3] offset:384
	global_store_dwordx4 v128, v[116:119], s[2:3] offset:640
	v_add_u32_e32 v0, 16, v71
	v_mul_u32_u24_e32 v128, 0xc00, v0
	v_add_u32_e32 v128, v128, v69
	global_store_dwordx4 v128, v[104:107], s[2:3] offset:384
	global_store_dwordx4 v128, v[120:123], s[2:3] offset:640
	v_add_u32_e32 v0, 24, v71
	v_mul_u32_u24_e32 v128, 0xc00, v0
	v_add_u32_e32 v128, v128, v69
	global_store_dwordx4 v128, v[108:111], s[2:3] offset:384
	global_store_dwordx4 v128, v[124:127], s[2:3] offset:640
	ds_write_b128 v66, v[2:5] offset:4608
	ds_write_b128 v66, v[6:9] offset:4640
	ds_write_b128 v66, v[10:13] offset:4672
	ds_write_b128 v66, v[14:17] offset:4704
	ds_read_b128 v[80:83], v67 offset:4608
	ds_read_b128 v[84:87], v67 offset:5760
	ds_read_b128 v[88:91], v67 offset:6912
	ds_read_b128 v[92:95], v67 offset:8064
	v_add_u32_e32 v0, 32, v71
	v_mul_u32_u24_e32 v128, 0xc00, v0
	v_add_u32_e32 v128, v128, v69
	global_load_dwordx4 v[96:99], v128, s[12:13] offset:128
	v_lshl_add_u32 v129, v0, 10, v70
	global_load_dwordx4 v[112:115], v129, s[14:15] offset:128
	v_add_u32_e32 v0, 40, v71
	v_mul_u32_u24_e32 v128, 0xc00, v0
	v_add_u32_e32 v128, v128, v69
	global_load_dwordx4 v[100:103], v128, s[12:13] offset:128
	v_lshl_add_u32 v129, v0, 10, v70
	global_load_dwordx4 v[116:119], v129, s[14:15] offset:128
	v_add_u32_e32 v0, 48, v71
	v_mul_u32_u24_e32 v128, 0xc00, v0
	v_add_u32_e32 v128, v128, v69
	global_load_dwordx4 v[104:107], v128, s[12:13] offset:128
	v_lshl_add_u32 v129, v0, 10, v70
	global_load_dwordx4 v[120:123], v129, s[14:15] offset:128
	v_add_u32_e32 v0, 56, v71
	v_mul_u32_u24_e32 v128, 0xc00, v0
	v_add_u32_e32 v128, v128, v69
	global_load_dwordx4 v[108:111], v128, s[12:13] offset:128
	v_lshl_add_u32 v129, v0, 10, v70
	global_load_dwordx4 v[124:127], v129, s[14:15] offset:128
	s_waitcnt vmcnt(0) lgkmcnt(0)
	v_add_f32_e32 v80, v80, v72
	v_mul_f32_e32 v80, 0xbfb8aa3b, v80
	v_exp_f32_e32 v80, v80
	s_nop 0
	v_add_f32_e32 v80, 1.0, v80
	v_rcp_f32_e32 v80, v80
	s_nop 0
	v_xor_b32_e32 v128, 0x80000000, v80
	v_mul_f32_e32 v96, v96, v128
	v_add_f32_e32 v80, -1.0, v80
	v_fma_f32 v80, v76, v80, 1.0
	v_mul_f32_e32 v112, v112, v80
	v_add_f32_e32 v81, v81, v73
	v_mul_f32_e32 v81, 0xbfb8aa3b, v81
	v_exp_f32_e32 v81, v81
	s_nop 0
	v_add_f32_e32 v81, 1.0, v81
	v_rcp_f32_e32 v81, v81
	s_nop 0
	v_xor_b32_e32 v128, 0x80000000, v81
	v_mul_f32_e32 v97, v97, v128
	v_add_f32_e32 v81, -1.0, v81
	v_fma_f32 v81, v77, v81, 1.0
	v_mul_f32_e32 v113, v113, v81
	v_add_f32_e32 v82, v82, v74
	v_mul_f32_e32 v82, 0xbfb8aa3b, v82
	v_exp_f32_e32 v82, v82
	s_nop 0
	v_add_f32_e32 v82, 1.0, v82
	v_rcp_f32_e32 v82, v82
	s_nop 0
	v_xor_b32_e32 v128, 0x80000000, v82
	v_mul_f32_e32 v98, v98, v128
	v_add_f32_e32 v82, -1.0, v82
	v_fma_f32 v82, v78, v82, 1.0
	v_mul_f32_e32 v114, v114, v82
	v_add_f32_e32 v83, v83, v75
	v_mul_f32_e32 v83, 0xbfb8aa3b, v83
	v_exp_f32_e32 v83, v83
	s_nop 0
	v_add_f32_e32 v83, 1.0, v83
	v_rcp_f32_e32 v83, v83
	s_nop 0
	v_xor_b32_e32 v128, 0x80000000, v83
	v_mul_f32_e32 v99, v99, v128
	v_add_f32_e32 v83, -1.0, v83
	v_fma_f32 v83, v79, v83, 1.0
	v_mul_f32_e32 v115, v115, v83
	v_add_f32_e32 v84, v84, v72
	v_mul_f32_e32 v84, 0xbfb8aa3b, v84
	v_exp_f32_e32 v84, v84
	s_nop 0
	v_add_f32_e32 v84, 1.0, v84
	v_rcp_f32_e32 v84, v84
	s_nop 0
	v_xor_b32_e32 v128, 0x80000000, v84
	v_mul_f32_e32 v100, v100, v128
	v_add_f32_e32 v84, -1.0, v84
	v_fma_f32 v84, v76, v84, 1.0
	v_mul_f32_e32 v116, v116, v84
	v_add_f32_e32 v85, v85, v73
	v_mul_f32_e32 v85, 0xbfb8aa3b, v85
	v_exp_f32_e32 v85, v85
	s_nop 0
	v_add_f32_e32 v85, 1.0, v85
	v_rcp_f32_e32 v85, v85
	s_nop 0
	v_xor_b32_e32 v128, 0x80000000, v85
	v_mul_f32_e32 v101, v101, v128
	v_add_f32_e32 v85, -1.0, v85
	v_fma_f32 v85, v77, v85, 1.0
	v_mul_f32_e32 v117, v117, v85
	v_add_f32_e32 v86, v86, v74
	v_mul_f32_e32 v86, 0xbfb8aa3b, v86
	v_exp_f32_e32 v86, v86
	s_nop 0
	v_add_f32_e32 v86, 1.0, v86
	v_rcp_f32_e32 v86, v86
	s_nop 0
	v_xor_b32_e32 v128, 0x80000000, v86
	v_mul_f32_e32 v102, v102, v128
	v_add_f32_e32 v86, -1.0, v86
	v_fma_f32 v86, v78, v86, 1.0
	v_mul_f32_e32 v118, v118, v86
	v_add_f32_e32 v87, v87, v75
	v_mul_f32_e32 v87, 0xbfb8aa3b, v87
	v_exp_f32_e32 v87, v87
	s_nop 0
	v_add_f32_e32 v87, 1.0, v87
	v_rcp_f32_e32 v87, v87
	s_nop 0
	v_xor_b32_e32 v128, 0x80000000, v87
	v_mul_f32_e32 v103, v103, v128
	v_add_f32_e32 v87, -1.0, v87
	v_fma_f32 v87, v79, v87, 1.0
	v_mul_f32_e32 v119, v119, v87
	v_add_f32_e32 v88, v88, v72
	v_mul_f32_e32 v88, 0xbfb8aa3b, v88
	v_exp_f32_e32 v88, v88
	s_nop 0
	v_add_f32_e32 v88, 1.0, v88
	v_rcp_f32_e32 v88, v88
	s_nop 0
	v_xor_b32_e32 v128, 0x80000000, v88
	v_mul_f32_e32 v104, v104, v128
	v_add_f32_e32 v88, -1.0, v88
	v_fma_f32 v88, v76, v88, 1.0
	v_mul_f32_e32 v120, v120, v88
	v_add_f32_e32 v89, v89, v73
	v_mul_f32_e32 v89, 0xbfb8aa3b, v89
	v_exp_f32_e32 v89, v89
	s_nop 0
	v_add_f32_e32 v89, 1.0, v89
	v_rcp_f32_e32 v89, v89
	s_nop 0
	v_xor_b32_e32 v128, 0x80000000, v89
	v_mul_f32_e32 v105, v105, v128
	v_add_f32_e32 v89, -1.0, v89
	v_fma_f32 v89, v77, v89, 1.0
	v_mul_f32_e32 v121, v121, v89
	v_add_f32_e32 v90, v90, v74
	v_mul_f32_e32 v90, 0xbfb8aa3b, v90
	v_exp_f32_e32 v90, v90
	s_nop 0
	v_add_f32_e32 v90, 1.0, v90
	v_rcp_f32_e32 v90, v90
	s_nop 0
	v_xor_b32_e32 v128, 0x80000000, v90
	v_mul_f32_e32 v106, v106, v128
	v_add_f32_e32 v90, -1.0, v90
	v_fma_f32 v90, v78, v90, 1.0
	v_mul_f32_e32 v122, v122, v90
	v_add_f32_e32 v91, v91, v75
	v_mul_f32_e32 v91, 0xbfb8aa3b, v91
	v_exp_f32_e32 v91, v91
	s_nop 0
	v_add_f32_e32 v91, 1.0, v91
	v_rcp_f32_e32 v91, v91
	s_nop 0
	v_xor_b32_e32 v128, 0x80000000, v91
	v_mul_f32_e32 v107, v107, v128
	v_add_f32_e32 v91, -1.0, v91
	v_fma_f32 v91, v79, v91, 1.0
	v_mul_f32_e32 v123, v123, v91
	v_add_f32_e32 v92, v92, v72
	v_mul_f32_e32 v92, 0xbfb8aa3b, v92
	v_exp_f32_e32 v92, v92
	s_nop 0
	v_add_f32_e32 v92, 1.0, v92
	v_rcp_f32_e32 v92, v92
	s_nop 0
	v_xor_b32_e32 v128, 0x80000000, v92
	v_mul_f32_e32 v108, v108, v128
	v_add_f32_e32 v92, -1.0, v92
	v_fma_f32 v92, v76, v92, 1.0
	v_mul_f32_e32 v124, v124, v92
	v_add_f32_e32 v93, v93, v73
	v_mul_f32_e32 v93, 0xbfb8aa3b, v93
	v_exp_f32_e32 v93, v93
	s_nop 0
	v_add_f32_e32 v93, 1.0, v93
	v_rcp_f32_e32 v93, v93
	s_nop 0
	v_xor_b32_e32 v128, 0x80000000, v93
	v_mul_f32_e32 v109, v109, v128
	v_add_f32_e32 v93, -1.0, v93
	v_fma_f32 v93, v77, v93, 1.0
	v_mul_f32_e32 v125, v125, v93
	v_add_f32_e32 v94, v94, v74
	v_mul_f32_e32 v94, 0xbfb8aa3b, v94
	v_exp_f32_e32 v94, v94
	s_nop 0
	v_add_f32_e32 v94, 1.0, v94
	v_rcp_f32_e32 v94, v94
	s_nop 0
	v_xor_b32_e32 v128, 0x80000000, v94
	v_mul_f32_e32 v110, v110, v128
	v_add_f32_e32 v94, -1.0, v94
	v_fma_f32 v94, v78, v94, 1.0
	v_mul_f32_e32 v126, v126, v94
	v_add_f32_e32 v95, v95, v75
	v_mul_f32_e32 v95, 0xbfb8aa3b, v95
	v_exp_f32_e32 v95, v95
	s_nop 0
	v_add_f32_e32 v95, 1.0, v95
	v_rcp_f32_e32 v95, v95
	s_nop 0
	v_xor_b32_e32 v128, 0x80000000, v95
	v_mul_f32_e32 v111, v111, v128
	v_add_f32_e32 v95, -1.0, v95
	v_fma_f32 v95, v79, v95, 1.0
	v_mul_f32_e32 v127, v127, v95
	v_add_u32_e32 v0, 32, v71
	v_mul_u32_u24_e32 v128, 0xc00, v0
	v_add_u32_e32 v128, v128, v69
	global_store_dwordx4 v128, v[96:99], s[2:3] offset:384
	global_store_dwordx4 v128, v[112:115], s[2:3] offset:640
	v_add_u32_e32 v0, 40, v71
	v_mul_u32_u24_e32 v128, 0xc00, v0
	v_add_u32_e32 v128, v128, v69
	global_store_dwordx4 v128, v[100:103], s[2:3] offset:384
	global_store_dwordx4 v128, v[116:119], s[2:3] offset:640
	v_add_u32_e32 v0, 48, v71
	v_mul_u32_u24_e32 v128, 0xc00, v0
	v_add_u32_e32 v128, v128, v69
	global_store_dwordx4 v128, v[104:107], s[2:3] offset:384
	global_store_dwordx4 v128, v[120:123], s[2:3] offset:640
	v_add_u32_e32 v0, 56, v71
	v_mul_u32_u24_e32 v128, 0xc00, v0
	v_add_u32_e32 v128, v128, v69
	global_store_dwordx4 v128, v[108:111], s[2:3] offset:384
	global_store_dwordx4 v128, v[124:127], s[2:3] offset:640
	s_cmpk_gt_i32 s8, 0xbf
	s_cbranch_scc0 .LBB0_303
